# fast pipelined latent-row norm block in P1 and P6 (rows prefetched 3 ahead)
# speedup vs baseline: 1.0113x; 1.0113x over previous
; __device__ __forceinline__ void p_norm(const float* hlat, const float* hctx, const float* g, const float* modl, int sh_off, int sc_off, bf16_t* A, int M,
;                                        const float* part, const float* cgate, float* hcout) {
;     const int tid = otid(), lane = tid & 63, wave = tid >> 6;
;     const int stride = gridDim.x * 8;
;     int row = obid() * 8 + wave;
;     float4 v[4], nv[4];
;     ...
;     if (row < M) PN_LOAD(v, row);
;     while (row < M) {
;         const int nrow = row + stride;
;         if (nrow < M) PN_LOAD(nv, nrow);
;         const int r = row < NLAT ? (row >> 11) : 16;
;         float ss = 0.f;
; #pragma unroll
;         for (int i = 0; i < 4; ++i) {
;             if (part != nullptr && row >= NLAT) {
;                 const size_t po = (size_t)(row - NLAT) * 1024 + i * 256 + lane * 4;
;                 const float4 p0 = *(const float4*)(part + po), p1 = *(const float4*)(part + (size_t)4096 * 1024 + po), cg = *(const float4*)(cgate + i * 256 + lane * 4);
;                 v[i].x += cg.x * (p0.x + p1.x); v[i].y += cg.y * (p0.y + p1.y); v[i].z += cg.z * (p0.z + p1.z); v[i].w += cg.w * (p0.w + p1.w);
;                 *(float4*)(hcout + po) = v[i];
;             }
;             ss += v[i].x * v[i].x + v[i].y * v[i].y + v[i].z * v[i].z + v[i].w * v[i].w; }
;         ss = wave_sum(ss);
;         const float rstd = rsqrtf(ss * (1.0f / 1024.0f) + EPS);
;         const float* mr = modl + (size_t)r * 6144;
; #pragma unroll
;         for (int i = 0; i < 4; ++i) {
;             const int k = i * 256 + lane * 4;
;             const float4 gg = *(const float4*)(g + k), scv = *(const float4*)(mr + sc_off + k), shv = *(const float4*)(mr + sh_off + k);
;             const float o0 = v[i].x * rstd * gg.x * (1.0f + scv.x) + shv.x, o1 = v[i].y * rstd * gg.y * (1.0f + scv.y) + shv.y;
;             const float o2 = v[i].z * rstd * gg.z * (1.0f + scv.z) + shv.z, o3 = v[i].w * rstd * gg.w * (1.0f + scv.w) + shv.w;
;             uint2 w; w.x = pk2(o0, o1); w.y = pk2(o2, o3);
;             *(uint2*)(A + (size_t)row * 1024 + k) = w;
; __global__ void __launch_bounds__(512, 2) hybrid_fwd(Params P) {
;     ...
;         p_norm(hl_in, hc_in, PIN(6) + l * 1024, modl, 0, 1024, AO, MTOK, l > 0 ? (const float*)(PWS + WS_MK) : nullptr, mod + (size_t)((l > 0 ? l - 1 : 0) * 17 + 16) * 6144 + 5 * 1024, hc);
.LBB0_406:
	s_load_dwordx2 s[6:7], s[16:17], 0x0
	s_mul_hi_u32 s5, s8, 0x66000
	s_mov_b32 s9, s55
	v_mov_b32_e32 v14, v253
	s_waitcnt lgkmcnt(0)
	v_writelane_b32 v255, s6, 41
	v_ashrrev_i32_e32 v1, 6, v14
	s_nop 0
	v_writelane_b32 v255, s7, 42
	s_mul_i32 s6, s8, 0x66000
	s_add_u32 s6, s56, s6
	s_addc_u32 s7, s57, s5
	v_writelane_b32 v255, s6, 43
	s_mov_b32 s5, s63
	s_lshl_b32 s5, s5, 3
	v_writelane_b32 v255, s7, 44
	v_writelane_b32 v255, s8, 45
	s_lshl_b32 s6, s8, 10
	s_mov_b32 s7, s55
	v_writelane_b32 v255, s9, 46
	v_writelane_b32 v255, s6, 47
	v_add_u32_e32 v50, s5, v1
	s_waitcnt vmcnt(0) lgkmcnt(0)
	v_readlane_b32 s100, v255, 45
	s_load_dwordx2 s[48:49], s[0:1], 0x30
	s_cmp_eq_u32 s100, 0
	s_cselect_b32 s101, 0, 0xe8
	s_load_dwordx2 s[46:47], s[0:1], s101
	s_mul_i32 s101, s100, 0x66000
	s_add_u32 s50, s56, s101
	s_addc_u32 s51, s57, 0
	s_add_u32 s98, s50, 0x1000
	s_addc_u32 s99, s51, 0
	s_lshl_b32 s100, s100, 12
	v_and_b32_e32 v240, 63, v253
	v_lshlrev_b32_e32 v241, 4, v240
	v_lshlrev_b32_e32 v144, 12, v50
	v_add_u32_e32 v144, v144, v241
	v_lshlrev_b32_e32 v146, 11, v50
	v_lshl_add_u32 v146, v240, 3, v146
	v_mov_b32_e32 v148, v241
	s_waitcnt lgkmcnt(0)
	s_add_u32 s48, s48, s100
	s_addc_u32 s49, s49, 0
	global_load_dwordx4 v[80:83], v144, s[46:47]
	global_load_dwordx4 v[84:87], v144, s[46:47] offset:1024
	global_load_dwordx4 v[88:91], v144, s[46:47] offset:2048
	global_load_dwordx4 v[92:95], v144, s[46:47] offset:3072
	v_add_u32_e32 v144, 0x800000, v144
	global_load_dwordx4 v[156:159], v241, s[48:49]
	global_load_dwordx4 v[160:163], v241, s[48:49] offset:1024
	global_load_dwordx4 v[164:167], v241, s[48:49] offset:2048
	global_load_dwordx4 v[168:171], v241, s[48:49] offset:3072
	global_load_dwordx4 v[172:175], v148, s[98:99]
	global_load_dwordx4 v[176:179], v148, s[98:99] offset:1024
	global_load_dwordx4 v[180:183], v148, s[98:99] offset:2048
	global_load_dwordx4 v[184:187], v148, s[98:99] offset:3072
	global_load_dwordx4 v[188:191], v148, s[50:51]
	global_load_dwordx4 v[192:195], v148, s[50:51] offset:1024
	global_load_dwordx4 v[196:199], v148, s[50:51] offset:2048
	global_load_dwordx4 v[200:203], v148, s[50:51] offset:3072
	v_add_u32_e32 v148, 0x6000, v148
	global_load_dwordx4 v[96:99], v144, s[46:47]
	global_load_dwordx4 v[100:103], v144, s[46:47] offset:1024
	global_load_dwordx4 v[104:107], v144, s[46:47] offset:2048
	global_load_dwordx4 v[108:111], v144, s[46:47] offset:3072
	v_add_u32_e32 v144, 0x800000, v144
	global_load_dwordx4 v[112:115], v144, s[46:47]
	global_load_dwordx4 v[116:119], v144, s[46:47] offset:1024
	global_load_dwordx4 v[120:123], v144, s[46:47] offset:2048
	global_load_dwordx4 v[124:127], v144, s[46:47] offset:3072
	v_add_u32_e32 v144, 0x800000, v144
	global_load_dwordx4 v[34:37], v148, s[98:99]
	global_load_dwordx4 v[38:41], v148, s[98:99] offset:1024
	global_load_dwordx4 v[42:45], v148, s[98:99] offset:2048
	global_load_dwordx4 v[46:49], v148, s[98:99] offset:3072
	global_load_dwordx4 v[224:227], v148, s[50:51]
	global_load_dwordx4 v[228:231], v148, s[50:51] offset:1024
	global_load_dwordx4 v[232:235], v148, s[50:51] offset:2048
	global_load_dwordx4 v[236:239], v148, s[50:51] offset:3072
	v_add_u32_e32 v148, 0x6000, v148
	global_load_dwordx4 v[128:131], v144, s[46:47]
	global_load_dwordx4 v[132:135], v144, s[46:47] offset:1024
	global_load_dwordx4 v[136:139], v144, s[46:47] offset:2048
	global_load_dwordx4 v[140:143], v144, s[46:47] offset:3072
	v_add_u32_e32 v144, 0x800000, v144
	s_waitcnt vmcnt(32)
	v_pk_mul_f32 v[242:243], v[80:81], v[80:81]
	v_pk_mul_f32 v[244:245], v[84:85], v[84:85]
	v_pk_mul_f32 v[246:247], v[82:83], v[82:83]
	v_pk_mul_f32 v[248:249], v[86:87], v[86:87]
	v_add_f32_e32 v204, v245, v244
	v_add_f32_e32 v205, v243, v242
	v_add_f32_e32 v204, v248, v204
	v_add_f32_e32 v205, v246, v205
	v_add_f32_e32 v204, v249, v204
	v_add_f32_e32 v205, v247, v205
	v_pk_mul_f32 v[242:243], v[88:89], v[88:89]
	v_pk_mul_f32 v[244:245], v[92:93], v[92:93]
	v_pk_mul_f32 v[246:247], v[90:91], v[90:91]
	v_pk_mul_f32 v[248:249], v[94:95], v[94:95]
	v_add_f32_e32 v206, v243, v242
	v_add_f32_e32 v207, v245, v244
	v_add_f32_e32 v206, v246, v206
	v_add_f32_e32 v207, v248, v207
	v_add_f32_e32 v206, v247, v206
	v_add_f32_e32 v207, v249, v207
	v_add_f32_e32 v204, v205, v204
	v_add_f32_e32 v204, v204, v206
	v_add_f32_e32 v204, v204, v207
	ds_swizzle_b32 v205, v204 offset:swizzle(SWAP,1)
	s_waitcnt lgkmcnt(0)
	v_add_f32_e32 v204, v204, v205
	ds_swizzle_b32 v205, v204 offset:swizzle(SWAP,2)
	s_waitcnt lgkmcnt(0)
	v_add_f32_e32 v204, v204, v205
	ds_swizzle_b32 v205, v204 offset:swizzle(SWAP,4)
	s_waitcnt lgkmcnt(0)
	v_add_f32_e32 v204, v204, v205
	ds_swizzle_b32 v205, v204 offset:swizzle(SWAP,8)
	s_waitcnt lgkmcnt(0)
	v_add_f32_e32 v204, v204, v205
	ds_swizzle_b32 v205, v204 offset:swizzle(SWAP,16)
	s_waitcnt lgkmcnt(0)
	v_add_f32_e32 v204, v204, v205
	v_mov_b32_e32 v205, v204
	s_nop 1
	v_permlane32_swap_b32_e32 v204, v205
	v_add_f32_e32 v204, v204, v205
	v_mov_b32_e32 v205, 0x358637bd
	v_fmamk_f32 v204, v204, 0x3a800000, v205
	v_rsq_f32_e32 v204, v204
	s_nop 0
	s_waitcnt vmcnt(20)
; __device__ __forceinline__ unsigned pk2(float lo, float hi) { const g_f32x2 f = {lo, hi}; return __builtin_bit_cast(unsigned, __builtin_convertvector(f, g_bf16x2)); }
; __device__ __forceinline__ void p_norm(const float* hlat, const float* hctx, const float* g, const float* modl, int sh_off, int sc_off, bf16_t* A, int M,
;                                        const float* part, const float* cgate, float* hcout) {
;     ...
;         float ss = 0.f;
; #pragma unroll
;         for (int i = 0; i < 4; ++i) {
;             if (part != nullptr && row >= NLAT) {
;                 const size_t po = (size_t)(row - NLAT) * 1024 + i * 256 + lane * 4;
;                 const float4 p0 = *(const float4*)(part + po), p1 = *(const float4*)(part + (size_t)4096 * 1024 + po), cg = *(const float4*)(cgate + i * 256 + lane * 4);
;                 v[i].x += cg.x * (p0.x + p1.x); v[i].y += cg.y * (p0.y + p1.y); v[i].z += cg.z * (p0.z + p1.z); v[i].w += cg.w * (p0.w + p1.w);
;                 *(float4*)(hcout + po) = v[i];
;             }
;             ss += v[i].x * v[i].x + v[i].y * v[i].y + v[i].z * v[i].z + v[i].w * v[i].w; }
;         ss = wave_sum(ss);
;         const float rstd = rsqrtf(ss * (1.0f / 1024.0f) + EPS);
;         const float* mr = modl + (size_t)r * 6144;
; #pragma unroll
;         for (int i = 0; i < 4; ++i) {
;             const int k = i * 256 + lane * 4;
;             const float4 gg = *(const float4*)(g + k), scv = *(const float4*)(mr + sc_off + k), shv = *(const float4*)(mr + sh_off + k);
;             const float o0 = v[i].x * rstd * gg.x * (1.0f + scv.x) + shv.x, o1 = v[i].y * rstd * gg.y * (1.0f + scv.y) + shv.y;
;             const float o2 = v[i].z * rstd * gg.z * (1.0f + scv.z) + shv.z, o3 = v[i].w * rstd * gg.w * (1.0f + scv.w) + shv.w;
;             uint2 w; w.x = pk2(o0, o1); w.y = pk2(o2, o3);
;             *(uint2*)(A + (size_t)row * 1024 + k) = w;
	v_pk_mul_f32 v[80:81], v[80:81], v[204:205] op_sel_hi:[1,0]
	v_pk_mul_f32 v[82:83], v[82:83], v[204:205] op_sel_hi:[1,0]
	v_pk_mul_f32 v[80:81], v[156:157], v[80:81]
	v_pk_mul_f32 v[82:83], v[158:159], v[82:83]
	v_pk_add_f32 v[242:243], v[172:173], 1.0 op_sel_hi:[1,0]
	v_pk_add_f32 v[244:245], v[174:175], 1.0 op_sel_hi:[1,0]
	v_pk_fma_f32 v[80:81], v[242:243], v[80:81], v[188:189]
	v_pk_fma_f32 v[82:83], v[244:245], v[82:83], v[190:191]
	v_cvt_pk_bf16_f32 v80, v80, v81
	v_cvt_pk_bf16_f32 v81, v82, v83
	global_store_dwordx2 v146, v[80:81], s[66:67]
	v_pk_mul_f32 v[84:85], v[84:85], v[204:205] op_sel_hi:[1,0]
	v_pk_mul_f32 v[86:87], v[86:87], v[204:205] op_sel_hi:[1,0]
	v_pk_mul_f32 v[84:85], v[160:161], v[84:85]
	v_pk_mul_f32 v[86:87], v[162:163], v[86:87]
	v_pk_add_f32 v[242:243], v[176:177], 1.0 op_sel_hi:[1,0]
	v_pk_add_f32 v[244:245], v[178:179], 1.0 op_sel_hi:[1,0]
	v_pk_fma_f32 v[84:85], v[242:243], v[84:85], v[192:193]
	v_pk_fma_f32 v[86:87], v[244:245], v[86:87], v[194:195]
	v_cvt_pk_bf16_f32 v84, v84, v85
	v_cvt_pk_bf16_f32 v85, v86, v87
	global_store_dwordx2 v146, v[84:85], s[66:67] offset:512
	v_pk_mul_f32 v[88:89], v[88:89], v[204:205] op_sel_hi:[1,0]
	v_pk_mul_f32 v[90:91], v[90:91], v[204:205] op_sel_hi:[1,0]
	v_pk_mul_f32 v[88:89], v[164:165], v[88:89]
	v_pk_mul_f32 v[90:91], v[166:167], v[90:91]
	v_pk_add_f32 v[242:243], v[180:181], 1.0 op_sel_hi:[1,0]
	v_pk_add_f32 v[244:245], v[182:183], 1.0 op_sel_hi:[1,0]
	v_pk_fma_f32 v[88:89], v[242:243], v[88:89], v[196:197]
	v_pk_fma_f32 v[90:91], v[244:245], v[90:91], v[198:199]
	v_cvt_pk_bf16_f32 v88, v88, v89
	v_cvt_pk_bf16_f32 v89, v90, v91
	global_store_dwordx2 v146, v[88:89], s[66:67] offset:1024
	v_pk_mul_f32 v[92:93], v[92:93], v[204:205] op_sel_hi:[1,0]
	v_pk_mul_f32 v[94:95], v[94:95], v[204:205] op_sel_hi:[1,0]
	v_pk_mul_f32 v[92:93], v[168:169], v[92:93]
	v_pk_mul_f32 v[94:95], v[170:171], v[94:95]
	v_pk_add_f32 v[242:243], v[184:185], 1.0 op_sel_hi:[1,0]
	v_pk_add_f32 v[244:245], v[186:187], 1.0 op_sel_hi:[1,0]
	v_pk_fma_f32 v[92:93], v[242:243], v[92:93], v[200:201]
	v_pk_fma_f32 v[94:95], v[244:245], v[94:95], v[202:203]
	v_cvt_pk_bf16_f32 v92, v92, v93
	v_cvt_pk_bf16_f32 v93, v94, v95
	global_store_dwordx2 v146, v[92:93], s[66:67] offset:1536
	v_add_u32_e32 v146, 0x400000, v146
	global_load_dwordx4 v[172:175], v148, s[98:99]
	global_load_dwordx4 v[176:179], v148, s[98:99] offset:1024
	global_load_dwordx4 v[180:183], v148, s[98:99] offset:2048
	global_load_dwordx4 v[184:187], v148, s[98:99] offset:3072
	global_load_dwordx4 v[188:191], v148, s[50:51]
	global_load_dwordx4 v[192:195], v148, s[50:51] offset:1024
	global_load_dwordx4 v[196:199], v148, s[50:51] offset:2048
	global_load_dwordx4 v[200:203], v148, s[50:51] offset:3072
	v_add_u32_e32 v148, 0x6000, v148
	global_load_dwordx4 v[80:83], v144, s[46:47]
	global_load_dwordx4 v[84:87], v144, s[46:47] offset:1024
	global_load_dwordx4 v[88:91], v144, s[46:47] offset:2048
	global_load_dwordx4 v[92:95], v144, s[46:47] offset:3072
	v_add_u32_e32 v144, 0x800000, v144
	s_waitcnt vmcnt(32)
	v_pk_mul_f32 v[242:243], v[96:97], v[96:97]
	v_pk_mul_f32 v[244:245], v[100:101], v[100:101]
	v_pk_mul_f32 v[246:247], v[98:99], v[98:99]
	v_pk_mul_f32 v[248:249], v[102:103], v[102:103]
	v_add_f32_e32 v204, v245, v244
	v_add_f32_e32 v205, v243, v242
	v_add_f32_e32 v204, v248, v204
	v_add_f32_e32 v205, v246, v205
	v_add_f32_e32 v204, v249, v204
	v_add_f32_e32 v205, v247, v205
	v_pk_mul_f32 v[242:243], v[104:105], v[104:105]
	v_pk_mul_f32 v[244:245], v[108:109], v[108:109]
	v_pk_mul_f32 v[246:247], v[106:107], v[106:107]
	v_pk_mul_f32 v[248:249], v[110:111], v[110:111]
	v_add_f32_e32 v206, v243, v242
	v_add_f32_e32 v207, v245, v244
	v_add_f32_e32 v206, v246, v206
	v_add_f32_e32 v207, v248, v207
	v_add_f32_e32 v206, v247, v206
	v_add_f32_e32 v207, v249, v207
	v_add_f32_e32 v204, v205, v204
	v_add_f32_e32 v204, v204, v206
	v_add_f32_e32 v204, v204, v207
	ds_swizzle_b32 v205, v204 offset:swizzle(SWAP,1)
	s_waitcnt lgkmcnt(0)
	v_add_f32_e32 v204, v204, v205
	ds_swizzle_b32 v205, v204 offset:swizzle(SWAP,2)
	s_waitcnt lgkmcnt(0)
	v_add_f32_e32 v204, v204, v205
	ds_swizzle_b32 v205, v204 offset:swizzle(SWAP,4)
	s_waitcnt lgkmcnt(0)
	v_add_f32_e32 v204, v204, v205
	ds_swizzle_b32 v205, v204 offset:swizzle(SWAP,8)
	s_waitcnt lgkmcnt(0)
	v_add_f32_e32 v204, v204, v205
	ds_swizzle_b32 v205, v204 offset:swizzle(SWAP,16)
	s_waitcnt lgkmcnt(0)
	v_add_f32_e32 v204, v204, v205
	v_mov_b32_e32 v205, v204
	s_nop 1
	v_permlane32_swap_b32_e32 v204, v205
	v_add_f32_e32 v204, v204, v205
	v_mov_b32_e32 v205, 0x358637bd
	v_fmamk_f32 v204, v204, 0x3a800000, v205
	v_rsq_f32_e32 v204, v204
	s_nop 0
	s_waitcnt vmcnt(20)
; __device__ __forceinline__ unsigned pk2(float lo, float hi) { const g_f32x2 f = {lo, hi}; return __builtin_bit_cast(unsigned, __builtin_convertvector(f, g_bf16x2)); }
; __device__ __forceinline__ void p_norm(const float* hlat, const float* hctx, const float* g, const float* modl, int sh_off, int sc_off, bf16_t* A, int M,
;                                        const float* part, const float* cgate, float* hcout) {
;     ...
;         float ss = 0.f;
; #pragma unroll
;         for (int i = 0; i < 4; ++i) {
;             if (part != nullptr && row >= NLAT) {
;                 const size_t po = (size_t)(row - NLAT) * 1024 + i * 256 + lane * 4;
;                 const float4 p0 = *(const float4*)(part + po), p1 = *(const float4*)(part + (size_t)4096 * 1024 + po), cg = *(const float4*)(cgate + i * 256 + lane * 4);
;                 v[i].x += cg.x * (p0.x + p1.x); v[i].y += cg.y * (p0.y + p1.y); v[i].z += cg.z * (p0.z + p1.z); v[i].w += cg.w * (p0.w + p1.w);
;                 *(float4*)(hcout + po) = v[i];
;             }
;             ss += v[i].x * v[i].x + v[i].y * v[i].y + v[i].z * v[i].z + v[i].w * v[i].w; }
;         ss = wave_sum(ss);
;         const float rstd = rsqrtf(ss * (1.0f / 1024.0f) + EPS);
;         const float* mr = modl + (size_t)r * 6144;
; #pragma unroll
;         for (int i = 0; i < 4; ++i) {
;             const int k = i * 256 + lane * 4;
;             const float4 gg = *(const float4*)(g + k), scv = *(const float4*)(mr + sc_off + k), shv = *(const float4*)(mr + sh_off + k);
;             const float o0 = v[i].x * rstd * gg.x * (1.0f + scv.x) + shv.x, o1 = v[i].y * rstd * gg.y * (1.0f + scv.y) + shv.y;
;             const float o2 = v[i].z * rstd * gg.z * (1.0f + scv.z) + shv.z, o3 = v[i].w * rstd * gg.w * (1.0f + scv.w) + shv.w;
;             uint2 w; w.x = pk2(o0, o1); w.y = pk2(o2, o3);
;             *(uint2*)(A + (size_t)row * 1024 + k) = w;
	v_pk_mul_f32 v[96:97], v[96:97], v[204:205] op_sel_hi:[1,0]
	v_pk_mul_f32 v[98:99], v[98:99], v[204:205] op_sel_hi:[1,0]
	v_pk_mul_f32 v[96:97], v[156:157], v[96:97]
	v_pk_mul_f32 v[98:99], v[158:159], v[98:99]
	v_pk_add_f32 v[242:243], v[34:35], 1.0 op_sel_hi:[1,0]
	v_pk_add_f32 v[244:245], v[36:37], 1.0 op_sel_hi:[1,0]
	v_pk_fma_f32 v[96:97], v[242:243], v[96:97], v[224:225]
	v_pk_fma_f32 v[98:99], v[244:245], v[98:99], v[226:227]
	v_cvt_pk_bf16_f32 v96, v96, v97
	v_cvt_pk_bf16_f32 v97, v98, v99
	global_store_dwordx2 v146, v[96:97], s[66:67]
	v_pk_mul_f32 v[100:101], v[100:101], v[204:205] op_sel_hi:[1,0]
	v_pk_mul_f32 v[102:103], v[102:103], v[204:205] op_sel_hi:[1,0]
	v_pk_mul_f32 v[100:101], v[160:161], v[100:101]
	v_pk_mul_f32 v[102:103], v[162:163], v[102:103]
	v_pk_add_f32 v[242:243], v[38:39], 1.0 op_sel_hi:[1,0]
	v_pk_add_f32 v[244:245], v[40:41], 1.0 op_sel_hi:[1,0]
	v_pk_fma_f32 v[100:101], v[242:243], v[100:101], v[228:229]
	v_pk_fma_f32 v[102:103], v[244:245], v[102:103], v[230:231]
	v_cvt_pk_bf16_f32 v100, v100, v101
	v_cvt_pk_bf16_f32 v101, v102, v103
	global_store_dwordx2 v146, v[100:101], s[66:67] offset:512
	v_pk_mul_f32 v[104:105], v[104:105], v[204:205] op_sel_hi:[1,0]
	v_pk_mul_f32 v[106:107], v[106:107], v[204:205] op_sel_hi:[1,0]
	v_pk_mul_f32 v[104:105], v[164:165], v[104:105]
	v_pk_mul_f32 v[106:107], v[166:167], v[106:107]
	v_pk_add_f32 v[242:243], v[42:43], 1.0 op_sel_hi:[1,0]
	v_pk_add_f32 v[244:245], v[44:45], 1.0 op_sel_hi:[1,0]
	v_pk_fma_f32 v[104:105], v[242:243], v[104:105], v[232:233]
	v_pk_fma_f32 v[106:107], v[244:245], v[106:107], v[234:235]
	v_cvt_pk_bf16_f32 v104, v104, v105
	v_cvt_pk_bf16_f32 v105, v106, v107
	global_store_dwordx2 v146, v[104:105], s[66:67] offset:1024
	v_pk_mul_f32 v[108:109], v[108:109], v[204:205] op_sel_hi:[1,0]
	v_pk_mul_f32 v[110:111], v[110:111], v[204:205] op_sel_hi:[1,0]
	v_pk_mul_f32 v[108:109], v[168:169], v[108:109]
	v_pk_mul_f32 v[110:111], v[170:171], v[110:111]
	v_pk_add_f32 v[242:243], v[46:47], 1.0 op_sel_hi:[1,0]
	v_pk_add_f32 v[244:245], v[48:49], 1.0 op_sel_hi:[1,0]
	v_pk_fma_f32 v[108:109], v[242:243], v[108:109], v[236:237]
	v_pk_fma_f32 v[110:111], v[244:245], v[110:111], v[238:239]
	v_cvt_pk_bf16_f32 v108, v108, v109
	v_cvt_pk_bf16_f32 v109, v110, v111
	global_store_dwordx2 v146, v[108:109], s[66:67] offset:1536
	v_add_u32_e32 v146, 0x400000, v146
	global_load_dwordx4 v[34:37], v148, s[98:99]
	global_load_dwordx4 v[38:41], v148, s[98:99] offset:1024
	global_load_dwordx4 v[42:45], v148, s[98:99] offset:2048
	global_load_dwordx4 v[46:49], v148, s[98:99] offset:3072
	global_load_dwordx4 v[224:227], v148, s[50:51]
	global_load_dwordx4 v[228:231], v148, s[50:51] offset:1024
	global_load_dwordx4 v[232:235], v148, s[50:51] offset:2048
	global_load_dwordx4 v[236:239], v148, s[50:51] offset:3072
	v_add_u32_e32 v148, 0x6000, v148
	global_load_dwordx4 v[96:99], v144, s[46:47]
	global_load_dwordx4 v[100:103], v144, s[46:47] offset:1024
	global_load_dwordx4 v[104:107], v144, s[46:47] offset:2048
	global_load_dwordx4 v[108:111], v144, s[46:47] offset:3072
	v_add_u32_e32 v144, 0x800000, v144
	v_pk_mul_f32 v[242:243], v[112:113], v[112:113]
	v_pk_mul_f32 v[244:245], v[116:117], v[116:117]
	v_pk_mul_f32 v[246:247], v[114:115], v[114:115]
	v_pk_mul_f32 v[248:249], v[118:119], v[118:119]
	v_add_f32_e32 v204, v245, v244
	v_add_f32_e32 v205, v243, v242
	v_add_f32_e32 v204, v248, v204
	v_add_f32_e32 v205, v246, v205
	v_add_f32_e32 v204, v249, v204
	v_add_f32_e32 v205, v247, v205
	v_pk_mul_f32 v[242:243], v[120:121], v[120:121]
	v_pk_mul_f32 v[244:245], v[124:125], v[124:125]
	v_pk_mul_f32 v[246:247], v[122:123], v[122:123]
	v_pk_mul_f32 v[248:249], v[126:127], v[126:127]
	v_add_f32_e32 v206, v243, v242
	v_add_f32_e32 v207, v245, v244
	v_add_f32_e32 v206, v246, v206
	v_add_f32_e32 v207, v248, v207
	v_add_f32_e32 v206, v247, v206
	v_add_f32_e32 v207, v249, v207
	v_add_f32_e32 v204, v205, v204
	v_add_f32_e32 v204, v204, v206
	v_add_f32_e32 v204, v204, v207
	ds_swizzle_b32 v205, v204 offset:swizzle(SWAP,1)
	s_waitcnt lgkmcnt(0)
	v_add_f32_e32 v204, v204, v205
	ds_swizzle_b32 v205, v204 offset:swizzle(SWAP,2)
	s_waitcnt lgkmcnt(0)
	v_add_f32_e32 v204, v204, v205
	ds_swizzle_b32 v205, v204 offset:swizzle(SWAP,4)
	s_waitcnt lgkmcnt(0)
	v_add_f32_e32 v204, v204, v205
	ds_swizzle_b32 v205, v204 offset:swizzle(SWAP,8)
	s_waitcnt lgkmcnt(0)
	v_add_f32_e32 v204, v204, v205
	ds_swizzle_b32 v205, v204 offset:swizzle(SWAP,16)
	s_waitcnt lgkmcnt(0)
	v_add_f32_e32 v204, v204, v205
	v_mov_b32_e32 v205, v204
	s_nop 1
	v_permlane32_swap_b32_e32 v204, v205
	v_add_f32_e32 v204, v204, v205
	v_mov_b32_e32 v205, 0x358637bd
	v_fmamk_f32 v204, v204, 0x3a800000, v205
	v_rsq_f32_e32 v204, v204
	s_nop 0
	s_waitcnt vmcnt(20)
; __device__ __forceinline__ unsigned pk2(float lo, float hi) { const g_f32x2 f = {lo, hi}; return __builtin_bit_cast(unsigned, __builtin_convertvector(f, g_bf16x2)); }
; __device__ __forceinline__ void p_norm(const float* hlat, const float* hctx, const float* g, const float* modl, int sh_off, int sc_off, bf16_t* A, int M,
;                                        const float* part, const float* cgate, float* hcout) {
;     ...
;         float ss = 0.f;
; #pragma unroll
;         for (int i = 0; i < 4; ++i) {
;             if (part != nullptr && row >= NLAT) {
;                 const size_t po = (size_t)(row - NLAT) * 1024 + i * 256 + lane * 4;
;                 const float4 p0 = *(const float4*)(part + po), p1 = *(const float4*)(part + (size_t)4096 * 1024 + po), cg = *(const float4*)(cgate + i * 256 + lane * 4);
;                 v[i].x += cg.x * (p0.x + p1.x); v[i].y += cg.y * (p0.y + p1.y); v[i].z += cg.z * (p0.z + p1.z); v[i].w += cg.w * (p0.w + p1.w);
;                 *(float4*)(hcout + po) = v[i];
;             }
;             ss += v[i].x * v[i].x + v[i].y * v[i].y + v[i].z * v[i].z + v[i].w * v[i].w; }
;         ss = wave_sum(ss);
;         const float rstd = rsqrtf(ss * (1.0f / 1024.0f) + EPS);
;         const float* mr = modl + (size_t)r * 6144;
; #pragma unroll
;         for (int i = 0; i < 4; ++i) {
;             const int k = i * 256 + lane * 4;
;             const float4 gg = *(const float4*)(g + k), scv = *(const float4*)(mr + sc_off + k), shv = *(const float4*)(mr + sh_off + k);
;             const float o0 = v[i].x * rstd * gg.x * (1.0f + scv.x) + shv.x, o1 = v[i].y * rstd * gg.y * (1.0f + scv.y) + shv.y;
;             const float o2 = v[i].z * rstd * gg.z * (1.0f + scv.z) + shv.z, o3 = v[i].w * rstd * gg.w * (1.0f + scv.w) + shv.w;
;             uint2 w; w.x = pk2(o0, o1); w.y = pk2(o2, o3);
;             *(uint2*)(A + (size_t)row * 1024 + k) = w;
	v_pk_mul_f32 v[112:113], v[112:113], v[204:205] op_sel_hi:[1,0]
	v_pk_mul_f32 v[114:115], v[114:115], v[204:205] op_sel_hi:[1,0]
	v_pk_mul_f32 v[112:113], v[156:157], v[112:113]
	v_pk_mul_f32 v[114:115], v[158:159], v[114:115]
	v_pk_add_f32 v[242:243], v[172:173], 1.0 op_sel_hi:[1,0]
	v_pk_add_f32 v[244:245], v[174:175], 1.0 op_sel_hi:[1,0]
	v_pk_fma_f32 v[112:113], v[242:243], v[112:113], v[188:189]
	v_pk_fma_f32 v[114:115], v[244:245], v[114:115], v[190:191]
	v_cvt_pk_bf16_f32 v112, v112, v113
	v_cvt_pk_bf16_f32 v113, v114, v115
	global_store_dwordx2 v146, v[112:113], s[66:67]
	v_pk_mul_f32 v[116:117], v[116:117], v[204:205] op_sel_hi:[1,0]
	v_pk_mul_f32 v[118:119], v[118:119], v[204:205] op_sel_hi:[1,0]
	v_pk_mul_f32 v[116:117], v[160:161], v[116:117]
	v_pk_mul_f32 v[118:119], v[162:163], v[118:119]
	v_pk_add_f32 v[242:243], v[176:177], 1.0 op_sel_hi:[1,0]
	v_pk_add_f32 v[244:245], v[178:179], 1.0 op_sel_hi:[1,0]
	v_pk_fma_f32 v[116:117], v[242:243], v[116:117], v[192:193]
	v_pk_fma_f32 v[118:119], v[244:245], v[118:119], v[194:195]
	v_cvt_pk_bf16_f32 v116, v116, v117
	v_cvt_pk_bf16_f32 v117, v118, v119
	global_store_dwordx2 v146, v[116:117], s[66:67] offset:512
	v_pk_mul_f32 v[120:121], v[120:121], v[204:205] op_sel_hi:[1,0]
	v_pk_mul_f32 v[122:123], v[122:123], v[204:205] op_sel_hi:[1,0]
	v_pk_mul_f32 v[120:121], v[164:165], v[120:121]
	v_pk_mul_f32 v[122:123], v[166:167], v[122:123]
	v_pk_add_f32 v[242:243], v[180:181], 1.0 op_sel_hi:[1,0]
	v_pk_add_f32 v[244:245], v[182:183], 1.0 op_sel_hi:[1,0]
	v_pk_fma_f32 v[120:121], v[242:243], v[120:121], v[196:197]
	v_pk_fma_f32 v[122:123], v[244:245], v[122:123], v[198:199]
	v_cvt_pk_bf16_f32 v120, v120, v121
	v_cvt_pk_bf16_f32 v121, v122, v123
	global_store_dwordx2 v146, v[120:121], s[66:67] offset:1024
	v_pk_mul_f32 v[124:125], v[124:125], v[204:205] op_sel_hi:[1,0]
	v_pk_mul_f32 v[126:127], v[126:127], v[204:205] op_sel_hi:[1,0]
	v_pk_mul_f32 v[124:125], v[168:169], v[124:125]
	v_pk_mul_f32 v[126:127], v[170:171], v[126:127]
	v_pk_add_f32 v[242:243], v[184:185], 1.0 op_sel_hi:[1,0]
	v_pk_add_f32 v[244:245], v[186:187], 1.0 op_sel_hi:[1,0]
	v_pk_fma_f32 v[124:125], v[242:243], v[124:125], v[200:201]
	v_pk_fma_f32 v[126:127], v[244:245], v[126:127], v[202:203]
	v_cvt_pk_bf16_f32 v124, v124, v125
	v_cvt_pk_bf16_f32 v125, v126, v127
	global_store_dwordx2 v146, v[124:125], s[66:67] offset:1536
	v_add_u32_e32 v146, 0x400000, v146
	global_load_dwordx4 v[172:175], v148, s[98:99]
	global_load_dwordx4 v[176:179], v148, s[98:99] offset:1024
	global_load_dwordx4 v[180:183], v148, s[98:99] offset:2048
	global_load_dwordx4 v[184:187], v148, s[98:99] offset:3072
	global_load_dwordx4 v[188:191], v148, s[50:51]
	global_load_dwordx4 v[192:195], v148, s[50:51] offset:1024
	global_load_dwordx4 v[196:199], v148, s[50:51] offset:2048
	global_load_dwordx4 v[200:203], v148, s[50:51] offset:3072
	v_add_u32_e32 v148, 0x6000, v148
	global_load_dwordx4 v[112:115], v144, s[46:47]
	global_load_dwordx4 v[116:119], v144, s[46:47] offset:1024
	global_load_dwordx4 v[120:123], v144, s[46:47] offset:2048
	global_load_dwordx4 v[124:127], v144, s[46:47] offset:3072
	v_add_u32_e32 v144, 0x800000, v144
	v_pk_mul_f32 v[242:243], v[128:129], v[128:129]
	v_pk_mul_f32 v[244:245], v[132:133], v[132:133]
	v_pk_mul_f32 v[246:247], v[130:131], v[130:131]
	v_pk_mul_f32 v[248:249], v[134:135], v[134:135]
	v_add_f32_e32 v204, v245, v244
	v_add_f32_e32 v205, v243, v242
	v_add_f32_e32 v204, v248, v204
	v_add_f32_e32 v205, v246, v205
	v_add_f32_e32 v204, v249, v204
	v_add_f32_e32 v205, v247, v205
	v_pk_mul_f32 v[242:243], v[136:137], v[136:137]
	v_pk_mul_f32 v[244:245], v[140:141], v[140:141]
	v_pk_mul_f32 v[246:247], v[138:139], v[138:139]
	v_pk_mul_f32 v[248:249], v[142:143], v[142:143]
	v_add_f32_e32 v206, v243, v242
	v_add_f32_e32 v207, v245, v244
	v_add_f32_e32 v206, v246, v206
	v_add_f32_e32 v207, v248, v207
	v_add_f32_e32 v206, v247, v206
	v_add_f32_e32 v207, v249, v207
	v_add_f32_e32 v204, v205, v204
	v_add_f32_e32 v204, v204, v206
	v_add_f32_e32 v204, v204, v207
	ds_swizzle_b32 v205, v204 offset:swizzle(SWAP,1)
	s_waitcnt lgkmcnt(0)
	v_add_f32_e32 v204, v204, v205
	ds_swizzle_b32 v205, v204 offset:swizzle(SWAP,2)
	s_waitcnt lgkmcnt(0)
	v_add_f32_e32 v204, v204, v205
	ds_swizzle_b32 v205, v204 offset:swizzle(SWAP,4)
	s_waitcnt lgkmcnt(0)
	v_add_f32_e32 v204, v204, v205
	ds_swizzle_b32 v205, v204 offset:swizzle(SWAP,8)
	s_waitcnt lgkmcnt(0)
	v_add_f32_e32 v204, v204, v205
	ds_swizzle_b32 v205, v204 offset:swizzle(SWAP,16)
	s_waitcnt lgkmcnt(0)
	v_add_f32_e32 v204, v204, v205
	v_mov_b32_e32 v205, v204
	s_nop 1
	v_permlane32_swap_b32_e32 v204, v205
	v_add_f32_e32 v204, v204, v205
	v_mov_b32_e32 v205, 0x358637bd
	v_fmamk_f32 v204, v204, 0x3a800000, v205
	v_rsq_f32_e32 v204, v204
	s_nop 0
	s_waitcnt vmcnt(20)
; __device__ __forceinline__ unsigned pk2(float lo, float hi) { const g_f32x2 f = {lo, hi}; return __builtin_bit_cast(unsigned, __builtin_convertvector(f, g_bf16x2)); }
; __device__ __forceinline__ void p_norm(const float* hlat, const float* hctx, const float* g, const float* modl, int sh_off, int sc_off, bf16_t* A, int M,
;                                        const float* part, const float* cgate, float* hcout) {
;     ...
;         float ss = 0.f;
; #pragma unroll
;         for (int i = 0; i < 4; ++i) {
;             if (part != nullptr && row >= NLAT) {
;                 const size_t po = (size_t)(row - NLAT) * 1024 + i * 256 + lane * 4;
;                 const float4 p0 = *(const float4*)(part + po), p1 = *(const float4*)(part + (size_t)4096 * 1024 + po), cg = *(const float4*)(cgate + i * 256 + lane * 4);
;                 v[i].x += cg.x * (p0.x + p1.x); v[i].y += cg.y * (p0.y + p1.y); v[i].z += cg.z * (p0.z + p1.z); v[i].w += cg.w * (p0.w + p1.w);
;                 *(float4*)(hcout + po) = v[i];
;             }
;             ss += v[i].x * v[i].x + v[i].y * v[i].y + v[i].z * v[i].z + v[i].w * v[i].w; }
;         ss = wave_sum(ss);
;         const float rstd = rsqrtf(ss * (1.0f / 1024.0f) + EPS);
;         const float* mr = modl + (size_t)r * 6144;
; #pragma unroll
;         for (int i = 0; i < 4; ++i) {
;             const int k = i * 256 + lane * 4;
;             const float4 gg = *(const float4*)(g + k), scv = *(const float4*)(mr + sc_off + k), shv = *(const float4*)(mr + sh_off + k);
;             const float o0 = v[i].x * rstd * gg.x * (1.0f + scv.x) + shv.x, o1 = v[i].y * rstd * gg.y * (1.0f + scv.y) + shv.y;
;             const float o2 = v[i].z * rstd * gg.z * (1.0f + scv.z) + shv.z, o3 = v[i].w * rstd * gg.w * (1.0f + scv.w) + shv.w;
;             uint2 w; w.x = pk2(o0, o1); w.y = pk2(o2, o3);
;             *(uint2*)(A + (size_t)row * 1024 + k) = w;
	v_pk_mul_f32 v[128:129], v[128:129], v[204:205] op_sel_hi:[1,0]
	v_pk_mul_f32 v[130:131], v[130:131], v[204:205] op_sel_hi:[1,0]
	v_pk_mul_f32 v[128:129], v[156:157], v[128:129]
	v_pk_mul_f32 v[130:131], v[158:159], v[130:131]
	v_pk_add_f32 v[242:243], v[34:35], 1.0 op_sel_hi:[1,0]
	v_pk_add_f32 v[244:245], v[36:37], 1.0 op_sel_hi:[1,0]
	v_pk_fma_f32 v[128:129], v[242:243], v[128:129], v[224:225]
	v_pk_fma_f32 v[130:131], v[244:245], v[130:131], v[226:227]
	v_cvt_pk_bf16_f32 v128, v128, v129
	v_cvt_pk_bf16_f32 v129, v130, v131
	global_store_dwordx2 v146, v[128:129], s[66:67]
	v_pk_mul_f32 v[132:133], v[132:133], v[204:205] op_sel_hi:[1,0]
	v_pk_mul_f32 v[134:135], v[134:135], v[204:205] op_sel_hi:[1,0]
	v_pk_mul_f32 v[132:133], v[160:161], v[132:133]
	v_pk_mul_f32 v[134:135], v[162:163], v[134:135]
	v_pk_add_f32 v[242:243], v[38:39], 1.0 op_sel_hi:[1,0]
	v_pk_add_f32 v[244:245], v[40:41], 1.0 op_sel_hi:[1,0]
	v_pk_fma_f32 v[132:133], v[242:243], v[132:133], v[228:229]
	v_pk_fma_f32 v[134:135], v[244:245], v[134:135], v[230:231]
	v_cvt_pk_bf16_f32 v132, v132, v133
	v_cvt_pk_bf16_f32 v133, v134, v135
	global_store_dwordx2 v146, v[132:133], s[66:67] offset:512
	v_pk_mul_f32 v[136:137], v[136:137], v[204:205] op_sel_hi:[1,0]
	v_pk_mul_f32 v[138:139], v[138:139], v[204:205] op_sel_hi:[1,0]
	v_pk_mul_f32 v[136:137], v[164:165], v[136:137]
	v_pk_mul_f32 v[138:139], v[166:167], v[138:139]
	v_pk_add_f32 v[242:243], v[42:43], 1.0 op_sel_hi:[1,0]
	v_pk_add_f32 v[244:245], v[44:45], 1.0 op_sel_hi:[1,0]
	v_pk_fma_f32 v[136:137], v[242:243], v[136:137], v[232:233]
	v_pk_fma_f32 v[138:139], v[244:245], v[138:139], v[234:235]
	v_cvt_pk_bf16_f32 v136, v136, v137
	v_cvt_pk_bf16_f32 v137, v138, v139
	global_store_dwordx2 v146, v[136:137], s[66:67] offset:1024
	v_pk_mul_f32 v[140:141], v[140:141], v[204:205] op_sel_hi:[1,0]
	v_pk_mul_f32 v[142:143], v[142:143], v[204:205] op_sel_hi:[1,0]
	v_pk_mul_f32 v[140:141], v[168:169], v[140:141]
	v_pk_mul_f32 v[142:143], v[170:171], v[142:143]
	v_pk_add_f32 v[242:243], v[46:47], 1.0 op_sel_hi:[1,0]
	v_pk_add_f32 v[244:245], v[48:49], 1.0 op_sel_hi:[1,0]
	v_pk_fma_f32 v[140:141], v[242:243], v[140:141], v[236:237]
	v_pk_fma_f32 v[142:143], v[244:245], v[142:143], v[238:239]
	v_cvt_pk_bf16_f32 v140, v140, v141
	v_cvt_pk_bf16_f32 v141, v142, v143
	global_store_dwordx2 v146, v[140:141], s[66:67] offset:1536
	v_add_u32_e32 v146, 0x400000, v146
	global_load_dwordx4 v[34:37], v148, s[98:99]
	global_load_dwordx4 v[38:41], v148, s[98:99] offset:1024
	global_load_dwordx4 v[42:45], v148, s[98:99] offset:2048
	global_load_dwordx4 v[46:49], v148, s[98:99] offset:3072
	global_load_dwordx4 v[224:227], v148, s[50:51]
	global_load_dwordx4 v[228:231], v148, s[50:51] offset:1024
	global_load_dwordx4 v[232:235], v148, s[50:51] offset:2048
	global_load_dwordx4 v[236:239], v148, s[50:51] offset:3072
	v_add_u32_e32 v148, 0x6000, v148
	global_load_dwordx4 v[128:131], v144, s[46:47]
	global_load_dwordx4 v[132:135], v144, s[46:47] offset:1024
	global_load_dwordx4 v[136:139], v144, s[46:47] offset:2048
	global_load_dwordx4 v[140:143], v144, s[46:47] offset:3072
	v_add_u32_e32 v144, 0x800000, v144
	v_pk_mul_f32 v[242:243], v[80:81], v[80:81]
	v_pk_mul_f32 v[244:245], v[84:85], v[84:85]
	v_pk_mul_f32 v[246:247], v[82:83], v[82:83]
	v_pk_mul_f32 v[248:249], v[86:87], v[86:87]
	v_add_f32_e32 v204, v245, v244
	v_add_f32_e32 v205, v243, v242
	v_add_f32_e32 v204, v248, v204
	v_add_f32_e32 v205, v246, v205
	v_add_f32_e32 v204, v249, v204
	v_add_f32_e32 v205, v247, v205
	v_pk_mul_f32 v[242:243], v[88:89], v[88:89]
	v_pk_mul_f32 v[244:245], v[92:93], v[92:93]
	v_pk_mul_f32 v[246:247], v[90:91], v[90:91]
	v_pk_mul_f32 v[248:249], v[94:95], v[94:95]
	v_add_f32_e32 v206, v243, v242
	v_add_f32_e32 v207, v245, v244
	v_add_f32_e32 v206, v246, v206
	v_add_f32_e32 v207, v248, v207
	v_add_f32_e32 v206, v247, v206
	v_add_f32_e32 v207, v249, v207
	v_add_f32_e32 v204, v205, v204
	v_add_f32_e32 v204, v204, v206
	v_add_f32_e32 v204, v204, v207
	ds_swizzle_b32 v205, v204 offset:swizzle(SWAP,1)
	s_waitcnt lgkmcnt(0)
	v_add_f32_e32 v204, v204, v205
	ds_swizzle_b32 v205, v204 offset:swizzle(SWAP,2)
	s_waitcnt lgkmcnt(0)
	v_add_f32_e32 v204, v204, v205
	ds_swizzle_b32 v205, v204 offset:swizzle(SWAP,4)
	s_waitcnt lgkmcnt(0)
	v_add_f32_e32 v204, v204, v205
	ds_swizzle_b32 v205, v204 offset:swizzle(SWAP,8)
	s_waitcnt lgkmcnt(0)
	v_add_f32_e32 v204, v204, v205
	ds_swizzle_b32 v205, v204 offset:swizzle(SWAP,16)
	s_waitcnt lgkmcnt(0)
	v_add_f32_e32 v204, v204, v205
	v_mov_b32_e32 v205, v204
	s_nop 1
	v_permlane32_swap_b32_e32 v204, v205
	v_add_f32_e32 v204, v204, v205
	v_mov_b32_e32 v205, 0x358637bd
	v_fmamk_f32 v204, v204, 0x3a800000, v205
	v_rsq_f32_e32 v204, v204
	s_nop 0
	s_waitcnt vmcnt(20)
; __device__ __forceinline__ unsigned pk2(float lo, float hi) { const g_f32x2 f = {lo, hi}; return __builtin_bit_cast(unsigned, __builtin_convertvector(f, g_bf16x2)); }
; __device__ __forceinline__ void p_norm(const float* hlat, const float* hctx, const float* g, const float* modl, int sh_off, int sc_off, bf16_t* A, int M,
;                                        const float* part, const float* cgate, float* hcout) {
;     ...
;         float ss = 0.f;
; #pragma unroll
;         for (int i = 0; i < 4; ++i) {
;             if (part != nullptr && row >= NLAT) {
;                 const size_t po = (size_t)(row - NLAT) * 1024 + i * 256 + lane * 4;
;                 const float4 p0 = *(const float4*)(part + po), p1 = *(const float4*)(part + (size_t)4096 * 1024 + po), cg = *(const float4*)(cgate + i * 256 + lane * 4);
;                 v[i].x += cg.x * (p0.x + p1.x); v[i].y += cg.y * (p0.y + p1.y); v[i].z += cg.z * (p0.z + p1.z); v[i].w += cg.w * (p0.w + p1.w);
;                 *(float4*)(hcout + po) = v[i];
;             }
;             ss += v[i].x * v[i].x + v[i].y * v[i].y + v[i].z * v[i].z + v[i].w * v[i].w; }
;         ss = wave_sum(ss);
;         const float rstd = rsqrtf(ss * (1.0f / 1024.0f) + EPS);
;         const float* mr = modl + (size_t)r * 6144;
; #pragma unroll
;         for (int i = 0; i < 4; ++i) {
;             const int k = i * 256 + lane * 4;
;             const float4 gg = *(const float4*)(g + k), scv = *(const float4*)(mr + sc_off + k), shv = *(const float4*)(mr + sh_off + k);
;             const float o0 = v[i].x * rstd * gg.x * (1.0f + scv.x) + shv.x, o1 = v[i].y * rstd * gg.y * (1.0f + scv.y) + shv.y;
;             const float o2 = v[i].z * rstd * gg.z * (1.0f + scv.z) + shv.z, o3 = v[i].w * rstd * gg.w * (1.0f + scv.w) + shv.w;
;             uint2 w; w.x = pk2(o0, o1); w.y = pk2(o2, o3);
;             *(uint2*)(A + (size_t)row * 1024 + k) = w;
	v_pk_mul_f32 v[80:81], v[80:81], v[204:205] op_sel_hi:[1,0]
	v_pk_mul_f32 v[82:83], v[82:83], v[204:205] op_sel_hi:[1,0]
	v_pk_mul_f32 v[80:81], v[156:157], v[80:81]
	v_pk_mul_f32 v[82:83], v[158:159], v[82:83]
	v_pk_add_f32 v[242:243], v[172:173], 1.0 op_sel_hi:[1,0]
	v_pk_add_f32 v[244:245], v[174:175], 1.0 op_sel_hi:[1,0]
	v_pk_fma_f32 v[80:81], v[242:243], v[80:81], v[188:189]
	v_pk_fma_f32 v[82:83], v[244:245], v[82:83], v[190:191]
	v_cvt_pk_bf16_f32 v80, v80, v81
	v_cvt_pk_bf16_f32 v81, v82, v83
	global_store_dwordx2 v146, v[80:81], s[66:67]
	v_pk_mul_f32 v[84:85], v[84:85], v[204:205] op_sel_hi:[1,0]
	v_pk_mul_f32 v[86:87], v[86:87], v[204:205] op_sel_hi:[1,0]
	v_pk_mul_f32 v[84:85], v[160:161], v[84:85]
	v_pk_mul_f32 v[86:87], v[162:163], v[86:87]
	v_pk_add_f32 v[242:243], v[176:177], 1.0 op_sel_hi:[1,0]
	v_pk_add_f32 v[244:245], v[178:179], 1.0 op_sel_hi:[1,0]
	v_pk_fma_f32 v[84:85], v[242:243], v[84:85], v[192:193]
	v_pk_fma_f32 v[86:87], v[244:245], v[86:87], v[194:195]
	v_cvt_pk_bf16_f32 v84, v84, v85
	v_cvt_pk_bf16_f32 v85, v86, v87
	global_store_dwordx2 v146, v[84:85], s[66:67] offset:512
	v_pk_mul_f32 v[88:89], v[88:89], v[204:205] op_sel_hi:[1,0]
	v_pk_mul_f32 v[90:91], v[90:91], v[204:205] op_sel_hi:[1,0]
	v_pk_mul_f32 v[88:89], v[164:165], v[88:89]
	v_pk_mul_f32 v[90:91], v[166:167], v[90:91]
	v_pk_add_f32 v[242:243], v[180:181], 1.0 op_sel_hi:[1,0]
	v_pk_add_f32 v[244:245], v[182:183], 1.0 op_sel_hi:[1,0]
	v_pk_fma_f32 v[88:89], v[242:243], v[88:89], v[196:197]
	v_pk_fma_f32 v[90:91], v[244:245], v[90:91], v[198:199]
	v_cvt_pk_bf16_f32 v88, v88, v89
	v_cvt_pk_bf16_f32 v89, v90, v91
	global_store_dwordx2 v146, v[88:89], s[66:67] offset:1024
	v_pk_mul_f32 v[92:93], v[92:93], v[204:205] op_sel_hi:[1,0]
	v_pk_mul_f32 v[94:95], v[94:95], v[204:205] op_sel_hi:[1,0]
	v_pk_mul_f32 v[92:93], v[168:169], v[92:93]
	v_pk_mul_f32 v[94:95], v[170:171], v[94:95]
	v_pk_add_f32 v[242:243], v[184:185], 1.0 op_sel_hi:[1,0]
	v_pk_add_f32 v[244:245], v[186:187], 1.0 op_sel_hi:[1,0]
	v_pk_fma_f32 v[92:93], v[242:243], v[92:93], v[200:201]
	v_pk_fma_f32 v[94:95], v[244:245], v[94:95], v[202:203]
	v_cvt_pk_bf16_f32 v92, v92, v93
	v_cvt_pk_bf16_f32 v93, v94, v95
	global_store_dwordx2 v146, v[92:93], s[66:67] offset:1536
	v_add_u32_e32 v146, 0x400000, v146
	global_load_dwordx4 v[172:175], v148, s[98:99]
	global_load_dwordx4 v[176:179], v148, s[98:99] offset:1024
	global_load_dwordx4 v[180:183], v148, s[98:99] offset:2048
	global_load_dwordx4 v[184:187], v148, s[98:99] offset:3072
	global_load_dwordx4 v[188:191], v148, s[50:51]
	global_load_dwordx4 v[192:195], v148, s[50:51] offset:1024
	global_load_dwordx4 v[196:199], v148, s[50:51] offset:2048
	global_load_dwordx4 v[200:203], v148, s[50:51] offset:3072
	v_add_u32_e32 v148, 0x6000, v148
	global_load_dwordx4 v[80:83], v144, s[46:47]
	global_load_dwordx4 v[84:87], v144, s[46:47] offset:1024
	global_load_dwordx4 v[88:91], v144, s[46:47] offset:2048
	global_load_dwordx4 v[92:95], v144, s[46:47] offset:3072
	v_add_u32_e32 v144, 0x800000, v144
	v_pk_mul_f32 v[242:243], v[96:97], v[96:97]
	v_pk_mul_f32 v[244:245], v[100:101], v[100:101]
	v_pk_mul_f32 v[246:247], v[98:99], v[98:99]
	v_pk_mul_f32 v[248:249], v[102:103], v[102:103]
	v_add_f32_e32 v204, v245, v244
	v_add_f32_e32 v205, v243, v242
	v_add_f32_e32 v204, v248, v204
	v_add_f32_e32 v205, v246, v205
	v_add_f32_e32 v204, v249, v204
	v_add_f32_e32 v205, v247, v205
	v_pk_mul_f32 v[242:243], v[104:105], v[104:105]
	v_pk_mul_f32 v[244:245], v[108:109], v[108:109]
	v_pk_mul_f32 v[246:247], v[106:107], v[106:107]
	v_pk_mul_f32 v[248:249], v[110:111], v[110:111]
	v_add_f32_e32 v206, v243, v242
	v_add_f32_e32 v207, v245, v244
	v_add_f32_e32 v206, v246, v206
	v_add_f32_e32 v207, v248, v207
	v_add_f32_e32 v206, v247, v206
	v_add_f32_e32 v207, v249, v207
	v_add_f32_e32 v204, v205, v204
	v_add_f32_e32 v204, v204, v206
	v_add_f32_e32 v204, v204, v207
	ds_swizzle_b32 v205, v204 offset:swizzle(SWAP,1)
	s_waitcnt lgkmcnt(0)
	v_add_f32_e32 v204, v204, v205
	ds_swizzle_b32 v205, v204 offset:swizzle(SWAP,2)
	s_waitcnt lgkmcnt(0)
	v_add_f32_e32 v204, v204, v205
	ds_swizzle_b32 v205, v204 offset:swizzle(SWAP,4)
	s_waitcnt lgkmcnt(0)
	v_add_f32_e32 v204, v204, v205
	ds_swizzle_b32 v205, v204 offset:swizzle(SWAP,8)
	s_waitcnt lgkmcnt(0)
	v_add_f32_e32 v204, v204, v205
	ds_swizzle_b32 v205, v204 offset:swizzle(SWAP,16)
	s_waitcnt lgkmcnt(0)
	v_add_f32_e32 v204, v204, v205
	v_mov_b32_e32 v205, v204
	s_nop 1
	v_permlane32_swap_b32_e32 v204, v205
	v_add_f32_e32 v204, v204, v205
	v_mov_b32_e32 v205, 0x358637bd
	v_fmamk_f32 v204, v204, 0x3a800000, v205
	v_rsq_f32_e32 v204, v204
	s_nop 0
	s_waitcnt vmcnt(20)
; __device__ __forceinline__ unsigned pk2(float lo, float hi) { const g_f32x2 f = {lo, hi}; return __builtin_bit_cast(unsigned, __builtin_convertvector(f, g_bf16x2)); }
; __device__ __forceinline__ void p_norm(const float* hlat, const float* hctx, const float* g, const float* modl, int sh_off, int sc_off, bf16_t* A, int M,
;                                        const float* part, const float* cgate, float* hcout) {
;     ...
;         float ss = 0.f;
; #pragma unroll
;         for (int i = 0; i < 4; ++i) {
;             if (part != nullptr && row >= NLAT) {
;                 const size_t po = (size_t)(row - NLAT) * 1024 + i * 256 + lane * 4;
;                 const float4 p0 = *(const float4*)(part + po), p1 = *(const float4*)(part + (size_t)4096 * 1024 + po), cg = *(const float4*)(cgate + i * 256 + lane * 4);
;                 v[i].x += cg.x * (p0.x + p1.x); v[i].y += cg.y * (p0.y + p1.y); v[i].z += cg.z * (p0.z + p1.z); v[i].w += cg.w * (p0.w + p1.w);
;                 *(float4*)(hcout + po) = v[i];
;             }
;             ss += v[i].x * v[i].x + v[i].y * v[i].y + v[i].z * v[i].z + v[i].w * v[i].w; }
;         ss = wave_sum(ss);
;         const float rstd = rsqrtf(ss * (1.0f / 1024.0f) + EPS);
;         const float* mr = modl + (size_t)r * 6144;
; #pragma unroll
;         for (int i = 0; i < 4; ++i) {
;             const int k = i * 256 + lane * 4;
;             const float4 gg = *(const float4*)(g + k), scv = *(const float4*)(mr + sc_off + k), shv = *(const float4*)(mr + sh_off + k);
;             const float o0 = v[i].x * rstd * gg.x * (1.0f + scv.x) + shv.x, o1 = v[i].y * rstd * gg.y * (1.0f + scv.y) + shv.y;
;             const float o2 = v[i].z * rstd * gg.z * (1.0f + scv.z) + shv.z, o3 = v[i].w * rstd * gg.w * (1.0f + scv.w) + shv.w;
;             uint2 w; w.x = pk2(o0, o1); w.y = pk2(o2, o3);
;             *(uint2*)(A + (size_t)row * 1024 + k) = w;
	v_pk_mul_f32 v[96:97], v[96:97], v[204:205] op_sel_hi:[1,0]
	v_pk_mul_f32 v[98:99], v[98:99], v[204:205] op_sel_hi:[1,0]
	v_pk_mul_f32 v[96:97], v[156:157], v[96:97]
	v_pk_mul_f32 v[98:99], v[158:159], v[98:99]
	v_pk_add_f32 v[242:243], v[34:35], 1.0 op_sel_hi:[1,0]
	v_pk_add_f32 v[244:245], v[36:37], 1.0 op_sel_hi:[1,0]
	v_pk_fma_f32 v[96:97], v[242:243], v[96:97], v[224:225]
	v_pk_fma_f32 v[98:99], v[244:245], v[98:99], v[226:227]
	v_cvt_pk_bf16_f32 v96, v96, v97
	v_cvt_pk_bf16_f32 v97, v98, v99
	global_store_dwordx2 v146, v[96:97], s[66:67]
	v_pk_mul_f32 v[100:101], v[100:101], v[204:205] op_sel_hi:[1,0]
	v_pk_mul_f32 v[102:103], v[102:103], v[204:205] op_sel_hi:[1,0]
	v_pk_mul_f32 v[100:101], v[160:161], v[100:101]
	v_pk_mul_f32 v[102:103], v[162:163], v[102:103]
	v_pk_add_f32 v[242:243], v[38:39], 1.0 op_sel_hi:[1,0]
	v_pk_add_f32 v[244:245], v[40:41], 1.0 op_sel_hi:[1,0]
	v_pk_fma_f32 v[100:101], v[242:243], v[100:101], v[228:229]
	v_pk_fma_f32 v[102:103], v[244:245], v[102:103], v[230:231]
	v_cvt_pk_bf16_f32 v100, v100, v101
	v_cvt_pk_bf16_f32 v101, v102, v103
	global_store_dwordx2 v146, v[100:101], s[66:67] offset:512
	v_pk_mul_f32 v[104:105], v[104:105], v[204:205] op_sel_hi:[1,0]
	v_pk_mul_f32 v[106:107], v[106:107], v[204:205] op_sel_hi:[1,0]
	v_pk_mul_f32 v[104:105], v[164:165], v[104:105]
	v_pk_mul_f32 v[106:107], v[166:167], v[106:107]
	v_pk_add_f32 v[242:243], v[42:43], 1.0 op_sel_hi:[1,0]
	v_pk_add_f32 v[244:245], v[44:45], 1.0 op_sel_hi:[1,0]
	v_pk_fma_f32 v[104:105], v[242:243], v[104:105], v[232:233]
	v_pk_fma_f32 v[106:107], v[244:245], v[106:107], v[234:235]
	v_cvt_pk_bf16_f32 v104, v104, v105
	v_cvt_pk_bf16_f32 v105, v106, v107
	global_store_dwordx2 v146, v[104:105], s[66:67] offset:1024
	v_pk_mul_f32 v[108:109], v[108:109], v[204:205] op_sel_hi:[1,0]
	v_pk_mul_f32 v[110:111], v[110:111], v[204:205] op_sel_hi:[1,0]
	v_pk_mul_f32 v[108:109], v[168:169], v[108:109]
	v_pk_mul_f32 v[110:111], v[170:171], v[110:111]
	v_pk_add_f32 v[242:243], v[46:47], 1.0 op_sel_hi:[1,0]
	v_pk_add_f32 v[244:245], v[48:49], 1.0 op_sel_hi:[1,0]
	v_pk_fma_f32 v[108:109], v[242:243], v[108:109], v[236:237]
	v_pk_fma_f32 v[110:111], v[244:245], v[110:111], v[238:239]
	v_cvt_pk_bf16_f32 v108, v108, v109
	v_cvt_pk_bf16_f32 v109, v110, v111
	global_store_dwordx2 v146, v[108:109], s[66:67] offset:1536
	v_add_u32_e32 v146, 0x400000, v146
	global_load_dwordx4 v[34:37], v148, s[98:99]
	global_load_dwordx4 v[38:41], v148, s[98:99] offset:1024
	global_load_dwordx4 v[42:45], v148, s[98:99] offset:2048
	global_load_dwordx4 v[46:49], v148, s[98:99] offset:3072
	global_load_dwordx4 v[224:227], v148, s[50:51]
	global_load_dwordx4 v[228:231], v148, s[50:51] offset:1024
	global_load_dwordx4 v[232:235], v148, s[50:51] offset:2048
	global_load_dwordx4 v[236:239], v148, s[50:51] offset:3072
	v_add_u32_e32 v148, 0x6000, v148
	global_load_dwordx4 v[96:99], v144, s[46:47]
	global_load_dwordx4 v[100:103], v144, s[46:47] offset:1024
	global_load_dwordx4 v[104:107], v144, s[46:47] offset:2048
	global_load_dwordx4 v[108:111], v144, s[46:47] offset:3072
	v_add_u32_e32 v144, 0x800000, v144
	v_pk_mul_f32 v[242:243], v[112:113], v[112:113]
	v_pk_mul_f32 v[244:245], v[116:117], v[116:117]
	v_pk_mul_f32 v[246:247], v[114:115], v[114:115]
	v_pk_mul_f32 v[248:249], v[118:119], v[118:119]
	v_add_f32_e32 v204, v245, v244
	v_add_f32_e32 v205, v243, v242
	v_add_f32_e32 v204, v248, v204
	v_add_f32_e32 v205, v246, v205
	v_add_f32_e32 v204, v249, v204
	v_add_f32_e32 v205, v247, v205
	v_pk_mul_f32 v[242:243], v[120:121], v[120:121]
	v_pk_mul_f32 v[244:245], v[124:125], v[124:125]
	v_pk_mul_f32 v[246:247], v[122:123], v[122:123]
	v_pk_mul_f32 v[248:249], v[126:127], v[126:127]
	v_add_f32_e32 v206, v243, v242
	v_add_f32_e32 v207, v245, v244
	v_add_f32_e32 v206, v246, v206
	v_add_f32_e32 v207, v248, v207
	v_add_f32_e32 v206, v247, v206
	v_add_f32_e32 v207, v249, v207
	v_add_f32_e32 v204, v205, v204
	v_add_f32_e32 v204, v204, v206
	v_add_f32_e32 v204, v204, v207
	ds_swizzle_b32 v205, v204 offset:swizzle(SWAP,1)
	s_waitcnt lgkmcnt(0)
	v_add_f32_e32 v204, v204, v205
	ds_swizzle_b32 v205, v204 offset:swizzle(SWAP,2)
	s_waitcnt lgkmcnt(0)
	v_add_f32_e32 v204, v204, v205
	ds_swizzle_b32 v205, v204 offset:swizzle(SWAP,4)
	s_waitcnt lgkmcnt(0)
	v_add_f32_e32 v204, v204, v205
	ds_swizzle_b32 v205, v204 offset:swizzle(SWAP,8)
	s_waitcnt lgkmcnt(0)
	v_add_f32_e32 v204, v204, v205
	ds_swizzle_b32 v205, v204 offset:swizzle(SWAP,16)
	s_waitcnt lgkmcnt(0)
	v_add_f32_e32 v204, v204, v205
	v_mov_b32_e32 v205, v204
	s_nop 1
	v_permlane32_swap_b32_e32 v204, v205
	v_add_f32_e32 v204, v204, v205
	v_mov_b32_e32 v205, 0x358637bd
	v_fmamk_f32 v204, v204, 0x3a800000, v205
	v_rsq_f32_e32 v204, v204
	s_nop 0
	s_waitcnt vmcnt(20)
; __device__ __forceinline__ unsigned pk2(float lo, float hi) { const g_f32x2 f = {lo, hi}; return __builtin_bit_cast(unsigned, __builtin_convertvector(f, g_bf16x2)); }
; __device__ __forceinline__ void p_norm(const float* hlat, const float* hctx, const float* g, const float* modl, int sh_off, int sc_off, bf16_t* A, int M,
;                                        const float* part, const float* cgate, float* hcout) {
;     ...
;         float ss = 0.f;
; #pragma unroll
;         for (int i = 0; i < 4; ++i) {
;             if (part != nullptr && row >= NLAT) {
;                 const size_t po = (size_t)(row - NLAT) * 1024 + i * 256 + lane * 4;
;                 const float4 p0 = *(const float4*)(part + po), p1 = *(const float4*)(part + (size_t)4096 * 1024 + po), cg = *(const float4*)(cgate + i * 256 + lane * 4);
;                 v[i].x += cg.x * (p0.x + p1.x); v[i].y += cg.y * (p0.y + p1.y); v[i].z += cg.z * (p0.z + p1.z); v[i].w += cg.w * (p0.w + p1.w);
;                 *(float4*)(hcout + po) = v[i];
;             }
;             ss += v[i].x * v[i].x + v[i].y * v[i].y + v[i].z * v[i].z + v[i].w * v[i].w; }
;         ss = wave_sum(ss);
;         const float rstd = rsqrtf(ss * (1.0f / 1024.0f) + EPS);
;         const float* mr = modl + (size_t)r * 6144;
; #pragma unroll
;         for (int i = 0; i < 4; ++i) {
;             const int k = i * 256 + lane * 4;
;             const float4 gg = *(const float4*)(g + k), scv = *(const float4*)(mr + sc_off + k), shv = *(const float4*)(mr + sh_off + k);
;             const float o0 = v[i].x * rstd * gg.x * (1.0f + scv.x) + shv.x, o1 = v[i].y * rstd * gg.y * (1.0f + scv.y) + shv.y;
;             const float o2 = v[i].z * rstd * gg.z * (1.0f + scv.z) + shv.z, o3 = v[i].w * rstd * gg.w * (1.0f + scv.w) + shv.w;
;             uint2 w; w.x = pk2(o0, o1); w.y = pk2(o2, o3);
;             *(uint2*)(A + (size_t)row * 1024 + k) = w;
	v_pk_mul_f32 v[112:113], v[112:113], v[204:205] op_sel_hi:[1,0]
	v_pk_mul_f32 v[114:115], v[114:115], v[204:205] op_sel_hi:[1,0]
	v_pk_mul_f32 v[112:113], v[156:157], v[112:113]
	v_pk_mul_f32 v[114:115], v[158:159], v[114:115]
	v_pk_add_f32 v[242:243], v[172:173], 1.0 op_sel_hi:[1,0]
	v_pk_add_f32 v[244:245], v[174:175], 1.0 op_sel_hi:[1,0]
	v_pk_fma_f32 v[112:113], v[242:243], v[112:113], v[188:189]
	v_pk_fma_f32 v[114:115], v[244:245], v[114:115], v[190:191]
	v_cvt_pk_bf16_f32 v112, v112, v113
	v_cvt_pk_bf16_f32 v113, v114, v115
	global_store_dwordx2 v146, v[112:113], s[66:67]
	v_pk_mul_f32 v[116:117], v[116:117], v[204:205] op_sel_hi:[1,0]
	v_pk_mul_f32 v[118:119], v[118:119], v[204:205] op_sel_hi:[1,0]
	v_pk_mul_f32 v[116:117], v[160:161], v[116:117]
	v_pk_mul_f32 v[118:119], v[162:163], v[118:119]
	v_pk_add_f32 v[242:243], v[176:177], 1.0 op_sel_hi:[1,0]
	v_pk_add_f32 v[244:245], v[178:179], 1.0 op_sel_hi:[1,0]
	v_pk_fma_f32 v[116:117], v[242:243], v[116:117], v[192:193]
	v_pk_fma_f32 v[118:119], v[244:245], v[118:119], v[194:195]
	v_cvt_pk_bf16_f32 v116, v116, v117
	v_cvt_pk_bf16_f32 v117, v118, v119
	global_store_dwordx2 v146, v[116:117], s[66:67] offset:512
	v_pk_mul_f32 v[120:121], v[120:121], v[204:205] op_sel_hi:[1,0]
	v_pk_mul_f32 v[122:123], v[122:123], v[204:205] op_sel_hi:[1,0]
	v_pk_mul_f32 v[120:121], v[164:165], v[120:121]
	v_pk_mul_f32 v[122:123], v[166:167], v[122:123]
	v_pk_add_f32 v[242:243], v[180:181], 1.0 op_sel_hi:[1,0]
	v_pk_add_f32 v[244:245], v[182:183], 1.0 op_sel_hi:[1,0]
	v_pk_fma_f32 v[120:121], v[242:243], v[120:121], v[196:197]
	v_pk_fma_f32 v[122:123], v[244:245], v[122:123], v[198:199]
	v_cvt_pk_bf16_f32 v120, v120, v121
	v_cvt_pk_bf16_f32 v121, v122, v123
	global_store_dwordx2 v146, v[120:121], s[66:67] offset:1024
	v_pk_mul_f32 v[124:125], v[124:125], v[204:205] op_sel_hi:[1,0]
	v_pk_mul_f32 v[126:127], v[126:127], v[204:205] op_sel_hi:[1,0]
	v_pk_mul_f32 v[124:125], v[168:169], v[124:125]
	v_pk_mul_f32 v[126:127], v[170:171], v[126:127]
	v_pk_add_f32 v[242:243], v[184:185], 1.0 op_sel_hi:[1,0]
	v_pk_add_f32 v[244:245], v[186:187], 1.0 op_sel_hi:[1,0]
	v_pk_fma_f32 v[124:125], v[242:243], v[124:125], v[200:201]
	v_pk_fma_f32 v[126:127], v[244:245], v[126:127], v[202:203]
	v_cvt_pk_bf16_f32 v124, v124, v125
	v_cvt_pk_bf16_f32 v125, v126, v127
	global_store_dwordx2 v146, v[124:125], s[66:67] offset:1536
	v_add_u32_e32 v146, 0x400000, v146
	global_load_dwordx4 v[172:175], v148, s[98:99]
	global_load_dwordx4 v[176:179], v148, s[98:99] offset:1024
	global_load_dwordx4 v[180:183], v148, s[98:99] offset:2048
	global_load_dwordx4 v[184:187], v148, s[98:99] offset:3072
	global_load_dwordx4 v[188:191], v148, s[50:51]
	global_load_dwordx4 v[192:195], v148, s[50:51] offset:1024
	global_load_dwordx4 v[196:199], v148, s[50:51] offset:2048
	global_load_dwordx4 v[200:203], v148, s[50:51] offset:3072
	v_add_u32_e32 v148, 0x6000, v148
	global_load_dwordx4 v[112:115], v144, s[46:47]
	global_load_dwordx4 v[116:119], v144, s[46:47] offset:1024
	global_load_dwordx4 v[120:123], v144, s[46:47] offset:2048
	global_load_dwordx4 v[124:127], v144, s[46:47] offset:3072
	v_add_u32_e32 v144, 0x800000, v144
	v_pk_mul_f32 v[242:243], v[128:129], v[128:129]
	v_pk_mul_f32 v[244:245], v[132:133], v[132:133]
	v_pk_mul_f32 v[246:247], v[130:131], v[130:131]
	v_pk_mul_f32 v[248:249], v[134:135], v[134:135]
	v_add_f32_e32 v204, v245, v244
	v_add_f32_e32 v205, v243, v242
	v_add_f32_e32 v204, v248, v204
	v_add_f32_e32 v205, v246, v205
	v_add_f32_e32 v204, v249, v204
	v_add_f32_e32 v205, v247, v205
	v_pk_mul_f32 v[242:243], v[136:137], v[136:137]
	v_pk_mul_f32 v[244:245], v[140:141], v[140:141]
	v_pk_mul_f32 v[246:247], v[138:139], v[138:139]
	v_pk_mul_f32 v[248:249], v[142:143], v[142:143]
	v_add_f32_e32 v206, v243, v242
	v_add_f32_e32 v207, v245, v244
	v_add_f32_e32 v206, v246, v206
	v_add_f32_e32 v207, v248, v207
	v_add_f32_e32 v206, v247, v206
	v_add_f32_e32 v207, v249, v207
	v_add_f32_e32 v204, v205, v204
	v_add_f32_e32 v204, v204, v206
	v_add_f32_e32 v204, v204, v207
	ds_swizzle_b32 v205, v204 offset:swizzle(SWAP,1)
	s_waitcnt lgkmcnt(0)
	v_add_f32_e32 v204, v204, v205
	ds_swizzle_b32 v205, v204 offset:swizzle(SWAP,2)
	s_waitcnt lgkmcnt(0)
	v_add_f32_e32 v204, v204, v205
	ds_swizzle_b32 v205, v204 offset:swizzle(SWAP,4)
	s_waitcnt lgkmcnt(0)
	v_add_f32_e32 v204, v204, v205
	ds_swizzle_b32 v205, v204 offset:swizzle(SWAP,8)
	s_waitcnt lgkmcnt(0)
	v_add_f32_e32 v204, v204, v205
	ds_swizzle_b32 v205, v204 offset:swizzle(SWAP,16)
	s_waitcnt lgkmcnt(0)
	v_add_f32_e32 v204, v204, v205
	v_mov_b32_e32 v205, v204
	s_nop 1
	v_permlane32_swap_b32_e32 v204, v205
	v_add_f32_e32 v204, v204, v205
	v_mov_b32_e32 v205, 0x358637bd
	v_fmamk_f32 v204, v204, 0x3a800000, v205
	v_rsq_f32_e32 v204, v204
	s_nop 0
	s_waitcnt vmcnt(20)
; __device__ __forceinline__ unsigned pk2(float lo, float hi) { const g_f32x2 f = {lo, hi}; return __builtin_bit_cast(unsigned, __builtin_convertvector(f, g_bf16x2)); }
; __device__ __forceinline__ void p_norm(const float* hlat, const float* hctx, const float* g, const float* modl, int sh_off, int sc_off, bf16_t* A, int M,
;                                        const float* part, const float* cgate, float* hcout) {
;     ...
;         float ss = 0.f;
; #pragma unroll
;         for (int i = 0; i < 4; ++i) {
;             if (part != nullptr && row >= NLAT) {
;                 const size_t po = (size_t)(row - NLAT) * 1024 + i * 256 + lane * 4;
;                 const float4 p0 = *(const float4*)(part + po), p1 = *(const float4*)(part + (size_t)4096 * 1024 + po), cg = *(const float4*)(cgate + i * 256 + lane * 4);
;                 v[i].x += cg.x * (p0.x + p1.x); v[i].y += cg.y * (p0.y + p1.y); v[i].z += cg.z * (p0.z + p1.z); v[i].w += cg.w * (p0.w + p1.w);
;                 *(float4*)(hcout + po) = v[i];
;             }
;             ss += v[i].x * v[i].x + v[i].y * v[i].y + v[i].z * v[i].z + v[i].w * v[i].w; }
;         ss = wave_sum(ss);
;         const float rstd = rsqrtf(ss * (1.0f / 1024.0f) + EPS);
;         const float* mr = modl + (size_t)r * 6144;
; #pragma unroll
;         for (int i = 0; i < 4; ++i) {
;             const int k = i * 256 + lane * 4;
;             const float4 gg = *(const float4*)(g + k), scv = *(const float4*)(mr + sc_off + k), shv = *(const float4*)(mr + sh_off + k);
;             const float o0 = v[i].x * rstd * gg.x * (1.0f + scv.x) + shv.x, o1 = v[i].y * rstd * gg.y * (1.0f + scv.y) + shv.y;
;             const float o2 = v[i].z * rstd * gg.z * (1.0f + scv.z) + shv.z, o3 = v[i].w * rstd * gg.w * (1.0f + scv.w) + shv.w;
;             uint2 w; w.x = pk2(o0, o1); w.y = pk2(o2, o3);
;             *(uint2*)(A + (size_t)row * 1024 + k) = w;
	v_pk_mul_f32 v[128:129], v[128:129], v[204:205] op_sel_hi:[1,0]
	v_pk_mul_f32 v[130:131], v[130:131], v[204:205] op_sel_hi:[1,0]
	v_pk_mul_f32 v[128:129], v[156:157], v[128:129]
	v_pk_mul_f32 v[130:131], v[158:159], v[130:131]
	v_pk_add_f32 v[242:243], v[34:35], 1.0 op_sel_hi:[1,0]
	v_pk_add_f32 v[244:245], v[36:37], 1.0 op_sel_hi:[1,0]
	v_pk_fma_f32 v[128:129], v[242:243], v[128:129], v[224:225]
	v_pk_fma_f32 v[130:131], v[244:245], v[130:131], v[226:227]
	v_cvt_pk_bf16_f32 v128, v128, v129
	v_cvt_pk_bf16_f32 v129, v130, v131
	global_store_dwordx2 v146, v[128:129], s[66:67]
	v_pk_mul_f32 v[132:133], v[132:133], v[204:205] op_sel_hi:[1,0]
	v_pk_mul_f32 v[134:135], v[134:135], v[204:205] op_sel_hi:[1,0]
	v_pk_mul_f32 v[132:133], v[160:161], v[132:133]
	v_pk_mul_f32 v[134:135], v[162:163], v[134:135]
	v_pk_add_f32 v[242:243], v[38:39], 1.0 op_sel_hi:[1,0]
	v_pk_add_f32 v[244:245], v[40:41], 1.0 op_sel_hi:[1,0]
	v_pk_fma_f32 v[132:133], v[242:243], v[132:133], v[228:229]
	v_pk_fma_f32 v[134:135], v[244:245], v[134:135], v[230:231]
	v_cvt_pk_bf16_f32 v132, v132, v133
	v_cvt_pk_bf16_f32 v133, v134, v135
	global_store_dwordx2 v146, v[132:133], s[66:67] offset:512
	v_pk_mul_f32 v[136:137], v[136:137], v[204:205] op_sel_hi:[1,0]
	v_pk_mul_f32 v[138:139], v[138:139], v[204:205] op_sel_hi:[1,0]
	v_pk_mul_f32 v[136:137], v[164:165], v[136:137]
	v_pk_mul_f32 v[138:139], v[166:167], v[138:139]
	v_pk_add_f32 v[242:243], v[42:43], 1.0 op_sel_hi:[1,0]
	v_pk_add_f32 v[244:245], v[44:45], 1.0 op_sel_hi:[1,0]
	v_pk_fma_f32 v[136:137], v[242:243], v[136:137], v[232:233]
	v_pk_fma_f32 v[138:139], v[244:245], v[138:139], v[234:235]
	v_cvt_pk_bf16_f32 v136, v136, v137
	v_cvt_pk_bf16_f32 v137, v138, v139
	global_store_dwordx2 v146, v[136:137], s[66:67] offset:1024
	v_pk_mul_f32 v[140:141], v[140:141], v[204:205] op_sel_hi:[1,0]
	v_pk_mul_f32 v[142:143], v[142:143], v[204:205] op_sel_hi:[1,0]
	v_pk_mul_f32 v[140:141], v[168:169], v[140:141]
	v_pk_mul_f32 v[142:143], v[170:171], v[142:143]
	v_pk_add_f32 v[242:243], v[46:47], 1.0 op_sel_hi:[1,0]
	v_pk_add_f32 v[244:245], v[48:49], 1.0 op_sel_hi:[1,0]
	v_pk_fma_f32 v[140:141], v[242:243], v[140:141], v[236:237]
	v_pk_fma_f32 v[142:143], v[244:245], v[142:143], v[238:239]
	v_cvt_pk_bf16_f32 v140, v140, v141
	v_cvt_pk_bf16_f32 v141, v142, v143
	global_store_dwordx2 v146, v[140:141], s[66:67] offset:1536
	v_add_u32_e32 v146, 0x400000, v146
	global_load_dwordx4 v[34:37], v148, s[98:99]
	global_load_dwordx4 v[38:41], v148, s[98:99] offset:1024
	global_load_dwordx4 v[42:45], v148, s[98:99] offset:2048
	global_load_dwordx4 v[46:49], v148, s[98:99] offset:3072
	global_load_dwordx4 v[224:227], v148, s[50:51]
	global_load_dwordx4 v[228:231], v148, s[50:51] offset:1024
	global_load_dwordx4 v[232:235], v148, s[50:51] offset:2048
	global_load_dwordx4 v[236:239], v148, s[50:51] offset:3072
	v_add_u32_e32 v148, 0x6000, v148
	global_load_dwordx4 v[128:131], v144, s[46:47]
	global_load_dwordx4 v[132:135], v144, s[46:47] offset:1024
	global_load_dwordx4 v[136:139], v144, s[46:47] offset:2048
	global_load_dwordx4 v[140:143], v144, s[46:47] offset:3072
	v_add_u32_e32 v144, 0x800000, v144
	v_pk_mul_f32 v[242:243], v[80:81], v[80:81]
	v_pk_mul_f32 v[244:245], v[84:85], v[84:85]
	v_pk_mul_f32 v[246:247], v[82:83], v[82:83]
	v_pk_mul_f32 v[248:249], v[86:87], v[86:87]
	v_add_f32_e32 v204, v245, v244
	v_add_f32_e32 v205, v243, v242
	v_add_f32_e32 v204, v248, v204
	v_add_f32_e32 v205, v246, v205
	v_add_f32_e32 v204, v249, v204
	v_add_f32_e32 v205, v247, v205
	v_pk_mul_f32 v[242:243], v[88:89], v[88:89]
	v_pk_mul_f32 v[244:245], v[92:93], v[92:93]
	v_pk_mul_f32 v[246:247], v[90:91], v[90:91]
	v_pk_mul_f32 v[248:249], v[94:95], v[94:95]
	v_add_f32_e32 v206, v243, v242
	v_add_f32_e32 v207, v245, v244
	v_add_f32_e32 v206, v246, v206
	v_add_f32_e32 v207, v248, v207
	v_add_f32_e32 v206, v247, v206
	v_add_f32_e32 v207, v249, v207
	v_add_f32_e32 v204, v205, v204
	v_add_f32_e32 v204, v204, v206
	v_add_f32_e32 v204, v204, v207
	ds_swizzle_b32 v205, v204 offset:swizzle(SWAP,1)
	s_waitcnt lgkmcnt(0)
	v_add_f32_e32 v204, v204, v205
	ds_swizzle_b32 v205, v204 offset:swizzle(SWAP,2)
	s_waitcnt lgkmcnt(0)
	v_add_f32_e32 v204, v204, v205
	ds_swizzle_b32 v205, v204 offset:swizzle(SWAP,4)
	s_waitcnt lgkmcnt(0)
	v_add_f32_e32 v204, v204, v205
	ds_swizzle_b32 v205, v204 offset:swizzle(SWAP,8)
	s_waitcnt lgkmcnt(0)
	v_add_f32_e32 v204, v204, v205
	ds_swizzle_b32 v205, v204 offset:swizzle(SWAP,16)
	s_waitcnt lgkmcnt(0)
	v_add_f32_e32 v204, v204, v205
	v_mov_b32_e32 v205, v204
	s_nop 1
	v_permlane32_swap_b32_e32 v204, v205
	v_add_f32_e32 v204, v204, v205
	v_mov_b32_e32 v205, 0x358637bd
	v_fmamk_f32 v204, v204, 0x3a800000, v205
	v_rsq_f32_e32 v204, v204
	s_nop 0
	s_waitcnt vmcnt(20)
; __device__ __forceinline__ unsigned pk2(float lo, float hi) { const g_f32x2 f = {lo, hi}; return __builtin_bit_cast(unsigned, __builtin_convertvector(f, g_bf16x2)); }
; __device__ __forceinline__ void p_norm(const float* hlat, const float* hctx, const float* g, const float* modl, int sh_off, int sc_off, bf16_t* A, int M,
;                                        const float* part, const float* cgate, float* hcout) {
;     ...
;         float ss = 0.f;
; #pragma unroll
;         for (int i = 0; i < 4; ++i) {
;             if (part != nullptr && row >= NLAT) {
;                 const size_t po = (size_t)(row - NLAT) * 1024 + i * 256 + lane * 4;
;                 const float4 p0 = *(const float4*)(part + po), p1 = *(const float4*)(part + (size_t)4096 * 1024 + po), cg = *(const float4*)(cgate + i * 256 + lane * 4);
;                 v[i].x += cg.x * (p0.x + p1.x); v[i].y += cg.y * (p0.y + p1.y); v[i].z += cg.z * (p0.z + p1.z); v[i].w += cg.w * (p0.w + p1.w);
;                 *(float4*)(hcout + po) = v[i];
;             }
;             ss += v[i].x * v[i].x + v[i].y * v[i].y + v[i].z * v[i].z + v[i].w * v[i].w; }
;         ss = wave_sum(ss);
;         const float rstd = rsqrtf(ss * (1.0f / 1024.0f) + EPS);
;         const float* mr = modl + (size_t)r * 6144;
; #pragma unroll
;         for (int i = 0; i < 4; ++i) {
;             const int k = i * 256 + lane * 4;
;             const float4 gg = *(const float4*)(g + k), scv = *(const float4*)(mr + sc_off + k), shv = *(const float4*)(mr + sh_off + k);
;             const float o0 = v[i].x * rstd * gg.x * (1.0f + scv.x) + shv.x, o1 = v[i].y * rstd * gg.y * (1.0f + scv.y) + shv.y;
;             const float o2 = v[i].z * rstd * gg.z * (1.0f + scv.z) + shv.z, o3 = v[i].w * rstd * gg.w * (1.0f + scv.w) + shv.w;
;             uint2 w; w.x = pk2(o0, o1); w.y = pk2(o2, o3);
;             *(uint2*)(A + (size_t)row * 1024 + k) = w;
	v_pk_mul_f32 v[80:81], v[80:81], v[204:205] op_sel_hi:[1,0]
	v_pk_mul_f32 v[82:83], v[82:83], v[204:205] op_sel_hi:[1,0]
	v_pk_mul_f32 v[80:81], v[156:157], v[80:81]
	v_pk_mul_f32 v[82:83], v[158:159], v[82:83]
	v_pk_add_f32 v[242:243], v[172:173], 1.0 op_sel_hi:[1,0]
	v_pk_add_f32 v[244:245], v[174:175], 1.0 op_sel_hi:[1,0]
	v_pk_fma_f32 v[80:81], v[242:243], v[80:81], v[188:189]
	v_pk_fma_f32 v[82:83], v[244:245], v[82:83], v[190:191]
	v_cvt_pk_bf16_f32 v80, v80, v81
	v_cvt_pk_bf16_f32 v81, v82, v83
	global_store_dwordx2 v146, v[80:81], s[66:67]
	v_pk_mul_f32 v[84:85], v[84:85], v[204:205] op_sel_hi:[1,0]
	v_pk_mul_f32 v[86:87], v[86:87], v[204:205] op_sel_hi:[1,0]
	v_pk_mul_f32 v[84:85], v[160:161], v[84:85]
	v_pk_mul_f32 v[86:87], v[162:163], v[86:87]
	v_pk_add_f32 v[242:243], v[176:177], 1.0 op_sel_hi:[1,0]
	v_pk_add_f32 v[244:245], v[178:179], 1.0 op_sel_hi:[1,0]
	v_pk_fma_f32 v[84:85], v[242:243], v[84:85], v[192:193]
	v_pk_fma_f32 v[86:87], v[244:245], v[86:87], v[194:195]
	v_cvt_pk_bf16_f32 v84, v84, v85
	v_cvt_pk_bf16_f32 v85, v86, v87
	global_store_dwordx2 v146, v[84:85], s[66:67] offset:512
	v_pk_mul_f32 v[88:89], v[88:89], v[204:205] op_sel_hi:[1,0]
	v_pk_mul_f32 v[90:91], v[90:91], v[204:205] op_sel_hi:[1,0]
	v_pk_mul_f32 v[88:89], v[164:165], v[88:89]
	v_pk_mul_f32 v[90:91], v[166:167], v[90:91]
	v_pk_add_f32 v[242:243], v[180:181], 1.0 op_sel_hi:[1,0]
	v_pk_add_f32 v[244:245], v[182:183], 1.0 op_sel_hi:[1,0]
	v_pk_fma_f32 v[88:89], v[242:243], v[88:89], v[196:197]
	v_pk_fma_f32 v[90:91], v[244:245], v[90:91], v[198:199]
	v_cvt_pk_bf16_f32 v88, v88, v89
	v_cvt_pk_bf16_f32 v89, v90, v91
	global_store_dwordx2 v146, v[88:89], s[66:67] offset:1024
	v_pk_mul_f32 v[92:93], v[92:93], v[204:205] op_sel_hi:[1,0]
	v_pk_mul_f32 v[94:95], v[94:95], v[204:205] op_sel_hi:[1,0]
	v_pk_mul_f32 v[92:93], v[168:169], v[92:93]
	v_pk_mul_f32 v[94:95], v[170:171], v[94:95]
	v_pk_add_f32 v[242:243], v[184:185], 1.0 op_sel_hi:[1,0]
	v_pk_add_f32 v[244:245], v[186:187], 1.0 op_sel_hi:[1,0]
	v_pk_fma_f32 v[92:93], v[242:243], v[92:93], v[200:201]
	v_pk_fma_f32 v[94:95], v[244:245], v[94:95], v[202:203]
	v_cvt_pk_bf16_f32 v92, v92, v93
	v_cvt_pk_bf16_f32 v93, v94, v95
	global_store_dwordx2 v146, v[92:93], s[66:67] offset:1536
	v_add_u32_e32 v146, 0x400000, v146
	global_load_dwordx4 v[172:175], v148, s[98:99]
	global_load_dwordx4 v[176:179], v148, s[98:99] offset:1024
	global_load_dwordx4 v[180:183], v148, s[98:99] offset:2048
	global_load_dwordx4 v[184:187], v148, s[98:99] offset:3072
	global_load_dwordx4 v[188:191], v148, s[50:51]
	global_load_dwordx4 v[192:195], v148, s[50:51] offset:1024
	global_load_dwordx4 v[196:199], v148, s[50:51] offset:2048
	global_load_dwordx4 v[200:203], v148, s[50:51] offset:3072
	v_add_u32_e32 v148, 0x6000, v148
	global_load_dwordx4 v[80:83], v144, s[46:47]
	global_load_dwordx4 v[84:87], v144, s[46:47] offset:1024
	global_load_dwordx4 v[88:91], v144, s[46:47] offset:2048
	global_load_dwordx4 v[92:95], v144, s[46:47] offset:3072
	v_add_u32_e32 v144, 0x800000, v144
	v_pk_mul_f32 v[242:243], v[96:97], v[96:97]
	v_pk_mul_f32 v[244:245], v[100:101], v[100:101]
	v_pk_mul_f32 v[246:247], v[98:99], v[98:99]
	v_pk_mul_f32 v[248:249], v[102:103], v[102:103]
	v_add_f32_e32 v204, v245, v244
	v_add_f32_e32 v205, v243, v242
	v_add_f32_e32 v204, v248, v204
	v_add_f32_e32 v205, v246, v205
	v_add_f32_e32 v204, v249, v204
	v_add_f32_e32 v205, v247, v205
	v_pk_mul_f32 v[242:243], v[104:105], v[104:105]
	v_pk_mul_f32 v[244:245], v[108:109], v[108:109]
	v_pk_mul_f32 v[246:247], v[106:107], v[106:107]
	v_pk_mul_f32 v[248:249], v[110:111], v[110:111]
	v_add_f32_e32 v206, v243, v242
	v_add_f32_e32 v207, v245, v244
	v_add_f32_e32 v206, v246, v206
	v_add_f32_e32 v207, v248, v207
	v_add_f32_e32 v206, v247, v206
	v_add_f32_e32 v207, v249, v207
	v_add_f32_e32 v204, v205, v204
	v_add_f32_e32 v204, v204, v206
	v_add_f32_e32 v204, v204, v207
	ds_swizzle_b32 v205, v204 offset:swizzle(SWAP,1)
	s_waitcnt lgkmcnt(0)
	v_add_f32_e32 v204, v204, v205
	ds_swizzle_b32 v205, v204 offset:swizzle(SWAP,2)
	s_waitcnt lgkmcnt(0)
	v_add_f32_e32 v204, v204, v205
	ds_swizzle_b32 v205, v204 offset:swizzle(SWAP,4)
	s_waitcnt lgkmcnt(0)
	v_add_f32_e32 v204, v204, v205
	ds_swizzle_b32 v205, v204 offset:swizzle(SWAP,8)
	s_waitcnt lgkmcnt(0)
	v_add_f32_e32 v204, v204, v205
	ds_swizzle_b32 v205, v204 offset:swizzle(SWAP,16)
	s_waitcnt lgkmcnt(0)
	v_add_f32_e32 v204, v204, v205
	v_mov_b32_e32 v205, v204
	s_nop 1
	v_permlane32_swap_b32_e32 v204, v205
	v_add_f32_e32 v204, v204, v205
	v_mov_b32_e32 v205, 0x358637bd
	v_fmamk_f32 v204, v204, 0x3a800000, v205
	v_rsq_f32_e32 v204, v204
	s_nop 0
	s_waitcnt vmcnt(20)
; __device__ __forceinline__ unsigned pk2(float lo, float hi) { const g_f32x2 f = {lo, hi}; return __builtin_bit_cast(unsigned, __builtin_convertvector(f, g_bf16x2)); }
; __device__ __forceinline__ void p_norm(const float* hlat, const float* hctx, const float* g, const float* modl, int sh_off, int sc_off, bf16_t* A, int M,
;                                        const float* part, const float* cgate, float* hcout) {
;     ...
;         float ss = 0.f;
; #pragma unroll
;         for (int i = 0; i < 4; ++i) {
;             if (part != nullptr && row >= NLAT) {
;                 const size_t po = (size_t)(row - NLAT) * 1024 + i * 256 + lane * 4;
;                 const float4 p0 = *(const float4*)(part + po), p1 = *(const float4*)(part + (size_t)4096 * 1024 + po), cg = *(const float4*)(cgate + i * 256 + lane * 4);
;                 v[i].x += cg.x * (p0.x + p1.x); v[i].y += cg.y * (p0.y + p1.y); v[i].z += cg.z * (p0.z + p1.z); v[i].w += cg.w * (p0.w + p1.w);
;                 *(float4*)(hcout + po) = v[i];
;             }
;             ss += v[i].x * v[i].x + v[i].y * v[i].y + v[i].z * v[i].z + v[i].w * v[i].w; }
;         ss = wave_sum(ss);
;         const float rstd = rsqrtf(ss * (1.0f / 1024.0f) + EPS);
;         const float* mr = modl + (size_t)r * 6144;
; #pragma unroll
;         for (int i = 0; i < 4; ++i) {
;             const int k = i * 256 + lane * 4;
;             const float4 gg = *(const float4*)(g + k), scv = *(const float4*)(mr + sc_off + k), shv = *(const float4*)(mr + sh_off + k);
;             const float o0 = v[i].x * rstd * gg.x * (1.0f + scv.x) + shv.x, o1 = v[i].y * rstd * gg.y * (1.0f + scv.y) + shv.y;
;             const float o2 = v[i].z * rstd * gg.z * (1.0f + scv.z) + shv.z, o3 = v[i].w * rstd * gg.w * (1.0f + scv.w) + shv.w;
;             uint2 w; w.x = pk2(o0, o1); w.y = pk2(o2, o3);
;             *(uint2*)(A + (size_t)row * 1024 + k) = w;
	v_pk_mul_f32 v[96:97], v[96:97], v[204:205] op_sel_hi:[1,0]
	v_pk_mul_f32 v[98:99], v[98:99], v[204:205] op_sel_hi:[1,0]
	v_pk_mul_f32 v[96:97], v[156:157], v[96:97]
	v_pk_mul_f32 v[98:99], v[158:159], v[98:99]
	v_pk_add_f32 v[242:243], v[34:35], 1.0 op_sel_hi:[1,0]
	v_pk_add_f32 v[244:245], v[36:37], 1.0 op_sel_hi:[1,0]
	v_pk_fma_f32 v[96:97], v[242:243], v[96:97], v[224:225]
	v_pk_fma_f32 v[98:99], v[244:245], v[98:99], v[226:227]
	v_cvt_pk_bf16_f32 v96, v96, v97
	v_cvt_pk_bf16_f32 v97, v98, v99
	global_store_dwordx2 v146, v[96:97], s[66:67]
	v_pk_mul_f32 v[100:101], v[100:101], v[204:205] op_sel_hi:[1,0]
	v_pk_mul_f32 v[102:103], v[102:103], v[204:205] op_sel_hi:[1,0]
	v_pk_mul_f32 v[100:101], v[160:161], v[100:101]
	v_pk_mul_f32 v[102:103], v[162:163], v[102:103]
	v_pk_add_f32 v[242:243], v[38:39], 1.0 op_sel_hi:[1,0]
	v_pk_add_f32 v[244:245], v[40:41], 1.0 op_sel_hi:[1,0]
	v_pk_fma_f32 v[100:101], v[242:243], v[100:101], v[228:229]
	v_pk_fma_f32 v[102:103], v[244:245], v[102:103], v[230:231]
	v_cvt_pk_bf16_f32 v100, v100, v101
	v_cvt_pk_bf16_f32 v101, v102, v103
	global_store_dwordx2 v146, v[100:101], s[66:67] offset:512
	v_pk_mul_f32 v[104:105], v[104:105], v[204:205] op_sel_hi:[1,0]
	v_pk_mul_f32 v[106:107], v[106:107], v[204:205] op_sel_hi:[1,0]
	v_pk_mul_f32 v[104:105], v[164:165], v[104:105]
	v_pk_mul_f32 v[106:107], v[166:167], v[106:107]
	v_pk_add_f32 v[242:243], v[42:43], 1.0 op_sel_hi:[1,0]
	v_pk_add_f32 v[244:245], v[44:45], 1.0 op_sel_hi:[1,0]
	v_pk_fma_f32 v[104:105], v[242:243], v[104:105], v[232:233]
	v_pk_fma_f32 v[106:107], v[244:245], v[106:107], v[234:235]
	v_cvt_pk_bf16_f32 v104, v104, v105
	v_cvt_pk_bf16_f32 v105, v106, v107
	global_store_dwordx2 v146, v[104:105], s[66:67] offset:1024
	v_pk_mul_f32 v[108:109], v[108:109], v[204:205] op_sel_hi:[1,0]
	v_pk_mul_f32 v[110:111], v[110:111], v[204:205] op_sel_hi:[1,0]
	v_pk_mul_f32 v[108:109], v[168:169], v[108:109]
	v_pk_mul_f32 v[110:111], v[170:171], v[110:111]
	v_pk_add_f32 v[242:243], v[46:47], 1.0 op_sel_hi:[1,0]
	v_pk_add_f32 v[244:245], v[48:49], 1.0 op_sel_hi:[1,0]
	v_pk_fma_f32 v[108:109], v[242:243], v[108:109], v[236:237]
	v_pk_fma_f32 v[110:111], v[244:245], v[110:111], v[238:239]
	v_cvt_pk_bf16_f32 v108, v108, v109
	v_cvt_pk_bf16_f32 v109, v110, v111
	global_store_dwordx2 v146, v[108:109], s[66:67] offset:1536
	v_add_u32_e32 v146, 0x400000, v146
	global_load_dwordx4 v[34:37], v148, s[98:99]
	global_load_dwordx4 v[38:41], v148, s[98:99] offset:1024
	global_load_dwordx4 v[42:45], v148, s[98:99] offset:2048
	global_load_dwordx4 v[46:49], v148, s[98:99] offset:3072
	global_load_dwordx4 v[224:227], v148, s[50:51]
	global_load_dwordx4 v[228:231], v148, s[50:51] offset:1024
	global_load_dwordx4 v[232:235], v148, s[50:51] offset:2048
	global_load_dwordx4 v[236:239], v148, s[50:51] offset:3072
	v_add_u32_e32 v148, 0x6000, v148
	global_load_dwordx4 v[96:99], v144, s[46:47]
	global_load_dwordx4 v[100:103], v144, s[46:47] offset:1024
	global_load_dwordx4 v[104:107], v144, s[46:47] offset:2048
	global_load_dwordx4 v[108:111], v144, s[46:47] offset:3072
	v_add_u32_e32 v144, 0x800000, v144
	v_pk_mul_f32 v[242:243], v[112:113], v[112:113]
	v_pk_mul_f32 v[244:245], v[116:117], v[116:117]
	v_pk_mul_f32 v[246:247], v[114:115], v[114:115]
	v_pk_mul_f32 v[248:249], v[118:119], v[118:119]
	v_add_f32_e32 v204, v245, v244
	v_add_f32_e32 v205, v243, v242
	v_add_f32_e32 v204, v248, v204
	v_add_f32_e32 v205, v246, v205
	v_add_f32_e32 v204, v249, v204
	v_add_f32_e32 v205, v247, v205
	v_pk_mul_f32 v[242:243], v[120:121], v[120:121]
	v_pk_mul_f32 v[244:245], v[124:125], v[124:125]
	v_pk_mul_f32 v[246:247], v[122:123], v[122:123]
	v_pk_mul_f32 v[248:249], v[126:127], v[126:127]
	v_add_f32_e32 v206, v243, v242
	v_add_f32_e32 v207, v245, v244
	v_add_f32_e32 v206, v246, v206
	v_add_f32_e32 v207, v248, v207
	v_add_f32_e32 v206, v247, v206
	v_add_f32_e32 v207, v249, v207
	v_add_f32_e32 v204, v205, v204
	v_add_f32_e32 v204, v204, v206
	v_add_f32_e32 v204, v204, v207
	ds_swizzle_b32 v205, v204 offset:swizzle(SWAP,1)
	s_waitcnt lgkmcnt(0)
	v_add_f32_e32 v204, v204, v205
	ds_swizzle_b32 v205, v204 offset:swizzle(SWAP,2)
	s_waitcnt lgkmcnt(0)
	v_add_f32_e32 v204, v204, v205
	ds_swizzle_b32 v205, v204 offset:swizzle(SWAP,4)
	s_waitcnt lgkmcnt(0)
	v_add_f32_e32 v204, v204, v205
	ds_swizzle_b32 v205, v204 offset:swizzle(SWAP,8)
	s_waitcnt lgkmcnt(0)
	v_add_f32_e32 v204, v204, v205
	ds_swizzle_b32 v205, v204 offset:swizzle(SWAP,16)
	s_waitcnt lgkmcnt(0)
	v_add_f32_e32 v204, v204, v205
	v_mov_b32_e32 v205, v204
	s_nop 1
	v_permlane32_swap_b32_e32 v204, v205
	v_add_f32_e32 v204, v204, v205
	v_mov_b32_e32 v205, 0x358637bd
	v_fmamk_f32 v204, v204, 0x3a800000, v205
	v_rsq_f32_e32 v204, v204
	s_nop 0
	s_waitcnt vmcnt(20)
; __device__ __forceinline__ unsigned pk2(float lo, float hi) { const g_f32x2 f = {lo, hi}; return __builtin_bit_cast(unsigned, __builtin_convertvector(f, g_bf16x2)); }
; __device__ __forceinline__ void p_norm(const float* hlat, const float* hctx, const float* g, const float* modl, int sh_off, int sc_off, bf16_t* A, int M,
;                                        const float* part, const float* cgate, float* hcout) {
;     ...
;         float ss = 0.f;
; #pragma unroll
;         for (int i = 0; i < 4; ++i) {
;             if (part != nullptr && row >= NLAT) {
;                 const size_t po = (size_t)(row - NLAT) * 1024 + i * 256 + lane * 4;
;                 const float4 p0 = *(const float4*)(part + po), p1 = *(const float4*)(part + (size_t)4096 * 1024 + po), cg = *(const float4*)(cgate + i * 256 + lane * 4);
;                 v[i].x += cg.x * (p0.x + p1.x); v[i].y += cg.y * (p0.y + p1.y); v[i].z += cg.z * (p0.z + p1.z); v[i].w += cg.w * (p0.w + p1.w);
;                 *(float4*)(hcout + po) = v[i];
;             }
;             ss += v[i].x * v[i].x + v[i].y * v[i].y + v[i].z * v[i].z + v[i].w * v[i].w; }
;         ss = wave_sum(ss);
;         const float rstd = rsqrtf(ss * (1.0f / 1024.0f) + EPS);
;         const float* mr = modl + (size_t)r * 6144;
; #pragma unroll
;         for (int i = 0; i < 4; ++i) {
;             const int k = i * 256 + lane * 4;
;             const float4 gg = *(const float4*)(g + k), scv = *(const float4*)(mr + sc_off + k), shv = *(const float4*)(mr + sh_off + k);
;             const float o0 = v[i].x * rstd * gg.x * (1.0f + scv.x) + shv.x, o1 = v[i].y * rstd * gg.y * (1.0f + scv.y) + shv.y;
;             const float o2 = v[i].z * rstd * gg.z * (1.0f + scv.z) + shv.z, o3 = v[i].w * rstd * gg.w * (1.0f + scv.w) + shv.w;
;             uint2 w; w.x = pk2(o0, o1); w.y = pk2(o2, o3);
;             *(uint2*)(A + (size_t)row * 1024 + k) = w;
	v_pk_mul_f32 v[112:113], v[112:113], v[204:205] op_sel_hi:[1,0]
	v_pk_mul_f32 v[114:115], v[114:115], v[204:205] op_sel_hi:[1,0]
	v_pk_mul_f32 v[112:113], v[156:157], v[112:113]
	v_pk_mul_f32 v[114:115], v[158:159], v[114:115]
	v_pk_add_f32 v[242:243], v[172:173], 1.0 op_sel_hi:[1,0]
	v_pk_add_f32 v[244:245], v[174:175], 1.0 op_sel_hi:[1,0]
	v_pk_fma_f32 v[112:113], v[242:243], v[112:113], v[188:189]
	v_pk_fma_f32 v[114:115], v[244:245], v[114:115], v[190:191]
	v_cvt_pk_bf16_f32 v112, v112, v113
	v_cvt_pk_bf16_f32 v113, v114, v115
	global_store_dwordx2 v146, v[112:113], s[66:67]
	v_pk_mul_f32 v[116:117], v[116:117], v[204:205] op_sel_hi:[1,0]
	v_pk_mul_f32 v[118:119], v[118:119], v[204:205] op_sel_hi:[1,0]
	v_pk_mul_f32 v[116:117], v[160:161], v[116:117]
	v_pk_mul_f32 v[118:119], v[162:163], v[118:119]
	v_pk_add_f32 v[242:243], v[176:177], 1.0 op_sel_hi:[1,0]
	v_pk_add_f32 v[244:245], v[178:179], 1.0 op_sel_hi:[1,0]
	v_pk_fma_f32 v[116:117], v[242:243], v[116:117], v[192:193]
	v_pk_fma_f32 v[118:119], v[244:245], v[118:119], v[194:195]
	v_cvt_pk_bf16_f32 v116, v116, v117
	v_cvt_pk_bf16_f32 v117, v118, v119
	global_store_dwordx2 v146, v[116:117], s[66:67] offset:512
	v_pk_mul_f32 v[120:121], v[120:121], v[204:205] op_sel_hi:[1,0]
	v_pk_mul_f32 v[122:123], v[122:123], v[204:205] op_sel_hi:[1,0]
	v_pk_mul_f32 v[120:121], v[164:165], v[120:121]
	v_pk_mul_f32 v[122:123], v[166:167], v[122:123]
	v_pk_add_f32 v[242:243], v[180:181], 1.0 op_sel_hi:[1,0]
	v_pk_add_f32 v[244:245], v[182:183], 1.0 op_sel_hi:[1,0]
	v_pk_fma_f32 v[120:121], v[242:243], v[120:121], v[196:197]
	v_pk_fma_f32 v[122:123], v[244:245], v[122:123], v[198:199]
	v_cvt_pk_bf16_f32 v120, v120, v121
	v_cvt_pk_bf16_f32 v121, v122, v123
	global_store_dwordx2 v146, v[120:121], s[66:67] offset:1024
	v_pk_mul_f32 v[124:125], v[124:125], v[204:205] op_sel_hi:[1,0]
	v_pk_mul_f32 v[126:127], v[126:127], v[204:205] op_sel_hi:[1,0]
	v_pk_mul_f32 v[124:125], v[168:169], v[124:125]
	v_pk_mul_f32 v[126:127], v[170:171], v[126:127]
	v_pk_add_f32 v[242:243], v[184:185], 1.0 op_sel_hi:[1,0]
	v_pk_add_f32 v[244:245], v[186:187], 1.0 op_sel_hi:[1,0]
	v_pk_fma_f32 v[124:125], v[242:243], v[124:125], v[200:201]
	v_pk_fma_f32 v[126:127], v[244:245], v[126:127], v[202:203]
	v_cvt_pk_bf16_f32 v124, v124, v125
	v_cvt_pk_bf16_f32 v125, v126, v127
	global_store_dwordx2 v146, v[124:125], s[66:67] offset:1536
	v_add_u32_e32 v146, 0x400000, v146
	global_load_dwordx4 v[172:175], v148, s[98:99]
	global_load_dwordx4 v[176:179], v148, s[98:99] offset:1024
	global_load_dwordx4 v[180:183], v148, s[98:99] offset:2048
	global_load_dwordx4 v[184:187], v148, s[98:99] offset:3072
	global_load_dwordx4 v[188:191], v148, s[50:51]
	global_load_dwordx4 v[192:195], v148, s[50:51] offset:1024
	global_load_dwordx4 v[196:199], v148, s[50:51] offset:2048
	global_load_dwordx4 v[200:203], v148, s[50:51] offset:3072
	v_add_u32_e32 v148, 0x6000, v148
	global_load_dwordx4 v[112:115], v144, s[46:47]
	global_load_dwordx4 v[116:119], v144, s[46:47] offset:1024
	global_load_dwordx4 v[120:123], v144, s[46:47] offset:2048
	global_load_dwordx4 v[124:127], v144, s[46:47] offset:3072
	v_add_u32_e32 v144, 0x800000, v144
	v_pk_mul_f32 v[242:243], v[128:129], v[128:129]
	v_pk_mul_f32 v[244:245], v[132:133], v[132:133]
	v_pk_mul_f32 v[246:247], v[130:131], v[130:131]
	v_pk_mul_f32 v[248:249], v[134:135], v[134:135]
	v_add_f32_e32 v204, v245, v244
	v_add_f32_e32 v205, v243, v242
	v_add_f32_e32 v204, v248, v204
	v_add_f32_e32 v205, v246, v205
	v_add_f32_e32 v204, v249, v204
	v_add_f32_e32 v205, v247, v205
	v_pk_mul_f32 v[242:243], v[136:137], v[136:137]
	v_pk_mul_f32 v[244:245], v[140:141], v[140:141]
	v_pk_mul_f32 v[246:247], v[138:139], v[138:139]
	v_pk_mul_f32 v[248:249], v[142:143], v[142:143]
	v_add_f32_e32 v206, v243, v242
	v_add_f32_e32 v207, v245, v244
	v_add_f32_e32 v206, v246, v206
	v_add_f32_e32 v207, v248, v207
	v_add_f32_e32 v206, v247, v206
	v_add_f32_e32 v207, v249, v207
	v_add_f32_e32 v204, v205, v204
	v_add_f32_e32 v204, v204, v206
	v_add_f32_e32 v204, v204, v207
	ds_swizzle_b32 v205, v204 offset:swizzle(SWAP,1)
	s_waitcnt lgkmcnt(0)
	v_add_f32_e32 v204, v204, v205
	ds_swizzle_b32 v205, v204 offset:swizzle(SWAP,2)
	s_waitcnt lgkmcnt(0)
	v_add_f32_e32 v204, v204, v205
	ds_swizzle_b32 v205, v204 offset:swizzle(SWAP,4)
	s_waitcnt lgkmcnt(0)
	v_add_f32_e32 v204, v204, v205
	ds_swizzle_b32 v205, v204 offset:swizzle(SWAP,8)
	s_waitcnt lgkmcnt(0)
	v_add_f32_e32 v204, v204, v205
	ds_swizzle_b32 v205, v204 offset:swizzle(SWAP,16)
	s_waitcnt lgkmcnt(0)
	v_add_f32_e32 v204, v204, v205
	v_mov_b32_e32 v205, v204
	s_nop 1
	v_permlane32_swap_b32_e32 v204, v205
	v_add_f32_e32 v204, v204, v205
	v_mov_b32_e32 v205, 0x358637bd
	v_fmamk_f32 v204, v204, 0x3a800000, v205
	v_rsq_f32_e32 v204, v204
	s_nop 0
	s_waitcnt vmcnt(20)
; __device__ __forceinline__ unsigned pk2(float lo, float hi) { const g_f32x2 f = {lo, hi}; return __builtin_bit_cast(unsigned, __builtin_convertvector(f, g_bf16x2)); }
; __device__ __forceinline__ void p_norm(const float* hlat, const float* hctx, const float* g, const float* modl, int sh_off, int sc_off, bf16_t* A, int M,
;                                        const float* part, const float* cgate, float* hcout) {
;     ...
;         float ss = 0.f;
; #pragma unroll
;         for (int i = 0; i < 4; ++i) {
;             if (part != nullptr && row >= NLAT) {
;                 const size_t po = (size_t)(row - NLAT) * 1024 + i * 256 + lane * 4;
;                 const float4 p0 = *(const float4*)(part + po), p1 = *(const float4*)(part + (size_t)4096 * 1024 + po), cg = *(const float4*)(cgate + i * 256 + lane * 4);
;                 v[i].x += cg.x * (p0.x + p1.x); v[i].y += cg.y * (p0.y + p1.y); v[i].z += cg.z * (p0.z + p1.z); v[i].w += cg.w * (p0.w + p1.w);
;                 *(float4*)(hcout + po) = v[i];
;             }
;             ss += v[i].x * v[i].x + v[i].y * v[i].y + v[i].z * v[i].z + v[i].w * v[i].w; }
;         ss = wave_sum(ss);
;         const float rstd = rsqrtf(ss * (1.0f / 1024.0f) + EPS);
;         const float* mr = modl + (size_t)r * 6144;
; #pragma unroll
;         for (int i = 0; i < 4; ++i) {
;             const int k = i * 256 + lane * 4;
;             const float4 gg = *(const float4*)(g + k), scv = *(const float4*)(mr + sc_off + k), shv = *(const float4*)(mr + sh_off + k);
;             const float o0 = v[i].x * rstd * gg.x * (1.0f + scv.x) + shv.x, o1 = v[i].y * rstd * gg.y * (1.0f + scv.y) + shv.y;
;             const float o2 = v[i].z * rstd * gg.z * (1.0f + scv.z) + shv.z, o3 = v[i].w * rstd * gg.w * (1.0f + scv.w) + shv.w;
;             uint2 w; w.x = pk2(o0, o1); w.y = pk2(o2, o3);
;             *(uint2*)(A + (size_t)row * 1024 + k) = w;
	v_pk_mul_f32 v[128:129], v[128:129], v[204:205] op_sel_hi:[1,0]
	v_pk_mul_f32 v[130:131], v[130:131], v[204:205] op_sel_hi:[1,0]
	v_pk_mul_f32 v[128:129], v[156:157], v[128:129]
	v_pk_mul_f32 v[130:131], v[158:159], v[130:131]
	v_pk_add_f32 v[242:243], v[34:35], 1.0 op_sel_hi:[1,0]
	v_pk_add_f32 v[244:245], v[36:37], 1.0 op_sel_hi:[1,0]
	v_pk_fma_f32 v[128:129], v[242:243], v[128:129], v[224:225]
	v_pk_fma_f32 v[130:131], v[244:245], v[130:131], v[226:227]
	v_cvt_pk_bf16_f32 v128, v128, v129
	v_cvt_pk_bf16_f32 v129, v130, v131
	global_store_dwordx2 v146, v[128:129], s[66:67]
	v_pk_mul_f32 v[132:133], v[132:133], v[204:205] op_sel_hi:[1,0]
	v_pk_mul_f32 v[134:135], v[134:135], v[204:205] op_sel_hi:[1,0]
	v_pk_mul_f32 v[132:133], v[160:161], v[132:133]
	v_pk_mul_f32 v[134:135], v[162:163], v[134:135]
	v_pk_add_f32 v[242:243], v[38:39], 1.0 op_sel_hi:[1,0]
	v_pk_add_f32 v[244:245], v[40:41], 1.0 op_sel_hi:[1,0]
	v_pk_fma_f32 v[132:133], v[242:243], v[132:133], v[228:229]
	v_pk_fma_f32 v[134:135], v[244:245], v[134:135], v[230:231]
	v_cvt_pk_bf16_f32 v132, v132, v133
	v_cvt_pk_bf16_f32 v133, v134, v135
	global_store_dwordx2 v146, v[132:133], s[66:67] offset:512
	v_pk_mul_f32 v[136:137], v[136:137], v[204:205] op_sel_hi:[1,0]
	v_pk_mul_f32 v[138:139], v[138:139], v[204:205] op_sel_hi:[1,0]
	v_pk_mul_f32 v[136:137], v[164:165], v[136:137]
	v_pk_mul_f32 v[138:139], v[166:167], v[138:139]
	v_pk_add_f32 v[242:243], v[42:43], 1.0 op_sel_hi:[1,0]
	v_pk_add_f32 v[244:245], v[44:45], 1.0 op_sel_hi:[1,0]
	v_pk_fma_f32 v[136:137], v[242:243], v[136:137], v[232:233]
	v_pk_fma_f32 v[138:139], v[244:245], v[138:139], v[234:235]
	v_cvt_pk_bf16_f32 v136, v136, v137
	v_cvt_pk_bf16_f32 v137, v138, v139
	global_store_dwordx2 v146, v[136:137], s[66:67] offset:1024
	v_pk_mul_f32 v[140:141], v[140:141], v[204:205] op_sel_hi:[1,0]
	v_pk_mul_f32 v[142:143], v[142:143], v[204:205] op_sel_hi:[1,0]
	v_pk_mul_f32 v[140:141], v[168:169], v[140:141]
	v_pk_mul_f32 v[142:143], v[170:171], v[142:143]
	v_pk_add_f32 v[242:243], v[46:47], 1.0 op_sel_hi:[1,0]
	v_pk_add_f32 v[244:245], v[48:49], 1.0 op_sel_hi:[1,0]
	v_pk_fma_f32 v[140:141], v[242:243], v[140:141], v[236:237]
	v_pk_fma_f32 v[142:143], v[244:245], v[142:143], v[238:239]
	v_cvt_pk_bf16_f32 v140, v140, v141
	v_cvt_pk_bf16_f32 v141, v142, v143
	global_store_dwordx2 v146, v[140:141], s[66:67] offset:1536
	v_add_u32_e32 v146, 0x400000, v146
	global_load_dwordx4 v[34:37], v148, s[98:99]
	global_load_dwordx4 v[38:41], v148, s[98:99] offset:1024
	global_load_dwordx4 v[42:45], v148, s[98:99] offset:2048
	global_load_dwordx4 v[46:49], v148, s[98:99] offset:3072
	global_load_dwordx4 v[224:227], v148, s[50:51]
	global_load_dwordx4 v[228:231], v148, s[50:51] offset:1024
	global_load_dwordx4 v[232:235], v148, s[50:51] offset:2048
	global_load_dwordx4 v[236:239], v148, s[50:51] offset:3072
	v_add_u32_e32 v148, 0x6000, v148
	global_load_dwordx4 v[128:131], v144, s[46:47]
	global_load_dwordx4 v[132:135], v144, s[46:47] offset:1024
	global_load_dwordx4 v[136:139], v144, s[46:47] offset:2048
	global_load_dwordx4 v[140:143], v144, s[46:47] offset:3072
	v_add_u32_e32 v144, 0x800000, v144
	v_pk_mul_f32 v[242:243], v[80:81], v[80:81]
	v_pk_mul_f32 v[244:245], v[84:85], v[84:85]
	v_pk_mul_f32 v[246:247], v[82:83], v[82:83]
	v_pk_mul_f32 v[248:249], v[86:87], v[86:87]
	v_add_f32_e32 v204, v245, v244
	v_add_f32_e32 v205, v243, v242
	v_add_f32_e32 v204, v248, v204
	v_add_f32_e32 v205, v246, v205
	v_add_f32_e32 v204, v249, v204
	v_add_f32_e32 v205, v247, v205
	v_pk_mul_f32 v[242:243], v[88:89], v[88:89]
	v_pk_mul_f32 v[244:245], v[92:93], v[92:93]
	v_pk_mul_f32 v[246:247], v[90:91], v[90:91]
	v_pk_mul_f32 v[248:249], v[94:95], v[94:95]
	v_add_f32_e32 v206, v243, v242
	v_add_f32_e32 v207, v245, v244
	v_add_f32_e32 v206, v246, v206
	v_add_f32_e32 v207, v248, v207
	v_add_f32_e32 v206, v247, v206
	v_add_f32_e32 v207, v249, v207
	v_add_f32_e32 v204, v205, v204
	v_add_f32_e32 v204, v204, v206
	v_add_f32_e32 v204, v204, v207
	ds_swizzle_b32 v205, v204 offset:swizzle(SWAP,1)
	s_waitcnt lgkmcnt(0)
	v_add_f32_e32 v204, v204, v205
	ds_swizzle_b32 v205, v204 offset:swizzle(SWAP,2)
	s_waitcnt lgkmcnt(0)
	v_add_f32_e32 v204, v204, v205
	ds_swizzle_b32 v205, v204 offset:swizzle(SWAP,4)
	s_waitcnt lgkmcnt(0)
	v_add_f32_e32 v204, v204, v205
	ds_swizzle_b32 v205, v204 offset:swizzle(SWAP,8)
	s_waitcnt lgkmcnt(0)
	v_add_f32_e32 v204, v204, v205
	ds_swizzle_b32 v205, v204 offset:swizzle(SWAP,16)
	s_waitcnt lgkmcnt(0)
	v_add_f32_e32 v204, v204, v205
	v_mov_b32_e32 v205, v204
	s_nop 1
	v_permlane32_swap_b32_e32 v204, v205
	v_add_f32_e32 v204, v204, v205
	v_mov_b32_e32 v205, 0x358637bd
	v_fmamk_f32 v204, v204, 0x3a800000, v205
	v_rsq_f32_e32 v204, v204
	s_nop 0
	s_waitcnt vmcnt(20)
; __device__ __forceinline__ unsigned pk2(float lo, float hi) { const g_f32x2 f = {lo, hi}; return __builtin_bit_cast(unsigned, __builtin_convertvector(f, g_bf16x2)); }
; __device__ __forceinline__ void p_norm(const float* hlat, const float* hctx, const float* g, const float* modl, int sh_off, int sc_off, bf16_t* A, int M,
;                                        const float* part, const float* cgate, float* hcout) {
;     ...
;         float ss = 0.f;
; #pragma unroll
;         for (int i = 0; i < 4; ++i) {
;             if (part != nullptr && row >= NLAT) {
;                 const size_t po = (size_t)(row - NLAT) * 1024 + i * 256 + lane * 4;
;                 const float4 p0 = *(const float4*)(part + po), p1 = *(const float4*)(part + (size_t)4096 * 1024 + po), cg = *(const float4*)(cgate + i * 256 + lane * 4);
;                 v[i].x += cg.x * (p0.x + p1.x); v[i].y += cg.y * (p0.y + p1.y); v[i].z += cg.z * (p0.z + p1.z); v[i].w += cg.w * (p0.w + p1.w);
;                 *(float4*)(hcout + po) = v[i];
;             }
;             ss += v[i].x * v[i].x + v[i].y * v[i].y + v[i].z * v[i].z + v[i].w * v[i].w; }
;         ss = wave_sum(ss);
;         const float rstd = rsqrtf(ss * (1.0f / 1024.0f) + EPS);
;         const float* mr = modl + (size_t)r * 6144;
; #pragma unroll
;         for (int i = 0; i < 4; ++i) {
;             const int k = i * 256 + lane * 4;
;             const float4 gg = *(const float4*)(g + k), scv = *(const float4*)(mr + sc_off + k), shv = *(const float4*)(mr + sh_off + k);
;             const float o0 = v[i].x * rstd * gg.x * (1.0f + scv.x) + shv.x, o1 = v[i].y * rstd * gg.y * (1.0f + scv.y) + shv.y;
;             const float o2 = v[i].z * rstd * gg.z * (1.0f + scv.z) + shv.z, o3 = v[i].w * rstd * gg.w * (1.0f + scv.w) + shv.w;
;             uint2 w; w.x = pk2(o0, o1); w.y = pk2(o2, o3);
;             *(uint2*)(A + (size_t)row * 1024 + k) = w;
	v_pk_mul_f32 v[80:81], v[80:81], v[204:205] op_sel_hi:[1,0]
	v_pk_mul_f32 v[82:83], v[82:83], v[204:205] op_sel_hi:[1,0]
	v_pk_mul_f32 v[80:81], v[156:157], v[80:81]
	v_pk_mul_f32 v[82:83], v[158:159], v[82:83]
	v_pk_add_f32 v[242:243], v[172:173], 1.0 op_sel_hi:[1,0]
	v_pk_add_f32 v[244:245], v[174:175], 1.0 op_sel_hi:[1,0]
	v_pk_fma_f32 v[80:81], v[242:243], v[80:81], v[188:189]
	v_pk_fma_f32 v[82:83], v[244:245], v[82:83], v[190:191]
	v_cvt_pk_bf16_f32 v80, v80, v81
	v_cvt_pk_bf16_f32 v81, v82, v83
	global_store_dwordx2 v146, v[80:81], s[66:67]
	v_pk_mul_f32 v[84:85], v[84:85], v[204:205] op_sel_hi:[1,0]
	v_pk_mul_f32 v[86:87], v[86:87], v[204:205] op_sel_hi:[1,0]
	v_pk_mul_f32 v[84:85], v[160:161], v[84:85]
	v_pk_mul_f32 v[86:87], v[162:163], v[86:87]
	v_pk_add_f32 v[242:243], v[176:177], 1.0 op_sel_hi:[1,0]
	v_pk_add_f32 v[244:245], v[178:179], 1.0 op_sel_hi:[1,0]
	v_pk_fma_f32 v[84:85], v[242:243], v[84:85], v[192:193]
	v_pk_fma_f32 v[86:87], v[244:245], v[86:87], v[194:195]
	v_cvt_pk_bf16_f32 v84, v84, v85
	v_cvt_pk_bf16_f32 v85, v86, v87
	global_store_dwordx2 v146, v[84:85], s[66:67] offset:512
	v_pk_mul_f32 v[88:89], v[88:89], v[204:205] op_sel_hi:[1,0]
	v_pk_mul_f32 v[90:91], v[90:91], v[204:205] op_sel_hi:[1,0]
	v_pk_mul_f32 v[88:89], v[164:165], v[88:89]
	v_pk_mul_f32 v[90:91], v[166:167], v[90:91]
	v_pk_add_f32 v[242:243], v[180:181], 1.0 op_sel_hi:[1,0]
	v_pk_add_f32 v[244:245], v[182:183], 1.0 op_sel_hi:[1,0]
	v_pk_fma_f32 v[88:89], v[242:243], v[88:89], v[196:197]
	v_pk_fma_f32 v[90:91], v[244:245], v[90:91], v[198:199]
	v_cvt_pk_bf16_f32 v88, v88, v89
	v_cvt_pk_bf16_f32 v89, v90, v91
	global_store_dwordx2 v146, v[88:89], s[66:67] offset:1024
	v_pk_mul_f32 v[92:93], v[92:93], v[204:205] op_sel_hi:[1,0]
	v_pk_mul_f32 v[94:95], v[94:95], v[204:205] op_sel_hi:[1,0]
	v_pk_mul_f32 v[92:93], v[168:169], v[92:93]
	v_pk_mul_f32 v[94:95], v[170:171], v[94:95]
	v_pk_add_f32 v[242:243], v[184:185], 1.0 op_sel_hi:[1,0]
	v_pk_add_f32 v[244:245], v[186:187], 1.0 op_sel_hi:[1,0]
	v_pk_fma_f32 v[92:93], v[242:243], v[92:93], v[200:201]
	v_pk_fma_f32 v[94:95], v[244:245], v[94:95], v[202:203]
	v_cvt_pk_bf16_f32 v92, v92, v93
	v_cvt_pk_bf16_f32 v93, v94, v95
	global_store_dwordx2 v146, v[92:93], s[66:67] offset:1536
	v_add_u32_e32 v146, 0x400000, v146
	global_load_dwordx4 v[172:175], v148, s[98:99]
	global_load_dwordx4 v[176:179], v148, s[98:99] offset:1024
	global_load_dwordx4 v[180:183], v148, s[98:99] offset:2048
	global_load_dwordx4 v[184:187], v148, s[98:99] offset:3072
	global_load_dwordx4 v[188:191], v148, s[50:51]
	global_load_dwordx4 v[192:195], v148, s[50:51] offset:1024
	global_load_dwordx4 v[196:199], v148, s[50:51] offset:2048
	global_load_dwordx4 v[200:203], v148, s[50:51] offset:3072
	v_add_u32_e32 v148, 0x6000, v148
	v_pk_mul_f32 v[242:243], v[96:97], v[96:97]
	v_pk_mul_f32 v[244:245], v[100:101], v[100:101]
	v_pk_mul_f32 v[246:247], v[98:99], v[98:99]
	v_pk_mul_f32 v[248:249], v[102:103], v[102:103]
	v_add_f32_e32 v204, v245, v244
	v_add_f32_e32 v205, v243, v242
	v_add_f32_e32 v204, v248, v204
	v_add_f32_e32 v205, v246, v205
	v_add_f32_e32 v204, v249, v204
	v_add_f32_e32 v205, v247, v205
	v_pk_mul_f32 v[242:243], v[104:105], v[104:105]
	v_pk_mul_f32 v[244:245], v[108:109], v[108:109]
	v_pk_mul_f32 v[246:247], v[106:107], v[106:107]
	v_pk_mul_f32 v[248:249], v[110:111], v[110:111]
	v_add_f32_e32 v206, v243, v242
	v_add_f32_e32 v207, v245, v244
	v_add_f32_e32 v206, v246, v206
	v_add_f32_e32 v207, v248, v207
	v_add_f32_e32 v206, v247, v206
	v_add_f32_e32 v207, v249, v207
	v_add_f32_e32 v204, v205, v204
	v_add_f32_e32 v204, v204, v206
	v_add_f32_e32 v204, v204, v207
	ds_swizzle_b32 v205, v204 offset:swizzle(SWAP,1)
	s_waitcnt lgkmcnt(0)
	v_add_f32_e32 v204, v204, v205
	ds_swizzle_b32 v205, v204 offset:swizzle(SWAP,2)
	s_waitcnt lgkmcnt(0)
	v_add_f32_e32 v204, v204, v205
	ds_swizzle_b32 v205, v204 offset:swizzle(SWAP,4)
	s_waitcnt lgkmcnt(0)
	v_add_f32_e32 v204, v204, v205
	ds_swizzle_b32 v205, v204 offset:swizzle(SWAP,8)
	s_waitcnt lgkmcnt(0)
	v_add_f32_e32 v204, v204, v205
	ds_swizzle_b32 v205, v204 offset:swizzle(SWAP,16)
	s_waitcnt lgkmcnt(0)
	v_add_f32_e32 v204, v204, v205
	v_mov_b32_e32 v205, v204
	s_nop 1
	v_permlane32_swap_b32_e32 v204, v205
	v_add_f32_e32 v204, v204, v205
	v_mov_b32_e32 v205, 0x358637bd
	v_fmamk_f32 v204, v204, 0x3a800000, v205
	v_rsq_f32_e32 v204, v204
	s_nop 0
	s_waitcnt vmcnt(16)
; __device__ __forceinline__ unsigned pk2(float lo, float hi) { const g_f32x2 f = {lo, hi}; return __builtin_bit_cast(unsigned, __builtin_convertvector(f, g_bf16x2)); }
; __device__ __forceinline__ void p_norm(const float* hlat, const float* hctx, const float* g, const float* modl, int sh_off, int sc_off, bf16_t* A, int M,
;                                        const float* part, const float* cgate, float* hcout) {
;     ...
;         float ss = 0.f;
; #pragma unroll
;         for (int i = 0; i < 4; ++i) {
;             if (part != nullptr && row >= NLAT) {
;                 const size_t po = (size_t)(row - NLAT) * 1024 + i * 256 + lane * 4;
;                 const float4 p0 = *(const float4*)(part + po), p1 = *(const float4*)(part + (size_t)4096 * 1024 + po), cg = *(const float4*)(cgate + i * 256 + lane * 4);
;                 v[i].x += cg.x * (p0.x + p1.x); v[i].y += cg.y * (p0.y + p1.y); v[i].z += cg.z * (p0.z + p1.z); v[i].w += cg.w * (p0.w + p1.w);
;                 *(float4*)(hcout + po) = v[i];
;             }
;             ss += v[i].x * v[i].x + v[i].y * v[i].y + v[i].z * v[i].z + v[i].w * v[i].w; }
;         ss = wave_sum(ss);
;         const float rstd = rsqrtf(ss * (1.0f / 1024.0f) + EPS);
;         const float* mr = modl + (size_t)r * 6144;
; #pragma unroll
;         for (int i = 0; i < 4; ++i) {
;             const int k = i * 256 + lane * 4;
;             const float4 gg = *(const float4*)(g + k), scv = *(const float4*)(mr + sc_off + k), shv = *(const float4*)(mr + sh_off + k);
;             const float o0 = v[i].x * rstd * gg.x * (1.0f + scv.x) + shv.x, o1 = v[i].y * rstd * gg.y * (1.0f + scv.y) + shv.y;
;             const float o2 = v[i].z * rstd * gg.z * (1.0f + scv.z) + shv.z, o3 = v[i].w * rstd * gg.w * (1.0f + scv.w) + shv.w;
;             uint2 w; w.x = pk2(o0, o1); w.y = pk2(o2, o3);
;             *(uint2*)(A + (size_t)row * 1024 + k) = w;
	v_pk_mul_f32 v[96:97], v[96:97], v[204:205] op_sel_hi:[1,0]
	v_pk_mul_f32 v[98:99], v[98:99], v[204:205] op_sel_hi:[1,0]
	v_pk_mul_f32 v[96:97], v[156:157], v[96:97]
	v_pk_mul_f32 v[98:99], v[158:159], v[98:99]
	v_pk_add_f32 v[242:243], v[34:35], 1.0 op_sel_hi:[1,0]
	v_pk_add_f32 v[244:245], v[36:37], 1.0 op_sel_hi:[1,0]
	v_pk_fma_f32 v[96:97], v[242:243], v[96:97], v[224:225]
	v_pk_fma_f32 v[98:99], v[244:245], v[98:99], v[226:227]
	v_cvt_pk_bf16_f32 v96, v96, v97
	v_cvt_pk_bf16_f32 v97, v98, v99
	global_store_dwordx2 v146, v[96:97], s[66:67]
	v_pk_mul_f32 v[100:101], v[100:101], v[204:205] op_sel_hi:[1,0]
	v_pk_mul_f32 v[102:103], v[102:103], v[204:205] op_sel_hi:[1,0]
	v_pk_mul_f32 v[100:101], v[160:161], v[100:101]
	v_pk_mul_f32 v[102:103], v[162:163], v[102:103]
	v_pk_add_f32 v[242:243], v[38:39], 1.0 op_sel_hi:[1,0]
	v_pk_add_f32 v[244:245], v[40:41], 1.0 op_sel_hi:[1,0]
	v_pk_fma_f32 v[100:101], v[242:243], v[100:101], v[228:229]
	v_pk_fma_f32 v[102:103], v[244:245], v[102:103], v[230:231]
	v_cvt_pk_bf16_f32 v100, v100, v101
	v_cvt_pk_bf16_f32 v101, v102, v103
	global_store_dwordx2 v146, v[100:101], s[66:67] offset:512
	v_pk_mul_f32 v[104:105], v[104:105], v[204:205] op_sel_hi:[1,0]
	v_pk_mul_f32 v[106:107], v[106:107], v[204:205] op_sel_hi:[1,0]
	v_pk_mul_f32 v[104:105], v[164:165], v[104:105]
	v_pk_mul_f32 v[106:107], v[166:167], v[106:107]
	v_pk_add_f32 v[242:243], v[42:43], 1.0 op_sel_hi:[1,0]
	v_pk_add_f32 v[244:245], v[44:45], 1.0 op_sel_hi:[1,0]
	v_pk_fma_f32 v[104:105], v[242:243], v[104:105], v[232:233]
	v_pk_fma_f32 v[106:107], v[244:245], v[106:107], v[234:235]
	v_cvt_pk_bf16_f32 v104, v104, v105
	v_cvt_pk_bf16_f32 v105, v106, v107
	global_store_dwordx2 v146, v[104:105], s[66:67] offset:1024
	v_pk_mul_f32 v[108:109], v[108:109], v[204:205] op_sel_hi:[1,0]
	v_pk_mul_f32 v[110:111], v[110:111], v[204:205] op_sel_hi:[1,0]
	v_pk_mul_f32 v[108:109], v[168:169], v[108:109]
	v_pk_mul_f32 v[110:111], v[170:171], v[110:111]
	v_pk_add_f32 v[242:243], v[46:47], 1.0 op_sel_hi:[1,0]
	v_pk_add_f32 v[244:245], v[48:49], 1.0 op_sel_hi:[1,0]
	v_pk_fma_f32 v[108:109], v[242:243], v[108:109], v[236:237]
	v_pk_fma_f32 v[110:111], v[244:245], v[110:111], v[238:239]
	v_cvt_pk_bf16_f32 v108, v108, v109
	v_cvt_pk_bf16_f32 v109, v110, v111
	global_store_dwordx2 v146, v[108:109], s[66:67] offset:1536
	v_add_u32_e32 v146, 0x400000, v146
	global_load_dwordx4 v[34:37], v148, s[98:99]
	global_load_dwordx4 v[38:41], v148, s[98:99] offset:1024
	global_load_dwordx4 v[42:45], v148, s[98:99] offset:2048
	global_load_dwordx4 v[46:49], v148, s[98:99] offset:3072
	global_load_dwordx4 v[224:227], v148, s[50:51]
	global_load_dwordx4 v[228:231], v148, s[50:51] offset:1024
	global_load_dwordx4 v[232:235], v148, s[50:51] offset:2048
	global_load_dwordx4 v[236:239], v148, s[50:51] offset:3072
	v_add_u32_e32 v148, 0x6000, v148
	v_pk_mul_f32 v[242:243], v[112:113], v[112:113]
	v_pk_mul_f32 v[244:245], v[116:117], v[116:117]
	v_pk_mul_f32 v[246:247], v[114:115], v[114:115]
	v_pk_mul_f32 v[248:249], v[118:119], v[118:119]
	v_add_f32_e32 v204, v245, v244
	v_add_f32_e32 v205, v243, v242
	v_add_f32_e32 v204, v248, v204
	v_add_f32_e32 v205, v246, v205
	v_add_f32_e32 v204, v249, v204
	v_add_f32_e32 v205, v247, v205
	v_pk_mul_f32 v[242:243], v[120:121], v[120:121]
	v_pk_mul_f32 v[244:245], v[124:125], v[124:125]
	v_pk_mul_f32 v[246:247], v[122:123], v[122:123]
	v_pk_mul_f32 v[248:249], v[126:127], v[126:127]
	v_add_f32_e32 v206, v243, v242
	v_add_f32_e32 v207, v245, v244
	v_add_f32_e32 v206, v246, v206
	v_add_f32_e32 v207, v248, v207
	v_add_f32_e32 v206, v247, v206
	v_add_f32_e32 v207, v249, v207
	v_add_f32_e32 v204, v205, v204
	v_add_f32_e32 v204, v204, v206
	v_add_f32_e32 v204, v204, v207
	ds_swizzle_b32 v205, v204 offset:swizzle(SWAP,1)
	s_waitcnt lgkmcnt(0)
	v_add_f32_e32 v204, v204, v205
	ds_swizzle_b32 v205, v204 offset:swizzle(SWAP,2)
	s_waitcnt lgkmcnt(0)
	v_add_f32_e32 v204, v204, v205
	ds_swizzle_b32 v205, v204 offset:swizzle(SWAP,4)
	s_waitcnt lgkmcnt(0)
	v_add_f32_e32 v204, v204, v205
	ds_swizzle_b32 v205, v204 offset:swizzle(SWAP,8)
	s_waitcnt lgkmcnt(0)
	v_add_f32_e32 v204, v204, v205
	ds_swizzle_b32 v205, v204 offset:swizzle(SWAP,16)
	s_waitcnt lgkmcnt(0)
	v_add_f32_e32 v204, v204, v205
	v_mov_b32_e32 v205, v204
	s_nop 1
	v_permlane32_swap_b32_e32 v204, v205
	v_add_f32_e32 v204, v204, v205
	v_mov_b32_e32 v205, 0x358637bd
	v_fmamk_f32 v204, v204, 0x3a800000, v205
	v_rsq_f32_e32 v204, v204
	s_nop 0
	s_waitcnt vmcnt(12)
; __device__ __forceinline__ unsigned pk2(float lo, float hi) { const g_f32x2 f = {lo, hi}; return __builtin_bit_cast(unsigned, __builtin_convertvector(f, g_bf16x2)); }
; __device__ __forceinline__ void p_norm(const float* hlat, const float* hctx, const float* g, const float* modl, int sh_off, int sc_off, bf16_t* A, int M,
;                                        const float* part, const float* cgate, float* hcout) {
;     ...
;         float ss = 0.f;
; #pragma unroll
;         for (int i = 0; i < 4; ++i) {
;             if (part != nullptr && row >= NLAT) {
;                 const size_t po = (size_t)(row - NLAT) * 1024 + i * 256 + lane * 4;
;                 const float4 p0 = *(const float4*)(part + po), p1 = *(const float4*)(part + (size_t)4096 * 1024 + po), cg = *(const float4*)(cgate + i * 256 + lane * 4);
;                 v[i].x += cg.x * (p0.x + p1.x); v[i].y += cg.y * (p0.y + p1.y); v[i].z += cg.z * (p0.z + p1.z); v[i].w += cg.w * (p0.w + p1.w);
;                 *(float4*)(hcout + po) = v[i];
;             }
;             ss += v[i].x * v[i].x + v[i].y * v[i].y + v[i].z * v[i].z + v[i].w * v[i].w; }
;         ss = wave_sum(ss);
;         const float rstd = rsqrtf(ss * (1.0f / 1024.0f) + EPS);
;         const float* mr = modl + (size_t)r * 6144;
; #pragma unroll
;         for (int i = 0; i < 4; ++i) {
;             const int k = i * 256 + lane * 4;
;             const float4 gg = *(const float4*)(g + k), scv = *(const float4*)(mr + sc_off + k), shv = *(const float4*)(mr + sh_off + k);
;             const float o0 = v[i].x * rstd * gg.x * (1.0f + scv.x) + shv.x, o1 = v[i].y * rstd * gg.y * (1.0f + scv.y) + shv.y;
;             const float o2 = v[i].z * rstd * gg.z * (1.0f + scv.z) + shv.z, o3 = v[i].w * rstd * gg.w * (1.0f + scv.w) + shv.w;
;             uint2 w; w.x = pk2(o0, o1); w.y = pk2(o2, o3);
;             *(uint2*)(A + (size_t)row * 1024 + k) = w;
	v_pk_mul_f32 v[112:113], v[112:113], v[204:205] op_sel_hi:[1,0]
	v_pk_mul_f32 v[114:115], v[114:115], v[204:205] op_sel_hi:[1,0]
	v_pk_mul_f32 v[112:113], v[156:157], v[112:113]
	v_pk_mul_f32 v[114:115], v[158:159], v[114:115]
	v_pk_add_f32 v[242:243], v[172:173], 1.0 op_sel_hi:[1,0]
	v_pk_add_f32 v[244:245], v[174:175], 1.0 op_sel_hi:[1,0]
	v_pk_fma_f32 v[112:113], v[242:243], v[112:113], v[188:189]
	v_pk_fma_f32 v[114:115], v[244:245], v[114:115], v[190:191]
	v_cvt_pk_bf16_f32 v112, v112, v113
	v_cvt_pk_bf16_f32 v113, v114, v115
	global_store_dwordx2 v146, v[112:113], s[66:67]
	v_pk_mul_f32 v[116:117], v[116:117], v[204:205] op_sel_hi:[1,0]
	v_pk_mul_f32 v[118:119], v[118:119], v[204:205] op_sel_hi:[1,0]
	v_pk_mul_f32 v[116:117], v[160:161], v[116:117]
	v_pk_mul_f32 v[118:119], v[162:163], v[118:119]
	v_pk_add_f32 v[242:243], v[176:177], 1.0 op_sel_hi:[1,0]
	v_pk_add_f32 v[244:245], v[178:179], 1.0 op_sel_hi:[1,0]
	v_pk_fma_f32 v[116:117], v[242:243], v[116:117], v[192:193]
	v_pk_fma_f32 v[118:119], v[244:245], v[118:119], v[194:195]
	v_cvt_pk_bf16_f32 v116, v116, v117
	v_cvt_pk_bf16_f32 v117, v118, v119
	global_store_dwordx2 v146, v[116:117], s[66:67] offset:512
	v_pk_mul_f32 v[120:121], v[120:121], v[204:205] op_sel_hi:[1,0]
	v_pk_mul_f32 v[122:123], v[122:123], v[204:205] op_sel_hi:[1,0]
	v_pk_mul_f32 v[120:121], v[164:165], v[120:121]
	v_pk_mul_f32 v[122:123], v[166:167], v[122:123]
	v_pk_add_f32 v[242:243], v[180:181], 1.0 op_sel_hi:[1,0]
	v_pk_add_f32 v[244:245], v[182:183], 1.0 op_sel_hi:[1,0]
	v_pk_fma_f32 v[120:121], v[242:243], v[120:121], v[196:197]
	v_pk_fma_f32 v[122:123], v[244:245], v[122:123], v[198:199]
	v_cvt_pk_bf16_f32 v120, v120, v121
	v_cvt_pk_bf16_f32 v121, v122, v123
	global_store_dwordx2 v146, v[120:121], s[66:67] offset:1024
	v_pk_mul_f32 v[124:125], v[124:125], v[204:205] op_sel_hi:[1,0]
	v_pk_mul_f32 v[126:127], v[126:127], v[204:205] op_sel_hi:[1,0]
	v_pk_mul_f32 v[124:125], v[168:169], v[124:125]
	v_pk_mul_f32 v[126:127], v[170:171], v[126:127]
	v_pk_add_f32 v[242:243], v[184:185], 1.0 op_sel_hi:[1,0]
	v_pk_add_f32 v[244:245], v[186:187], 1.0 op_sel_hi:[1,0]
	v_pk_fma_f32 v[124:125], v[242:243], v[124:125], v[200:201]
	v_pk_fma_f32 v[126:127], v[244:245], v[126:127], v[202:203]
	v_cvt_pk_bf16_f32 v124, v124, v125
	v_cvt_pk_bf16_f32 v125, v126, v127
	global_store_dwordx2 v146, v[124:125], s[66:67] offset:1536
	v_add_u32_e32 v146, 0x400000, v146
	v_pk_mul_f32 v[242:243], v[128:129], v[128:129]
	v_pk_mul_f32 v[244:245], v[132:133], v[132:133]
	v_pk_mul_f32 v[246:247], v[130:131], v[130:131]
	v_pk_mul_f32 v[248:249], v[134:135], v[134:135]
	v_add_f32_e32 v204, v245, v244
	v_add_f32_e32 v205, v243, v242
	v_add_f32_e32 v204, v248, v204
	v_add_f32_e32 v205, v246, v205
	v_add_f32_e32 v204, v249, v204
	v_add_f32_e32 v205, v247, v205
	v_pk_mul_f32 v[242:243], v[136:137], v[136:137]
	v_pk_mul_f32 v[244:245], v[140:141], v[140:141]
	v_pk_mul_f32 v[246:247], v[138:139], v[138:139]
	v_pk_mul_f32 v[248:249], v[142:143], v[142:143]
	v_add_f32_e32 v206, v243, v242
	v_add_f32_e32 v207, v245, v244
	v_add_f32_e32 v206, v246, v206
	v_add_f32_e32 v207, v248, v207
	v_add_f32_e32 v206, v247, v206
	v_add_f32_e32 v207, v249, v207
	v_add_f32_e32 v204, v205, v204
	v_add_f32_e32 v204, v204, v206
	v_add_f32_e32 v204, v204, v207
	ds_swizzle_b32 v205, v204 offset:swizzle(SWAP,1)
	s_waitcnt lgkmcnt(0)
	v_add_f32_e32 v204, v204, v205
	ds_swizzle_b32 v205, v204 offset:swizzle(SWAP,2)
	s_waitcnt lgkmcnt(0)
	v_add_f32_e32 v204, v204, v205
	ds_swizzle_b32 v205, v204 offset:swizzle(SWAP,4)
	s_waitcnt lgkmcnt(0)
	v_add_f32_e32 v204, v204, v205
	ds_swizzle_b32 v205, v204 offset:swizzle(SWAP,8)
	s_waitcnt lgkmcnt(0)
	v_add_f32_e32 v204, v204, v205
	ds_swizzle_b32 v205, v204 offset:swizzle(SWAP,16)
	s_waitcnt lgkmcnt(0)
	v_add_f32_e32 v204, v204, v205
	v_mov_b32_e32 v205, v204
	s_nop 1
	v_permlane32_swap_b32_e32 v204, v205
	v_add_f32_e32 v204, v204, v205
	v_mov_b32_e32 v205, 0x358637bd
	v_fmamk_f32 v204, v204, 0x3a800000, v205
	v_rsq_f32_e32 v204, v204
	s_nop 0
	s_waitcnt vmcnt(4)
	v_pk_mul_f32 v[128:129], v[128:129], v[204:205] op_sel_hi:[1,0]
	v_pk_mul_f32 v[130:131], v[130:131], v[204:205] op_sel_hi:[1,0]
	v_pk_mul_f32 v[128:129], v[156:157], v[128:129]
	v_pk_mul_f32 v[130:131], v[158:159], v[130:131]
	v_pk_add_f32 v[242:243], v[34:35], 1.0 op_sel_hi:[1,0]
	v_pk_add_f32 v[244:245], v[36:37], 1.0 op_sel_hi:[1,0]
	v_pk_fma_f32 v[128:129], v[242:243], v[128:129], v[224:225]
	v_pk_fma_f32 v[130:131], v[244:245], v[130:131], v[226:227]
	v_cvt_pk_bf16_f32 v128, v128, v129
	v_cvt_pk_bf16_f32 v129, v130, v131
	global_store_dwordx2 v146, v[128:129], s[66:67]
	v_pk_mul_f32 v[132:133], v[132:133], v[204:205] op_sel_hi:[1,0]
	v_pk_mul_f32 v[134:135], v[134:135], v[204:205] op_sel_hi:[1,0]
	v_pk_mul_f32 v[132:133], v[160:161], v[132:133]
	v_pk_mul_f32 v[134:135], v[162:163], v[134:135]
	v_pk_add_f32 v[242:243], v[38:39], 1.0 op_sel_hi:[1,0]
	v_pk_add_f32 v[244:245], v[40:41], 1.0 op_sel_hi:[1,0]
	v_pk_fma_f32 v[132:133], v[242:243], v[132:133], v[228:229]
	v_pk_fma_f32 v[134:135], v[244:245], v[134:135], v[230:231]
	v_cvt_pk_bf16_f32 v132, v132, v133
	v_cvt_pk_bf16_f32 v133, v134, v135
	global_store_dwordx2 v146, v[132:133], s[66:67] offset:512
	v_pk_mul_f32 v[136:137], v[136:137], v[204:205] op_sel_hi:[1,0]
	v_pk_mul_f32 v[138:139], v[138:139], v[204:205] op_sel_hi:[1,0]
	v_pk_mul_f32 v[136:137], v[164:165], v[136:137]
	v_pk_mul_f32 v[138:139], v[166:167], v[138:139]
	v_pk_add_f32 v[242:243], v[42:43], 1.0 op_sel_hi:[1,0]
	v_pk_add_f32 v[244:245], v[44:45], 1.0 op_sel_hi:[1,0]
	v_pk_fma_f32 v[136:137], v[242:243], v[136:137], v[232:233]
	v_pk_fma_f32 v[138:139], v[244:245], v[138:139], v[234:235]
	v_cvt_pk_bf16_f32 v136, v136, v137
	v_cvt_pk_bf16_f32 v137, v138, v139
	global_store_dwordx2 v146, v[136:137], s[66:67] offset:1024
	v_pk_mul_f32 v[140:141], v[140:141], v[204:205] op_sel_hi:[1,0]
	v_pk_mul_f32 v[142:143], v[142:143], v[204:205] op_sel_hi:[1,0]
	v_pk_mul_f32 v[140:141], v[168:169], v[140:141]
	v_pk_mul_f32 v[142:143], v[170:171], v[142:143]
	v_pk_add_f32 v[242:243], v[46:47], 1.0 op_sel_hi:[1,0]
	v_pk_add_f32 v[244:245], v[48:49], 1.0 op_sel_hi:[1,0]
	v_pk_fma_f32 v[140:141], v[242:243], v[140:141], v[236:237]
	v_pk_fma_f32 v[142:143], v[244:245], v[142:143], v[238:239]
	v_cvt_pk_bf16_f32 v140, v140, v141
	v_cvt_pk_bf16_f32 v141, v142, v143
	global_store_dwordx2 v146, v[140:141], s[66:67] offset:1536
	v_add_u32_e32 v146, 0x400000, v146
	v_add_u32_e32 v50, 0x8000, v50
	v_cmp_gt_i32_e32 vcc, s10, v50
	v_writelane_b32 v255, s7, 48
	s_and_saveexec_b64 s[16:17], vcc
	s_cbranch_execz .LBB0_419
; __device__ __forceinline__ int obid() { int b = blockIdx.x; asm volatile("" : "+s"(b)); return b; }
; #define PN_LOAD(dst, rw) do { const float* s_ = (rw) < NLAT ? hlat + (size_t)(rw) * 1024 : hctx + (size_t)((rw) - NLAT) * 1024; \
;         _Pragma("unroll") for (int i = 0; i < 4; ++i) dst[i] = *(const float4*)(s_ + i * 256 + lane * 4); } while (0)
; __device__ __forceinline__ void p_norm(const float* hlat, const float* hctx, const float* g, const float* modl, int sh_off, int sc_off, bf16_t* A, int M,
;                                        const float* part, const float* cgate, float* hcout) {
;     ...
;     int row = obid() * 8 + wave;
;     float4 v[4], nv[4];
;     ...
;     if (row < M) PN_LOAD(v, row);
;     while (row < M) {
;         const int nrow = row + stride;
;         if (nrow < M) PN_LOAD(nv, nrow);
;         const int r = row < NLAT ? (row >> 11) : 16;
;         float ss = 0.f;
; #pragma unroll
;         for (int i = 0; i < 4; ++i) {
;             if (part != nullptr && row >= NLAT) {
;                 const size_t po = (size_t)(row - NLAT) * 1024 + i * 256 + lane * 4;
;                 const float4 p0 = *(const float4*)(part + po), p1 = *(const float4*)(part + (size_t)4096 * 1024 + po), cg = *(const float4*)(cgate + i * 256 + lane * 4);
	s_mov_b32 s6, 0x8000
	v_cmp_gt_i32_e32 vcc, s6, v50
	v_readlane_b32 s6, v255, 39
	v_readlane_b32 s8, v255, 41
	v_readlane_b32 s7, v255, 40
	v_readlane_b32 s9, v255, 42
	v_add_u32_e32 v2, 0xffff8000, v50
	v_ashrrev_i32_e32 v51, 31, v50
	v_mov_b32_e32 v4, s7
	v_mov_b32_e32 v5, s9
	v_cndmask_b32_e32 v3, 0, v51, vcc
	v_cndmask_b32_e32 v2, v2, v50, vcc
	v_cndmask_b32_e32 v5, v4, v5, vcc
	v_mov_b32_e32 v4, s6
	v_mov_b32_e32 v6, s8
	v_cndmask_b32_e32 v4, v4, v6, vcc
	v_lshlrev_b64 v[2:3], 12, v[2:3]
	v_lshl_add_u64 v[2:3], v[4:5], 0, v[2:3]
	v_lshlrev_b32_e32 v4, 2, v14
	v_and_b32_e32 v34, 0xfc, v4
	v_lshlrev_b32_e32 v16, 2, v34
	v_mov_b32_e32 v17, v0
	v_lshl_add_u64 v[2:3], v[2:3], 0, v[16:17]
	global_load_dwordx4 v[18:21], v[2:3], off
	global_load_dwordx4 v[10:13], v[2:3], off offset:1024
	global_load_dwordx4 v[6:9], v[2:3], off offset:2048
	s_nop 0
	global_load_dwordx4 v[2:5], v[2:3], off offset:3072
	v_readlane_b32 s6, v255, 45
	s_load_dwordx2 s[8:9], s[0:1], 0x30
	v_readlane_b32 s7, v255, 46
	v_sub_u32_e64 v15, s6, 1 clamp
	s_mov_b32 s6, 0x19800
	v_mul_lo_u32 v22, v15, s6
	v_readlane_b32 s6, v255, 47
	v_readlane_b32 s7, v255, 48
	s_lshl_b64 s[6:7], s[6:7], 2
	s_waitcnt lgkmcnt(0)
	s_add_u32 s6, s8, s6
	v_mov_b32_e32 v23, v0
	s_addc_u32 s7, s9, s7
	v_lshlrev_b64 v[22:23], 2, v[22:23]
	s_cmp_lg_u64 s[2:3], 0
	v_lshl_add_u64 v[22:23], s[56:57], 0, v[22:23]
	s_cselect_b64 s[24:25], -1, 0
	s_add_u32 s26, s2, 0x1000000
	s_addc_u32 s27, s3, 0
	v_lshl_add_u64 v[22:23], v[22:23], 0, v[16:17]
	s_mov_b64 s[8:9], 0x65000
	v_lshlrev_b64 v[26:27], 11, v[50:51]
	v_and_b32_e32 v14, 63, v14
	s_add_i32 s5, s5, s72
	v_lshl_add_u64 v[36:37], v[22:23], 0, s[8:9]
	v_lshl_add_u64 v[38:39], s[6:7], 0, v[16:17]
	v_or_b32_e32 v16, 0x100, v34
	v_or_b32_e32 v22, 0x200, v34
	v_or_b32_e32 v24, 0x300, v34
	v_lshl_or_b32 v26, v14, 3, v26
	v_add_u32_e32 v42, s5, v1
	s_mov_b64 s[20:21], 0
	v_lshl_add_u64 v[40:41], s[66:67], 0, v[26:27]
	v_ashrrev_i32_e32 v43, 31, v42
	v_lshlrev_b32_e32 v44, 2, v16
	v_lshlrev_b32_e32 v46, 2, v22
	v_lshlrev_b32_e32 v48, 2, v24
	s_branch .LBB0_409

; #define PIN(i) ((const float*)(const GASP float*)karg_q(i))
; __device__ __forceinline__ void p_norm(const float* hlat, const float* hctx, const float* g, const float* modl, int sh_off, int sc_off, bf16_t* A, int M,
;                                        const float* part, const float* cgate, float* hcout) {
;     const int tid = otid(), lane = tid & 63, wave = tid >> 6;
;     const int stride = gridDim.x * 8;
;     int row = obid() * 8 + wave;
;     float4 v[4], nv[4];
;     ...
;     if (row < M) PN_LOAD(v, row);
;     while (row < M) {
;         const int nrow = row + stride;
;         if (nrow < M) PN_LOAD(nv, nrow);
;         const int r = row < NLAT ? (row >> 11) : 16;
;         float ss = 0.f;
; #pragma unroll
;         for (int i = 0; i < 4; ++i) {
;             if (part != nullptr && row >= NLAT) {
;                 const size_t po = (size_t)(row - NLAT) * 1024 + i * 256 + lane * 4;
;                 const float4 p0 = *(const float4*)(part + po), p1 = *(const float4*)(part + (size_t)4096 * 1024 + po), cg = *(const float4*)(cgate + i * 256 + lane * 4);
;                 v[i].x += cg.x * (p0.x + p1.x); v[i].y += cg.y * (p0.y + p1.y); v[i].z += cg.z * (p0.z + p1.z); v[i].w += cg.w * (p0.w + p1.w);
;                 *(float4*)(hcout + po) = v[i];
;             }
;             ss += v[i].x * v[i].x + v[i].y * v[i].y + v[i].z * v[i].z + v[i].w * v[i].w; }
;         ss = wave_sum(ss);
;         const float rstd = rsqrtf(ss * (1.0f / 1024.0f) + EPS);
;         const float* mr = modl + (size_t)r * 6144;
; #pragma unroll
;         for (int i = 0; i < 4; ++i) {
;             const int k = i * 256 + lane * 4;
;             const float4 gg = *(const float4*)(g + k), scv = *(const float4*)(mr + sc_off + k), shv = *(const float4*)(mr + sh_off + k);
;             const float o0 = v[i].x * rstd * gg.x * (1.0f + scv.x) + shv.x, o1 = v[i].y * rstd * gg.y * (1.0f + scv.y) + shv.y;
;             const float o2 = v[i].z * rstd * gg.z * (1.0f + scv.z) + shv.z, o3 = v[i].w * rstd * gg.w * (1.0f + scv.w) + shv.w;
;             uint2 w; w.x = pk2(o0, o1); w.y = pk2(o2, o3);
;             *(uint2*)(A + (size_t)row * 1024 + k) = w;
; __global__ void __launch_bounds__(512, 2) hybrid_fwd(Params P) {
;     ...
;         p_norm(POUT, hc_in, PIN(7) + l * 1024, modl, 3 * 1024, 4 * 1024, AO, Mf, last ? nullptr : (const float*)(PWS + WS_MK), modl + 16 * 6144 + 2 * 1024, hc);
.LBB0_1037:
	s_or_b64 exec, exec, s[2:3]
	s_and_b64 s[2:3], s[18:19], exec
	s_mov_b32 s2, 0x8000
	s_cselect_b32 s7, s2, 0x9000
	v_mov_b32_e32 v6, v253
	s_mov_b32 s2, s63
	s_waitcnt lgkmcnt(0)
	s_barrier
	s_lshl_b32 s5, s2, 3
	v_ashrrev_i32_e32 v1, 6, v6
	v_add_u32_e32 v50, s5, v1
	s_waitcnt vmcnt(0) lgkmcnt(0)
	v_readlane_b32 s100, v255, 45
	s_load_dwordx2 s[48:49], s[0:1], 0x38
	s_movk_i32 s101, 0xe8
	s_load_dwordx2 s[46:47], s[0:1], s101
	s_mul_i32 s101, s100, 0x66000
	s_add_u32 s50, s56, s101
	s_addc_u32 s51, s57, 0
	s_add_u32 s98, s50, 0x4000
	s_addc_u32 s99, s51, 0
	s_add_u32 s50, s50, 0x3000
	s_addc_u32 s51, s51, 0
	s_lshl_b32 s100, s100, 12
	v_and_b32_e32 v240, 63, v253
	v_lshlrev_b32_e32 v241, 4, v240
	v_lshlrev_b32_e32 v144, 12, v50
	v_add_u32_e32 v144, v144, v241
	v_lshlrev_b32_e32 v146, 11, v50
	v_lshl_add_u32 v146, v240, 3, v146
	v_mov_b32_e32 v148, v241
	s_waitcnt lgkmcnt(0)
	s_add_u32 s48, s48, s100
	s_addc_u32 s49, s49, 0
	global_load_dwordx4 v[80:83], v144, s[46:47]
	global_load_dwordx4 v[84:87], v144, s[46:47] offset:1024
	global_load_dwordx4 v[88:91], v144, s[46:47] offset:2048
	global_load_dwordx4 v[92:95], v144, s[46:47] offset:3072
	v_add_u32_e32 v144, 0x800000, v144
	global_load_dwordx4 v[156:159], v241, s[48:49]
	global_load_dwordx4 v[160:163], v241, s[48:49] offset:1024
	global_load_dwordx4 v[164:167], v241, s[48:49] offset:2048
	global_load_dwordx4 v[168:171], v241, s[48:49] offset:3072
	global_load_dwordx4 v[172:175], v148, s[98:99]
	global_load_dwordx4 v[176:179], v148, s[98:99] offset:1024
	global_load_dwordx4 v[180:183], v148, s[98:99] offset:2048
	global_load_dwordx4 v[184:187], v148, s[98:99] offset:3072
	global_load_dwordx4 v[188:191], v148, s[50:51]
	global_load_dwordx4 v[192:195], v148, s[50:51] offset:1024
	global_load_dwordx4 v[196:199], v148, s[50:51] offset:2048
	global_load_dwordx4 v[200:203], v148, s[50:51] offset:3072
	v_add_u32_e32 v148, 0x6000, v148
	global_load_dwordx4 v[96:99], v144, s[46:47]
	global_load_dwordx4 v[100:103], v144, s[46:47] offset:1024
	global_load_dwordx4 v[104:107], v144, s[46:47] offset:2048
	global_load_dwordx4 v[108:111], v144, s[46:47] offset:3072
	v_add_u32_e32 v144, 0x800000, v144
	global_load_dwordx4 v[112:115], v144, s[46:47]
	global_load_dwordx4 v[116:119], v144, s[46:47] offset:1024
	global_load_dwordx4 v[120:123], v144, s[46:47] offset:2048
	global_load_dwordx4 v[124:127], v144, s[46:47] offset:3072
	v_add_u32_e32 v144, 0x800000, v144
	global_load_dwordx4 v[34:37], v148, s[98:99]
	global_load_dwordx4 v[38:41], v148, s[98:99] offset:1024
	global_load_dwordx4 v[42:45], v148, s[98:99] offset:2048
	global_load_dwordx4 v[46:49], v148, s[98:99] offset:3072
	global_load_dwordx4 v[224:227], v148, s[50:51]
	global_load_dwordx4 v[228:231], v148, s[50:51] offset:1024
	global_load_dwordx4 v[232:235], v148, s[50:51] offset:2048
	global_load_dwordx4 v[236:239], v148, s[50:51] offset:3072
	v_add_u32_e32 v148, 0x6000, v148
	global_load_dwordx4 v[128:131], v144, s[46:47]
	global_load_dwordx4 v[132:135], v144, s[46:47] offset:1024
	global_load_dwordx4 v[136:139], v144, s[46:47] offset:2048
	global_load_dwordx4 v[140:143], v144, s[46:47] offset:3072
	v_add_u32_e32 v144, 0x800000, v144
	s_waitcnt vmcnt(32)
	v_pk_mul_f32 v[242:243], v[80:81], v[80:81]
	v_pk_mul_f32 v[244:245], v[84:85], v[84:85]
	v_pk_mul_f32 v[246:247], v[82:83], v[82:83]
	v_pk_mul_f32 v[248:249], v[86:87], v[86:87]
	v_add_f32_e32 v204, v245, v244
	v_add_f32_e32 v205, v243, v242
	v_add_f32_e32 v204, v248, v204
	v_add_f32_e32 v205, v246, v205
	v_add_f32_e32 v204, v249, v204
	v_add_f32_e32 v205, v247, v205
	v_pk_mul_f32 v[242:243], v[88:89], v[88:89]
	v_pk_mul_f32 v[244:245], v[92:93], v[92:93]
	v_pk_mul_f32 v[246:247], v[90:91], v[90:91]
	v_pk_mul_f32 v[248:249], v[94:95], v[94:95]
	v_add_f32_e32 v206, v243, v242
	v_add_f32_e32 v207, v245, v244
	v_add_f32_e32 v206, v246, v206
	v_add_f32_e32 v207, v248, v207
	v_add_f32_e32 v206, v247, v206
	v_add_f32_e32 v207, v249, v207
	v_add_f32_e32 v204, v205, v204
	v_add_f32_e32 v204, v204, v206
	v_add_f32_e32 v204, v204, v207
	ds_swizzle_b32 v205, v204 offset:swizzle(SWAP,1)
	s_waitcnt lgkmcnt(0)
	v_add_f32_e32 v204, v204, v205
	ds_swizzle_b32 v205, v204 offset:swizzle(SWAP,2)
	s_waitcnt lgkmcnt(0)
	v_add_f32_e32 v204, v204, v205
	ds_swizzle_b32 v205, v204 offset:swizzle(SWAP,4)
	s_waitcnt lgkmcnt(0)
	v_add_f32_e32 v204, v204, v205
	ds_swizzle_b32 v205, v204 offset:swizzle(SWAP,8)
	s_waitcnt lgkmcnt(0)
	v_add_f32_e32 v204, v204, v205
	ds_swizzle_b32 v205, v204 offset:swizzle(SWAP,16)
	s_waitcnt lgkmcnt(0)
	v_add_f32_e32 v204, v204, v205
	v_mov_b32_e32 v205, v204
	s_nop 1
	v_permlane32_swap_b32_e32 v204, v205
	v_add_f32_e32 v204, v204, v205
	v_mov_b32_e32 v205, 0x358637bd
	v_fmamk_f32 v204, v204, 0x3a800000, v205
	v_rsq_f32_e32 v204, v204
	s_nop 0
	s_waitcnt vmcnt(20)
; __device__ __forceinline__ unsigned pk2(float lo, float hi) { const g_f32x2 f = {lo, hi}; return __builtin_bit_cast(unsigned, __builtin_convertvector(f, g_bf16x2)); }
; __device__ __forceinline__ void p_norm(const float* hlat, const float* hctx, const float* g, const float* modl, int sh_off, int sc_off, bf16_t* A, int M,
;                                        const float* part, const float* cgate, float* hcout) {
;     ...
;         float ss = 0.f;
; #pragma unroll
;         for (int i = 0; i < 4; ++i) {
;             if (part != nullptr && row >= NLAT) {
;                 const size_t po = (size_t)(row - NLAT) * 1024 + i * 256 + lane * 4;
;                 const float4 p0 = *(const float4*)(part + po), p1 = *(const float4*)(part + (size_t)4096 * 1024 + po), cg = *(const float4*)(cgate + i * 256 + lane * 4);
;                 v[i].x += cg.x * (p0.x + p1.x); v[i].y += cg.y * (p0.y + p1.y); v[i].z += cg.z * (p0.z + p1.z); v[i].w += cg.w * (p0.w + p1.w);
;                 *(float4*)(hcout + po) = v[i];
;             }
;             ss += v[i].x * v[i].x + v[i].y * v[i].y + v[i].z * v[i].z + v[i].w * v[i].w; }
;         ss = wave_sum(ss);
;         const float rstd = rsqrtf(ss * (1.0f / 1024.0f) + EPS);
;         const float* mr = modl + (size_t)r * 6144;
; #pragma unroll
;         for (int i = 0; i < 4; ++i) {
;             const int k = i * 256 + lane * 4;
;             const float4 gg = *(const float4*)(g + k), scv = *(const float4*)(mr + sc_off + k), shv = *(const float4*)(mr + sh_off + k);
;             const float o0 = v[i].x * rstd * gg.x * (1.0f + scv.x) + shv.x, o1 = v[i].y * rstd * gg.y * (1.0f + scv.y) + shv.y;
;             const float o2 = v[i].z * rstd * gg.z * (1.0f + scv.z) + shv.z, o3 = v[i].w * rstd * gg.w * (1.0f + scv.w) + shv.w;
;             uint2 w; w.x = pk2(o0, o1); w.y = pk2(o2, o3);
;             *(uint2*)(A + (size_t)row * 1024 + k) = w;
	v_pk_mul_f32 v[80:81], v[80:81], v[204:205] op_sel_hi:[1,0]
	v_pk_mul_f32 v[82:83], v[82:83], v[204:205] op_sel_hi:[1,0]
	v_pk_mul_f32 v[80:81], v[156:157], v[80:81]
	v_pk_mul_f32 v[82:83], v[158:159], v[82:83]
	v_pk_add_f32 v[242:243], v[172:173], 1.0 op_sel_hi:[1,0]
	v_pk_add_f32 v[244:245], v[174:175], 1.0 op_sel_hi:[1,0]
	v_pk_fma_f32 v[80:81], v[242:243], v[80:81], v[188:189]
	v_pk_fma_f32 v[82:83], v[244:245], v[82:83], v[190:191]
	v_cvt_pk_bf16_f32 v80, v80, v81
	v_cvt_pk_bf16_f32 v81, v82, v83
	global_store_dwordx2 v146, v[80:81], s[66:67]
	v_pk_mul_f32 v[84:85], v[84:85], v[204:205] op_sel_hi:[1,0]
	v_pk_mul_f32 v[86:87], v[86:87], v[204:205] op_sel_hi:[1,0]
	v_pk_mul_f32 v[84:85], v[160:161], v[84:85]
	v_pk_mul_f32 v[86:87], v[162:163], v[86:87]
	v_pk_add_f32 v[242:243], v[176:177], 1.0 op_sel_hi:[1,0]
	v_pk_add_f32 v[244:245], v[178:179], 1.0 op_sel_hi:[1,0]
	v_pk_fma_f32 v[84:85], v[242:243], v[84:85], v[192:193]
	v_pk_fma_f32 v[86:87], v[244:245], v[86:87], v[194:195]
	v_cvt_pk_bf16_f32 v84, v84, v85
	v_cvt_pk_bf16_f32 v85, v86, v87
	global_store_dwordx2 v146, v[84:85], s[66:67] offset:512
	v_pk_mul_f32 v[88:89], v[88:89], v[204:205] op_sel_hi:[1,0]
	v_pk_mul_f32 v[90:91], v[90:91], v[204:205] op_sel_hi:[1,0]
	v_pk_mul_f32 v[88:89], v[164:165], v[88:89]
	v_pk_mul_f32 v[90:91], v[166:167], v[90:91]
	v_pk_add_f32 v[242:243], v[180:181], 1.0 op_sel_hi:[1,0]
	v_pk_add_f32 v[244:245], v[182:183], 1.0 op_sel_hi:[1,0]
	v_pk_fma_f32 v[88:89], v[242:243], v[88:89], v[196:197]
	v_pk_fma_f32 v[90:91], v[244:245], v[90:91], v[198:199]
	v_cvt_pk_bf16_f32 v88, v88, v89
	v_cvt_pk_bf16_f32 v89, v90, v91
	global_store_dwordx2 v146, v[88:89], s[66:67] offset:1024
	v_pk_mul_f32 v[92:93], v[92:93], v[204:205] op_sel_hi:[1,0]
	v_pk_mul_f32 v[94:95], v[94:95], v[204:205] op_sel_hi:[1,0]
	v_pk_mul_f32 v[92:93], v[168:169], v[92:93]
	v_pk_mul_f32 v[94:95], v[170:171], v[94:95]
	v_pk_add_f32 v[242:243], v[184:185], 1.0 op_sel_hi:[1,0]
	v_pk_add_f32 v[244:245], v[186:187], 1.0 op_sel_hi:[1,0]
	v_pk_fma_f32 v[92:93], v[242:243], v[92:93], v[200:201]
	v_pk_fma_f32 v[94:95], v[244:245], v[94:95], v[202:203]
	v_cvt_pk_bf16_f32 v92, v92, v93
	v_cvt_pk_bf16_f32 v93, v94, v95
	global_store_dwordx2 v146, v[92:93], s[66:67] offset:1536
	v_add_u32_e32 v146, 0x400000, v146
	global_load_dwordx4 v[172:175], v148, s[98:99]
	global_load_dwordx4 v[176:179], v148, s[98:99] offset:1024
	global_load_dwordx4 v[180:183], v148, s[98:99] offset:2048
	global_load_dwordx4 v[184:187], v148, s[98:99] offset:3072
	global_load_dwordx4 v[188:191], v148, s[50:51]
	global_load_dwordx4 v[192:195], v148, s[50:51] offset:1024
	global_load_dwordx4 v[196:199], v148, s[50:51] offset:2048
	global_load_dwordx4 v[200:203], v148, s[50:51] offset:3072
	v_add_u32_e32 v148, 0x6000, v148
	global_load_dwordx4 v[80:83], v144, s[46:47]
	global_load_dwordx4 v[84:87], v144, s[46:47] offset:1024
	global_load_dwordx4 v[88:91], v144, s[46:47] offset:2048
	global_load_dwordx4 v[92:95], v144, s[46:47] offset:3072
	v_add_u32_e32 v144, 0x800000, v144
	s_waitcnt vmcnt(32)
	v_pk_mul_f32 v[242:243], v[96:97], v[96:97]
	v_pk_mul_f32 v[244:245], v[100:101], v[100:101]
	v_pk_mul_f32 v[246:247], v[98:99], v[98:99]
	v_pk_mul_f32 v[248:249], v[102:103], v[102:103]
	v_add_f32_e32 v204, v245, v244
	v_add_f32_e32 v205, v243, v242
	v_add_f32_e32 v204, v248, v204
	v_add_f32_e32 v205, v246, v205
	v_add_f32_e32 v204, v249, v204
	v_add_f32_e32 v205, v247, v205
	v_pk_mul_f32 v[242:243], v[104:105], v[104:105]
	v_pk_mul_f32 v[244:245], v[108:109], v[108:109]
	v_pk_mul_f32 v[246:247], v[106:107], v[106:107]
	v_pk_mul_f32 v[248:249], v[110:111], v[110:111]
	v_add_f32_e32 v206, v243, v242
	v_add_f32_e32 v207, v245, v244
	v_add_f32_e32 v206, v246, v206
	v_add_f32_e32 v207, v248, v207
	v_add_f32_e32 v206, v247, v206
	v_add_f32_e32 v207, v249, v207
	v_add_f32_e32 v204, v205, v204
	v_add_f32_e32 v204, v204, v206
	v_add_f32_e32 v204, v204, v207
	ds_swizzle_b32 v205, v204 offset:swizzle(SWAP,1)
	s_waitcnt lgkmcnt(0)
	v_add_f32_e32 v204, v204, v205
	ds_swizzle_b32 v205, v204 offset:swizzle(SWAP,2)
	s_waitcnt lgkmcnt(0)
	v_add_f32_e32 v204, v204, v205
	ds_swizzle_b32 v205, v204 offset:swizzle(SWAP,4)
	s_waitcnt lgkmcnt(0)
	v_add_f32_e32 v204, v204, v205
	ds_swizzle_b32 v205, v204 offset:swizzle(SWAP,8)
	s_waitcnt lgkmcnt(0)
	v_add_f32_e32 v204, v204, v205
	ds_swizzle_b32 v205, v204 offset:swizzle(SWAP,16)
	s_waitcnt lgkmcnt(0)
	v_add_f32_e32 v204, v204, v205
	v_mov_b32_e32 v205, v204
	s_nop 1
	v_permlane32_swap_b32_e32 v204, v205
	v_add_f32_e32 v204, v204, v205
	v_mov_b32_e32 v205, 0x358637bd
	v_fmamk_f32 v204, v204, 0x3a800000, v205
	v_rsq_f32_e32 v204, v204
	s_nop 0
	s_waitcnt vmcnt(20)
; __device__ __forceinline__ unsigned pk2(float lo, float hi) { const g_f32x2 f = {lo, hi}; return __builtin_bit_cast(unsigned, __builtin_convertvector(f, g_bf16x2)); }
; __device__ __forceinline__ void p_norm(const float* hlat, const float* hctx, const float* g, const float* modl, int sh_off, int sc_off, bf16_t* A, int M,
;                                        const float* part, const float* cgate, float* hcout) {
;     ...
;         float ss = 0.f;
; #pragma unroll
;         for (int i = 0; i < 4; ++i) {
;             if (part != nullptr && row >= NLAT) {
;                 const size_t po = (size_t)(row - NLAT) * 1024 + i * 256 + lane * 4;
;                 const float4 p0 = *(const float4*)(part + po), p1 = *(const float4*)(part + (size_t)4096 * 1024 + po), cg = *(const float4*)(cgate + i * 256 + lane * 4);
;                 v[i].x += cg.x * (p0.x + p1.x); v[i].y += cg.y * (p0.y + p1.y); v[i].z += cg.z * (p0.z + p1.z); v[i].w += cg.w * (p0.w + p1.w);
;                 *(float4*)(hcout + po) = v[i];
;             }
;             ss += v[i].x * v[i].x + v[i].y * v[i].y + v[i].z * v[i].z + v[i].w * v[i].w; }
;         ss = wave_sum(ss);
;         const float rstd = rsqrtf(ss * (1.0f / 1024.0f) + EPS);
;         const float* mr = modl + (size_t)r * 6144;
; #pragma unroll
;         for (int i = 0; i < 4; ++i) {
;             const int k = i * 256 + lane * 4;
;             const float4 gg = *(const float4*)(g + k), scv = *(const float4*)(mr + sc_off + k), shv = *(const float4*)(mr + sh_off + k);
;             const float o0 = v[i].x * rstd * gg.x * (1.0f + scv.x) + shv.x, o1 = v[i].y * rstd * gg.y * (1.0f + scv.y) + shv.y;
;             const float o2 = v[i].z * rstd * gg.z * (1.0f + scv.z) + shv.z, o3 = v[i].w * rstd * gg.w * (1.0f + scv.w) + shv.w;
;             uint2 w; w.x = pk2(o0, o1); w.y = pk2(o2, o3);
;             *(uint2*)(A + (size_t)row * 1024 + k) = w;
	v_pk_mul_f32 v[96:97], v[96:97], v[204:205] op_sel_hi:[1,0]
	v_pk_mul_f32 v[98:99], v[98:99], v[204:205] op_sel_hi:[1,0]
	v_pk_mul_f32 v[96:97], v[156:157], v[96:97]
	v_pk_mul_f32 v[98:99], v[158:159], v[98:99]
	v_pk_add_f32 v[242:243], v[34:35], 1.0 op_sel_hi:[1,0]
	v_pk_add_f32 v[244:245], v[36:37], 1.0 op_sel_hi:[1,0]
	v_pk_fma_f32 v[96:97], v[242:243], v[96:97], v[224:225]
	v_pk_fma_f32 v[98:99], v[244:245], v[98:99], v[226:227]
	v_cvt_pk_bf16_f32 v96, v96, v97
	v_cvt_pk_bf16_f32 v97, v98, v99
	global_store_dwordx2 v146, v[96:97], s[66:67]
	v_pk_mul_f32 v[100:101], v[100:101], v[204:205] op_sel_hi:[1,0]
	v_pk_mul_f32 v[102:103], v[102:103], v[204:205] op_sel_hi:[1,0]
	v_pk_mul_f32 v[100:101], v[160:161], v[100:101]
	v_pk_mul_f32 v[102:103], v[162:163], v[102:103]
	v_pk_add_f32 v[242:243], v[38:39], 1.0 op_sel_hi:[1,0]
	v_pk_add_f32 v[244:245], v[40:41], 1.0 op_sel_hi:[1,0]
	v_pk_fma_f32 v[100:101], v[242:243], v[100:101], v[228:229]
	v_pk_fma_f32 v[102:103], v[244:245], v[102:103], v[230:231]
	v_cvt_pk_bf16_f32 v100, v100, v101
	v_cvt_pk_bf16_f32 v101, v102, v103
	global_store_dwordx2 v146, v[100:101], s[66:67] offset:512
	v_pk_mul_f32 v[104:105], v[104:105], v[204:205] op_sel_hi:[1,0]
	v_pk_mul_f32 v[106:107], v[106:107], v[204:205] op_sel_hi:[1,0]
	v_pk_mul_f32 v[104:105], v[164:165], v[104:105]
	v_pk_mul_f32 v[106:107], v[166:167], v[106:107]
	v_pk_add_f32 v[242:243], v[42:43], 1.0 op_sel_hi:[1,0]
	v_pk_add_f32 v[244:245], v[44:45], 1.0 op_sel_hi:[1,0]
	v_pk_fma_f32 v[104:105], v[242:243], v[104:105], v[232:233]
	v_pk_fma_f32 v[106:107], v[244:245], v[106:107], v[234:235]
	v_cvt_pk_bf16_f32 v104, v104, v105
	v_cvt_pk_bf16_f32 v105, v106, v107
	global_store_dwordx2 v146, v[104:105], s[66:67] offset:1024
	v_pk_mul_f32 v[108:109], v[108:109], v[204:205] op_sel_hi:[1,0]
	v_pk_mul_f32 v[110:111], v[110:111], v[204:205] op_sel_hi:[1,0]
	v_pk_mul_f32 v[108:109], v[168:169], v[108:109]
	v_pk_mul_f32 v[110:111], v[170:171], v[110:111]
	v_pk_add_f32 v[242:243], v[46:47], 1.0 op_sel_hi:[1,0]
	v_pk_add_f32 v[244:245], v[48:49], 1.0 op_sel_hi:[1,0]
	v_pk_fma_f32 v[108:109], v[242:243], v[108:109], v[236:237]
	v_pk_fma_f32 v[110:111], v[244:245], v[110:111], v[238:239]
	v_cvt_pk_bf16_f32 v108, v108, v109
	v_cvt_pk_bf16_f32 v109, v110, v111
	global_store_dwordx2 v146, v[108:109], s[66:67] offset:1536
	v_add_u32_e32 v146, 0x400000, v146
	global_load_dwordx4 v[34:37], v148, s[98:99]
	global_load_dwordx4 v[38:41], v148, s[98:99] offset:1024
	global_load_dwordx4 v[42:45], v148, s[98:99] offset:2048
	global_load_dwordx4 v[46:49], v148, s[98:99] offset:3072
	global_load_dwordx4 v[224:227], v148, s[50:51]
	global_load_dwordx4 v[228:231], v148, s[50:51] offset:1024
	global_load_dwordx4 v[232:235], v148, s[50:51] offset:2048
	global_load_dwordx4 v[236:239], v148, s[50:51] offset:3072
	v_add_u32_e32 v148, 0x6000, v148
	global_load_dwordx4 v[96:99], v144, s[46:47]
	global_load_dwordx4 v[100:103], v144, s[46:47] offset:1024
	global_load_dwordx4 v[104:107], v144, s[46:47] offset:2048
	global_load_dwordx4 v[108:111], v144, s[46:47] offset:3072
	v_add_u32_e32 v144, 0x800000, v144
	v_pk_mul_f32 v[242:243], v[112:113], v[112:113]
	v_pk_mul_f32 v[244:245], v[116:117], v[116:117]
	v_pk_mul_f32 v[246:247], v[114:115], v[114:115]
	v_pk_mul_f32 v[248:249], v[118:119], v[118:119]
	v_add_f32_e32 v204, v245, v244
	v_add_f32_e32 v205, v243, v242
	v_add_f32_e32 v204, v248, v204
	v_add_f32_e32 v205, v246, v205
	v_add_f32_e32 v204, v249, v204
	v_add_f32_e32 v205, v247, v205
	v_pk_mul_f32 v[242:243], v[120:121], v[120:121]
	v_pk_mul_f32 v[244:245], v[124:125], v[124:125]
	v_pk_mul_f32 v[246:247], v[122:123], v[122:123]
	v_pk_mul_f32 v[248:249], v[126:127], v[126:127]
	v_add_f32_e32 v206, v243, v242
	v_add_f32_e32 v207, v245, v244
	v_add_f32_e32 v206, v246, v206
	v_add_f32_e32 v207, v248, v207
	v_add_f32_e32 v206, v247, v206
	v_add_f32_e32 v207, v249, v207
	v_add_f32_e32 v204, v205, v204
	v_add_f32_e32 v204, v204, v206
	v_add_f32_e32 v204, v204, v207
	ds_swizzle_b32 v205, v204 offset:swizzle(SWAP,1)
	s_waitcnt lgkmcnt(0)
	v_add_f32_e32 v204, v204, v205
	ds_swizzle_b32 v205, v204 offset:swizzle(SWAP,2)
	s_waitcnt lgkmcnt(0)
	v_add_f32_e32 v204, v204, v205
	ds_swizzle_b32 v205, v204 offset:swizzle(SWAP,4)
	s_waitcnt lgkmcnt(0)
	v_add_f32_e32 v204, v204, v205
	ds_swizzle_b32 v205, v204 offset:swizzle(SWAP,8)
	s_waitcnt lgkmcnt(0)
	v_add_f32_e32 v204, v204, v205
	ds_swizzle_b32 v205, v204 offset:swizzle(SWAP,16)
	s_waitcnt lgkmcnt(0)
	v_add_f32_e32 v204, v204, v205
	v_mov_b32_e32 v205, v204
	s_nop 1
	v_permlane32_swap_b32_e32 v204, v205
	v_add_f32_e32 v204, v204, v205
	v_mov_b32_e32 v205, 0x358637bd
	v_fmamk_f32 v204, v204, 0x3a800000, v205
	v_rsq_f32_e32 v204, v204
	s_nop 0
	s_waitcnt vmcnt(20)
; __device__ __forceinline__ unsigned pk2(float lo, float hi) { const g_f32x2 f = {lo, hi}; return __builtin_bit_cast(unsigned, __builtin_convertvector(f, g_bf16x2)); }
; __device__ __forceinline__ void p_norm(const float* hlat, const float* hctx, const float* g, const float* modl, int sh_off, int sc_off, bf16_t* A, int M,
;                                        const float* part, const float* cgate, float* hcout) {
;     ...
;         float ss = 0.f;
; #pragma unroll
;         for (int i = 0; i < 4; ++i) {
;             if (part != nullptr && row >= NLAT) {
;                 const size_t po = (size_t)(row - NLAT) * 1024 + i * 256 + lane * 4;
;                 const float4 p0 = *(const float4*)(part + po), p1 = *(const float4*)(part + (size_t)4096 * 1024 + po), cg = *(const float4*)(cgate + i * 256 + lane * 4);
;                 v[i].x += cg.x * (p0.x + p1.x); v[i].y += cg.y * (p0.y + p1.y); v[i].z += cg.z * (p0.z + p1.z); v[i].w += cg.w * (p0.w + p1.w);
;                 *(float4*)(hcout + po) = v[i];
;             }
;             ss += v[i].x * v[i].x + v[i].y * v[i].y + v[i].z * v[i].z + v[i].w * v[i].w; }
;         ss = wave_sum(ss);
;         const float rstd = rsqrtf(ss * (1.0f / 1024.0f) + EPS);
;         const float* mr = modl + (size_t)r * 6144;
; #pragma unroll
;         for (int i = 0; i < 4; ++i) {
;             const int k = i * 256 + lane * 4;
;             const float4 gg = *(const float4*)(g + k), scv = *(const float4*)(mr + sc_off + k), shv = *(const float4*)(mr + sh_off + k);
;             const float o0 = v[i].x * rstd * gg.x * (1.0f + scv.x) + shv.x, o1 = v[i].y * rstd * gg.y * (1.0f + scv.y) + shv.y;
;             const float o2 = v[i].z * rstd * gg.z * (1.0f + scv.z) + shv.z, o3 = v[i].w * rstd * gg.w * (1.0f + scv.w) + shv.w;
;             uint2 w; w.x = pk2(o0, o1); w.y = pk2(o2, o3);
;             *(uint2*)(A + (size_t)row * 1024 + k) = w;
	v_pk_mul_f32 v[112:113], v[112:113], v[204:205] op_sel_hi:[1,0]
	v_pk_mul_f32 v[114:115], v[114:115], v[204:205] op_sel_hi:[1,0]
	v_pk_mul_f32 v[112:113], v[156:157], v[112:113]
	v_pk_mul_f32 v[114:115], v[158:159], v[114:115]
	v_pk_add_f32 v[242:243], v[172:173], 1.0 op_sel_hi:[1,0]
	v_pk_add_f32 v[244:245], v[174:175], 1.0 op_sel_hi:[1,0]
	v_pk_fma_f32 v[112:113], v[242:243], v[112:113], v[188:189]
	v_pk_fma_f32 v[114:115], v[244:245], v[114:115], v[190:191]
	v_cvt_pk_bf16_f32 v112, v112, v113
	v_cvt_pk_bf16_f32 v113, v114, v115
	global_store_dwordx2 v146, v[112:113], s[66:67]
	v_pk_mul_f32 v[116:117], v[116:117], v[204:205] op_sel_hi:[1,0]
	v_pk_mul_f32 v[118:119], v[118:119], v[204:205] op_sel_hi:[1,0]
	v_pk_mul_f32 v[116:117], v[160:161], v[116:117]
	v_pk_mul_f32 v[118:119], v[162:163], v[118:119]
	v_pk_add_f32 v[242:243], v[176:177], 1.0 op_sel_hi:[1,0]
	v_pk_add_f32 v[244:245], v[178:179], 1.0 op_sel_hi:[1,0]
	v_pk_fma_f32 v[116:117], v[242:243], v[116:117], v[192:193]
	v_pk_fma_f32 v[118:119], v[244:245], v[118:119], v[194:195]
	v_cvt_pk_bf16_f32 v116, v116, v117
	v_cvt_pk_bf16_f32 v117, v118, v119
	global_store_dwordx2 v146, v[116:117], s[66:67] offset:512
	v_pk_mul_f32 v[120:121], v[120:121], v[204:205] op_sel_hi:[1,0]
	v_pk_mul_f32 v[122:123], v[122:123], v[204:205] op_sel_hi:[1,0]
	v_pk_mul_f32 v[120:121], v[164:165], v[120:121]
	v_pk_mul_f32 v[122:123], v[166:167], v[122:123]
	v_pk_add_f32 v[242:243], v[180:181], 1.0 op_sel_hi:[1,0]
	v_pk_add_f32 v[244:245], v[182:183], 1.0 op_sel_hi:[1,0]
	v_pk_fma_f32 v[120:121], v[242:243], v[120:121], v[196:197]
	v_pk_fma_f32 v[122:123], v[244:245], v[122:123], v[198:199]
	v_cvt_pk_bf16_f32 v120, v120, v121
	v_cvt_pk_bf16_f32 v121, v122, v123
	global_store_dwordx2 v146, v[120:121], s[66:67] offset:1024
	v_pk_mul_f32 v[124:125], v[124:125], v[204:205] op_sel_hi:[1,0]
	v_pk_mul_f32 v[126:127], v[126:127], v[204:205] op_sel_hi:[1,0]
	v_pk_mul_f32 v[124:125], v[168:169], v[124:125]
	v_pk_mul_f32 v[126:127], v[170:171], v[126:127]
	v_pk_add_f32 v[242:243], v[184:185], 1.0 op_sel_hi:[1,0]
	v_pk_add_f32 v[244:245], v[186:187], 1.0 op_sel_hi:[1,0]
	v_pk_fma_f32 v[124:125], v[242:243], v[124:125], v[200:201]
	v_pk_fma_f32 v[126:127], v[244:245], v[126:127], v[202:203]
	v_cvt_pk_bf16_f32 v124, v124, v125
	v_cvt_pk_bf16_f32 v125, v126, v127
	global_store_dwordx2 v146, v[124:125], s[66:67] offset:1536
	v_add_u32_e32 v146, 0x400000, v146
	global_load_dwordx4 v[172:175], v148, s[98:99]
	global_load_dwordx4 v[176:179], v148, s[98:99] offset:1024
	global_load_dwordx4 v[180:183], v148, s[98:99] offset:2048
	global_load_dwordx4 v[184:187], v148, s[98:99] offset:3072
	global_load_dwordx4 v[188:191], v148, s[50:51]
	global_load_dwordx4 v[192:195], v148, s[50:51] offset:1024
	global_load_dwordx4 v[196:199], v148, s[50:51] offset:2048
	global_load_dwordx4 v[200:203], v148, s[50:51] offset:3072
	v_add_u32_e32 v148, 0x6000, v148
	global_load_dwordx4 v[112:115], v144, s[46:47]
	global_load_dwordx4 v[116:119], v144, s[46:47] offset:1024
	global_load_dwordx4 v[120:123], v144, s[46:47] offset:2048
	global_load_dwordx4 v[124:127], v144, s[46:47] offset:3072
	v_add_u32_e32 v144, 0x800000, v144
	v_pk_mul_f32 v[242:243], v[128:129], v[128:129]
	v_pk_mul_f32 v[244:245], v[132:133], v[132:133]
	v_pk_mul_f32 v[246:247], v[130:131], v[130:131]
	v_pk_mul_f32 v[248:249], v[134:135], v[134:135]
	v_add_f32_e32 v204, v245, v244
	v_add_f32_e32 v205, v243, v242
	v_add_f32_e32 v204, v248, v204
	v_add_f32_e32 v205, v246, v205
	v_add_f32_e32 v204, v249, v204
	v_add_f32_e32 v205, v247, v205
	v_pk_mul_f32 v[242:243], v[136:137], v[136:137]
	v_pk_mul_f32 v[244:245], v[140:141], v[140:141]
	v_pk_mul_f32 v[246:247], v[138:139], v[138:139]
	v_pk_mul_f32 v[248:249], v[142:143], v[142:143]
	v_add_f32_e32 v206, v243, v242
	v_add_f32_e32 v207, v245, v244
	v_add_f32_e32 v206, v246, v206
	v_add_f32_e32 v207, v248, v207
	v_add_f32_e32 v206, v247, v206
	v_add_f32_e32 v207, v249, v207
	v_add_f32_e32 v204, v205, v204
	v_add_f32_e32 v204, v204, v206
	v_add_f32_e32 v204, v204, v207
	ds_swizzle_b32 v205, v204 offset:swizzle(SWAP,1)
	s_waitcnt lgkmcnt(0)
	v_add_f32_e32 v204, v204, v205
	ds_swizzle_b32 v205, v204 offset:swizzle(SWAP,2)
	s_waitcnt lgkmcnt(0)
	v_add_f32_e32 v204, v204, v205
	ds_swizzle_b32 v205, v204 offset:swizzle(SWAP,4)
	s_waitcnt lgkmcnt(0)
	v_add_f32_e32 v204, v204, v205
	ds_swizzle_b32 v205, v204 offset:swizzle(SWAP,8)
	s_waitcnt lgkmcnt(0)
	v_add_f32_e32 v204, v204, v205
	ds_swizzle_b32 v205, v204 offset:swizzle(SWAP,16)
	s_waitcnt lgkmcnt(0)
	v_add_f32_e32 v204, v204, v205
	v_mov_b32_e32 v205, v204
	s_nop 1
	v_permlane32_swap_b32_e32 v204, v205
	v_add_f32_e32 v204, v204, v205
	v_mov_b32_e32 v205, 0x358637bd
	v_fmamk_f32 v204, v204, 0x3a800000, v205
	v_rsq_f32_e32 v204, v204
	s_nop 0
	s_waitcnt vmcnt(20)
; __device__ __forceinline__ unsigned pk2(float lo, float hi) { const g_f32x2 f = {lo, hi}; return __builtin_bit_cast(unsigned, __builtin_convertvector(f, g_bf16x2)); }
; __device__ __forceinline__ void p_norm(const float* hlat, const float* hctx, const float* g, const float* modl, int sh_off, int sc_off, bf16_t* A, int M,
;                                        const float* part, const float* cgate, float* hcout) {
;     ...
;         float ss = 0.f;
; #pragma unroll
;         for (int i = 0; i < 4; ++i) {
;             if (part != nullptr && row >= NLAT) {
;                 const size_t po = (size_t)(row - NLAT) * 1024 + i * 256 + lane * 4;
;                 const float4 p0 = *(const float4*)(part + po), p1 = *(const float4*)(part + (size_t)4096 * 1024 + po), cg = *(const float4*)(cgate + i * 256 + lane * 4);
;                 v[i].x += cg.x * (p0.x + p1.x); v[i].y += cg.y * (p0.y + p1.y); v[i].z += cg.z * (p0.z + p1.z); v[i].w += cg.w * (p0.w + p1.w);
;                 *(float4*)(hcout + po) = v[i];
;             }
;             ss += v[i].x * v[i].x + v[i].y * v[i].y + v[i].z * v[i].z + v[i].w * v[i].w; }
;         ss = wave_sum(ss);
;         const float rstd = rsqrtf(ss * (1.0f / 1024.0f) + EPS);
;         const float* mr = modl + (size_t)r * 6144;
; #pragma unroll
;         for (int i = 0; i < 4; ++i) {
;             const int k = i * 256 + lane * 4;
;             const float4 gg = *(const float4*)(g + k), scv = *(const float4*)(mr + sc_off + k), shv = *(const float4*)(mr + sh_off + k);
;             const float o0 = v[i].x * rstd * gg.x * (1.0f + scv.x) + shv.x, o1 = v[i].y * rstd * gg.y * (1.0f + scv.y) + shv.y;
;             const float o2 = v[i].z * rstd * gg.z * (1.0f + scv.z) + shv.z, o3 = v[i].w * rstd * gg.w * (1.0f + scv.w) + shv.w;
;             uint2 w; w.x = pk2(o0, o1); w.y = pk2(o2, o3);
;             *(uint2*)(A + (size_t)row * 1024 + k) = w;
	v_pk_mul_f32 v[128:129], v[128:129], v[204:205] op_sel_hi:[1,0]
	v_pk_mul_f32 v[130:131], v[130:131], v[204:205] op_sel_hi:[1,0]
	v_pk_mul_f32 v[128:129], v[156:157], v[128:129]
	v_pk_mul_f32 v[130:131], v[158:159], v[130:131]
	v_pk_add_f32 v[242:243], v[34:35], 1.0 op_sel_hi:[1,0]
	v_pk_add_f32 v[244:245], v[36:37], 1.0 op_sel_hi:[1,0]
	v_pk_fma_f32 v[128:129], v[242:243], v[128:129], v[224:225]
	v_pk_fma_f32 v[130:131], v[244:245], v[130:131], v[226:227]
	v_cvt_pk_bf16_f32 v128, v128, v129
	v_cvt_pk_bf16_f32 v129, v130, v131
	global_store_dwordx2 v146, v[128:129], s[66:67]
	v_pk_mul_f32 v[132:133], v[132:133], v[204:205] op_sel_hi:[1,0]
	v_pk_mul_f32 v[134:135], v[134:135], v[204:205] op_sel_hi:[1,0]
	v_pk_mul_f32 v[132:133], v[160:161], v[132:133]
	v_pk_mul_f32 v[134:135], v[162:163], v[134:135]
	v_pk_add_f32 v[242:243], v[38:39], 1.0 op_sel_hi:[1,0]
	v_pk_add_f32 v[244:245], v[40:41], 1.0 op_sel_hi:[1,0]
	v_pk_fma_f32 v[132:133], v[242:243], v[132:133], v[228:229]
	v_pk_fma_f32 v[134:135], v[244:245], v[134:135], v[230:231]
	v_cvt_pk_bf16_f32 v132, v132, v133
	v_cvt_pk_bf16_f32 v133, v134, v135
	global_store_dwordx2 v146, v[132:133], s[66:67] offset:512
	v_pk_mul_f32 v[136:137], v[136:137], v[204:205] op_sel_hi:[1,0]
	v_pk_mul_f32 v[138:139], v[138:139], v[204:205] op_sel_hi:[1,0]
	v_pk_mul_f32 v[136:137], v[164:165], v[136:137]
	v_pk_mul_f32 v[138:139], v[166:167], v[138:139]
	v_pk_add_f32 v[242:243], v[42:43], 1.0 op_sel_hi:[1,0]
	v_pk_add_f32 v[244:245], v[44:45], 1.0 op_sel_hi:[1,0]
	v_pk_fma_f32 v[136:137], v[242:243], v[136:137], v[232:233]
	v_pk_fma_f32 v[138:139], v[244:245], v[138:139], v[234:235]
	v_cvt_pk_bf16_f32 v136, v136, v137
	v_cvt_pk_bf16_f32 v137, v138, v139
	global_store_dwordx2 v146, v[136:137], s[66:67] offset:1024
	v_pk_mul_f32 v[140:141], v[140:141], v[204:205] op_sel_hi:[1,0]
	v_pk_mul_f32 v[142:143], v[142:143], v[204:205] op_sel_hi:[1,0]
	v_pk_mul_f32 v[140:141], v[168:169], v[140:141]
	v_pk_mul_f32 v[142:143], v[170:171], v[142:143]
	v_pk_add_f32 v[242:243], v[46:47], 1.0 op_sel_hi:[1,0]
	v_pk_add_f32 v[244:245], v[48:49], 1.0 op_sel_hi:[1,0]
	v_pk_fma_f32 v[140:141], v[242:243], v[140:141], v[236:237]
	v_pk_fma_f32 v[142:143], v[244:245], v[142:143], v[238:239]
	v_cvt_pk_bf16_f32 v140, v140, v141
	v_cvt_pk_bf16_f32 v141, v142, v143
	global_store_dwordx2 v146, v[140:141], s[66:67] offset:1536
	v_add_u32_e32 v146, 0x400000, v146
	global_load_dwordx4 v[34:37], v148, s[98:99]
	global_load_dwordx4 v[38:41], v148, s[98:99] offset:1024
	global_load_dwordx4 v[42:45], v148, s[98:99] offset:2048
	global_load_dwordx4 v[46:49], v148, s[98:99] offset:3072
	global_load_dwordx4 v[224:227], v148, s[50:51]
	global_load_dwordx4 v[228:231], v148, s[50:51] offset:1024
	global_load_dwordx4 v[232:235], v148, s[50:51] offset:2048
	global_load_dwordx4 v[236:239], v148, s[50:51] offset:3072
	v_add_u32_e32 v148, 0x6000, v148
	global_load_dwordx4 v[128:131], v144, s[46:47]
	global_load_dwordx4 v[132:135], v144, s[46:47] offset:1024
	global_load_dwordx4 v[136:139], v144, s[46:47] offset:2048
	global_load_dwordx4 v[140:143], v144, s[46:47] offset:3072
	v_add_u32_e32 v144, 0x800000, v144
	v_pk_mul_f32 v[242:243], v[80:81], v[80:81]
	v_pk_mul_f32 v[244:245], v[84:85], v[84:85]
	v_pk_mul_f32 v[246:247], v[82:83], v[82:83]
	v_pk_mul_f32 v[248:249], v[86:87], v[86:87]
	v_add_f32_e32 v204, v245, v244
	v_add_f32_e32 v205, v243, v242
	v_add_f32_e32 v204, v248, v204
	v_add_f32_e32 v205, v246, v205
	v_add_f32_e32 v204, v249, v204
	v_add_f32_e32 v205, v247, v205
	v_pk_mul_f32 v[242:243], v[88:89], v[88:89]
	v_pk_mul_f32 v[244:245], v[92:93], v[92:93]
	v_pk_mul_f32 v[246:247], v[90:91], v[90:91]
	v_pk_mul_f32 v[248:249], v[94:95], v[94:95]
	v_add_f32_e32 v206, v243, v242
	v_add_f32_e32 v207, v245, v244
	v_add_f32_e32 v206, v246, v206
	v_add_f32_e32 v207, v248, v207
	v_add_f32_e32 v206, v247, v206
	v_add_f32_e32 v207, v249, v207
	v_add_f32_e32 v204, v205, v204
	v_add_f32_e32 v204, v204, v206
	v_add_f32_e32 v204, v204, v207
	ds_swizzle_b32 v205, v204 offset:swizzle(SWAP,1)
	s_waitcnt lgkmcnt(0)
	v_add_f32_e32 v204, v204, v205
	ds_swizzle_b32 v205, v204 offset:swizzle(SWAP,2)
	s_waitcnt lgkmcnt(0)
	v_add_f32_e32 v204, v204, v205
	ds_swizzle_b32 v205, v204 offset:swizzle(SWAP,4)
	s_waitcnt lgkmcnt(0)
	v_add_f32_e32 v204, v204, v205
	ds_swizzle_b32 v205, v204 offset:swizzle(SWAP,8)
	s_waitcnt lgkmcnt(0)
	v_add_f32_e32 v204, v204, v205
	ds_swizzle_b32 v205, v204 offset:swizzle(SWAP,16)
	s_waitcnt lgkmcnt(0)
	v_add_f32_e32 v204, v204, v205
	v_mov_b32_e32 v205, v204
	s_nop 1
	v_permlane32_swap_b32_e32 v204, v205
	v_add_f32_e32 v204, v204, v205
	v_mov_b32_e32 v205, 0x358637bd
	v_fmamk_f32 v204, v204, 0x3a800000, v205
	v_rsq_f32_e32 v204, v204
	s_nop 0
	s_waitcnt vmcnt(20)
; __device__ __forceinline__ unsigned pk2(float lo, float hi) { const g_f32x2 f = {lo, hi}; return __builtin_bit_cast(unsigned, __builtin_convertvector(f, g_bf16x2)); }
; __device__ __forceinline__ void p_norm(const float* hlat, const float* hctx, const float* g, const float* modl, int sh_off, int sc_off, bf16_t* A, int M,
;                                        const float* part, const float* cgate, float* hcout) {
;     ...
;         float ss = 0.f;
; #pragma unroll
;         for (int i = 0; i < 4; ++i) {
;             if (part != nullptr && row >= NLAT) {
;                 const size_t po = (size_t)(row - NLAT) * 1024 + i * 256 + lane * 4;
;                 const float4 p0 = *(const float4*)(part + po), p1 = *(const float4*)(part + (size_t)4096 * 1024 + po), cg = *(const float4*)(cgate + i * 256 + lane * 4);
;                 v[i].x += cg.x * (p0.x + p1.x); v[i].y += cg.y * (p0.y + p1.y); v[i].z += cg.z * (p0.z + p1.z); v[i].w += cg.w * (p0.w + p1.w);
;                 *(float4*)(hcout + po) = v[i];
;             }
;             ss += v[i].x * v[i].x + v[i].y * v[i].y + v[i].z * v[i].z + v[i].w * v[i].w; }
;         ss = wave_sum(ss);
;         const float rstd = rsqrtf(ss * (1.0f / 1024.0f) + EPS);
;         const float* mr = modl + (size_t)r * 6144;
; #pragma unroll
;         for (int i = 0; i < 4; ++i) {
;             const int k = i * 256 + lane * 4;
;             const float4 gg = *(const float4*)(g + k), scv = *(const float4*)(mr + sc_off + k), shv = *(const float4*)(mr + sh_off + k);
;             const float o0 = v[i].x * rstd * gg.x * (1.0f + scv.x) + shv.x, o1 = v[i].y * rstd * gg.y * (1.0f + scv.y) + shv.y;
;             const float o2 = v[i].z * rstd * gg.z * (1.0f + scv.z) + shv.z, o3 = v[i].w * rstd * gg.w * (1.0f + scv.w) + shv.w;
;             uint2 w; w.x = pk2(o0, o1); w.y = pk2(o2, o3);
;             *(uint2*)(A + (size_t)row * 1024 + k) = w;
	v_pk_mul_f32 v[80:81], v[80:81], v[204:205] op_sel_hi:[1,0]
	v_pk_mul_f32 v[82:83], v[82:83], v[204:205] op_sel_hi:[1,0]
	v_pk_mul_f32 v[80:81], v[156:157], v[80:81]
	v_pk_mul_f32 v[82:83], v[158:159], v[82:83]
	v_pk_add_f32 v[242:243], v[172:173], 1.0 op_sel_hi:[1,0]
	v_pk_add_f32 v[244:245], v[174:175], 1.0 op_sel_hi:[1,0]
	v_pk_fma_f32 v[80:81], v[242:243], v[80:81], v[188:189]
	v_pk_fma_f32 v[82:83], v[244:245], v[82:83], v[190:191]
	v_cvt_pk_bf16_f32 v80, v80, v81
	v_cvt_pk_bf16_f32 v81, v82, v83
	global_store_dwordx2 v146, v[80:81], s[66:67]
	v_pk_mul_f32 v[84:85], v[84:85], v[204:205] op_sel_hi:[1,0]
	v_pk_mul_f32 v[86:87], v[86:87], v[204:205] op_sel_hi:[1,0]
	v_pk_mul_f32 v[84:85], v[160:161], v[84:85]
	v_pk_mul_f32 v[86:87], v[162:163], v[86:87]
	v_pk_add_f32 v[242:243], v[176:177], 1.0 op_sel_hi:[1,0]
	v_pk_add_f32 v[244:245], v[178:179], 1.0 op_sel_hi:[1,0]
	v_pk_fma_f32 v[84:85], v[242:243], v[84:85], v[192:193]
	v_pk_fma_f32 v[86:87], v[244:245], v[86:87], v[194:195]
	v_cvt_pk_bf16_f32 v84, v84, v85
	v_cvt_pk_bf16_f32 v85, v86, v87
	global_store_dwordx2 v146, v[84:85], s[66:67] offset:512
	v_pk_mul_f32 v[88:89], v[88:89], v[204:205] op_sel_hi:[1,0]
	v_pk_mul_f32 v[90:91], v[90:91], v[204:205] op_sel_hi:[1,0]
	v_pk_mul_f32 v[88:89], v[164:165], v[88:89]
	v_pk_mul_f32 v[90:91], v[166:167], v[90:91]
	v_pk_add_f32 v[242:243], v[180:181], 1.0 op_sel_hi:[1,0]
	v_pk_add_f32 v[244:245], v[182:183], 1.0 op_sel_hi:[1,0]
	v_pk_fma_f32 v[88:89], v[242:243], v[88:89], v[196:197]
	v_pk_fma_f32 v[90:91], v[244:245], v[90:91], v[198:199]
	v_cvt_pk_bf16_f32 v88, v88, v89
	v_cvt_pk_bf16_f32 v89, v90, v91
	global_store_dwordx2 v146, v[88:89], s[66:67] offset:1024
	v_pk_mul_f32 v[92:93], v[92:93], v[204:205] op_sel_hi:[1,0]
	v_pk_mul_f32 v[94:95], v[94:95], v[204:205] op_sel_hi:[1,0]
	v_pk_mul_f32 v[92:93], v[168:169], v[92:93]
	v_pk_mul_f32 v[94:95], v[170:171], v[94:95]
	v_pk_add_f32 v[242:243], v[184:185], 1.0 op_sel_hi:[1,0]
	v_pk_add_f32 v[244:245], v[186:187], 1.0 op_sel_hi:[1,0]
	v_pk_fma_f32 v[92:93], v[242:243], v[92:93], v[200:201]
	v_pk_fma_f32 v[94:95], v[244:245], v[94:95], v[202:203]
	v_cvt_pk_bf16_f32 v92, v92, v93
	v_cvt_pk_bf16_f32 v93, v94, v95
	global_store_dwordx2 v146, v[92:93], s[66:67] offset:1536
	v_add_u32_e32 v146, 0x400000, v146
	global_load_dwordx4 v[172:175], v148, s[98:99]
	global_load_dwordx4 v[176:179], v148, s[98:99] offset:1024
	global_load_dwordx4 v[180:183], v148, s[98:99] offset:2048
	global_load_dwordx4 v[184:187], v148, s[98:99] offset:3072
	global_load_dwordx4 v[188:191], v148, s[50:51]
	global_load_dwordx4 v[192:195], v148, s[50:51] offset:1024
	global_load_dwordx4 v[196:199], v148, s[50:51] offset:2048
	global_load_dwordx4 v[200:203], v148, s[50:51] offset:3072
	v_add_u32_e32 v148, 0x6000, v148
	global_load_dwordx4 v[80:83], v144, s[46:47]
	global_load_dwordx4 v[84:87], v144, s[46:47] offset:1024
	global_load_dwordx4 v[88:91], v144, s[46:47] offset:2048
	global_load_dwordx4 v[92:95], v144, s[46:47] offset:3072
	v_add_u32_e32 v144, 0x800000, v144
	v_pk_mul_f32 v[242:243], v[96:97], v[96:97]
	v_pk_mul_f32 v[244:245], v[100:101], v[100:101]
	v_pk_mul_f32 v[246:247], v[98:99], v[98:99]
	v_pk_mul_f32 v[248:249], v[102:103], v[102:103]
	v_add_f32_e32 v204, v245, v244
	v_add_f32_e32 v205, v243, v242
	v_add_f32_e32 v204, v248, v204
	v_add_f32_e32 v205, v246, v205
	v_add_f32_e32 v204, v249, v204
	v_add_f32_e32 v205, v247, v205
	v_pk_mul_f32 v[242:243], v[104:105], v[104:105]
	v_pk_mul_f32 v[244:245], v[108:109], v[108:109]
	v_pk_mul_f32 v[246:247], v[106:107], v[106:107]
	v_pk_mul_f32 v[248:249], v[110:111], v[110:111]
	v_add_f32_e32 v206, v243, v242
	v_add_f32_e32 v207, v245, v244
	v_add_f32_e32 v206, v246, v206
	v_add_f32_e32 v207, v248, v207
	v_add_f32_e32 v206, v247, v206
	v_add_f32_e32 v207, v249, v207
	v_add_f32_e32 v204, v205, v204
	v_add_f32_e32 v204, v204, v206
	v_add_f32_e32 v204, v204, v207
	ds_swizzle_b32 v205, v204 offset:swizzle(SWAP,1)
	s_waitcnt lgkmcnt(0)
	v_add_f32_e32 v204, v204, v205
	ds_swizzle_b32 v205, v204 offset:swizzle(SWAP,2)
	s_waitcnt lgkmcnt(0)
	v_add_f32_e32 v204, v204, v205
	ds_swizzle_b32 v205, v204 offset:swizzle(SWAP,4)
	s_waitcnt lgkmcnt(0)
	v_add_f32_e32 v204, v204, v205
	ds_swizzle_b32 v205, v204 offset:swizzle(SWAP,8)
	s_waitcnt lgkmcnt(0)
	v_add_f32_e32 v204, v204, v205
	ds_swizzle_b32 v205, v204 offset:swizzle(SWAP,16)
	s_waitcnt lgkmcnt(0)
	v_add_f32_e32 v204, v204, v205
	v_mov_b32_e32 v205, v204
	s_nop 1
	v_permlane32_swap_b32_e32 v204, v205
	v_add_f32_e32 v204, v204, v205
	v_mov_b32_e32 v205, 0x358637bd
	v_fmamk_f32 v204, v204, 0x3a800000, v205
	v_rsq_f32_e32 v204, v204
	s_nop 0
	s_waitcnt vmcnt(20)
; __device__ __forceinline__ unsigned pk2(float lo, float hi) { const g_f32x2 f = {lo, hi}; return __builtin_bit_cast(unsigned, __builtin_convertvector(f, g_bf16x2)); }
; __device__ __forceinline__ void p_norm(const float* hlat, const float* hctx, const float* g, const float* modl, int sh_off, int sc_off, bf16_t* A, int M,
;                                        const float* part, const float* cgate, float* hcout) {
;     ...
;         float ss = 0.f;
; #pragma unroll
;         for (int i = 0; i < 4; ++i) {
;             if (part != nullptr && row >= NLAT) {
;                 const size_t po = (size_t)(row - NLAT) * 1024 + i * 256 + lane * 4;
;                 const float4 p0 = *(const float4*)(part + po), p1 = *(const float4*)(part + (size_t)4096 * 1024 + po), cg = *(const float4*)(cgate + i * 256 + lane * 4);
;                 v[i].x += cg.x * (p0.x + p1.x); v[i].y += cg.y * (p0.y + p1.y); v[i].z += cg.z * (p0.z + p1.z); v[i].w += cg.w * (p0.w + p1.w);
;                 *(float4*)(hcout + po) = v[i];
;             }
;             ss += v[i].x * v[i].x + v[i].y * v[i].y + v[i].z * v[i].z + v[i].w * v[i].w; }
;         ss = wave_sum(ss);
;         const float rstd = rsqrtf(ss * (1.0f / 1024.0f) + EPS);
;         const float* mr = modl + (size_t)r * 6144;
; #pragma unroll
;         for (int i = 0; i < 4; ++i) {
;             const int k = i * 256 + lane * 4;
;             const float4 gg = *(const float4*)(g + k), scv = *(const float4*)(mr + sc_off + k), shv = *(const float4*)(mr + sh_off + k);
;             const float o0 = v[i].x * rstd * gg.x * (1.0f + scv.x) + shv.x, o1 = v[i].y * rstd * gg.y * (1.0f + scv.y) + shv.y;
;             const float o2 = v[i].z * rstd * gg.z * (1.0f + scv.z) + shv.z, o3 = v[i].w * rstd * gg.w * (1.0f + scv.w) + shv.w;
;             uint2 w; w.x = pk2(o0, o1); w.y = pk2(o2, o3);
;             *(uint2*)(A + (size_t)row * 1024 + k) = w;
	v_pk_mul_f32 v[96:97], v[96:97], v[204:205] op_sel_hi:[1,0]
	v_pk_mul_f32 v[98:99], v[98:99], v[204:205] op_sel_hi:[1,0]
	v_pk_mul_f32 v[96:97], v[156:157], v[96:97]
	v_pk_mul_f32 v[98:99], v[158:159], v[98:99]
	v_pk_add_f32 v[242:243], v[34:35], 1.0 op_sel_hi:[1,0]
	v_pk_add_f32 v[244:245], v[36:37], 1.0 op_sel_hi:[1,0]
	v_pk_fma_f32 v[96:97], v[242:243], v[96:97], v[224:225]
	v_pk_fma_f32 v[98:99], v[244:245], v[98:99], v[226:227]
	v_cvt_pk_bf16_f32 v96, v96, v97
	v_cvt_pk_bf16_f32 v97, v98, v99
	global_store_dwordx2 v146, v[96:97], s[66:67]
	v_pk_mul_f32 v[100:101], v[100:101], v[204:205] op_sel_hi:[1,0]
	v_pk_mul_f32 v[102:103], v[102:103], v[204:205] op_sel_hi:[1,0]
	v_pk_mul_f32 v[100:101], v[160:161], v[100:101]
	v_pk_mul_f32 v[102:103], v[162:163], v[102:103]
	v_pk_add_f32 v[242:243], v[38:39], 1.0 op_sel_hi:[1,0]
	v_pk_add_f32 v[244:245], v[40:41], 1.0 op_sel_hi:[1,0]
	v_pk_fma_f32 v[100:101], v[242:243], v[100:101], v[228:229]
	v_pk_fma_f32 v[102:103], v[244:245], v[102:103], v[230:231]
	v_cvt_pk_bf16_f32 v100, v100, v101
	v_cvt_pk_bf16_f32 v101, v102, v103
	global_store_dwordx2 v146, v[100:101], s[66:67] offset:512
	v_pk_mul_f32 v[104:105], v[104:105], v[204:205] op_sel_hi:[1,0]
	v_pk_mul_f32 v[106:107], v[106:107], v[204:205] op_sel_hi:[1,0]
	v_pk_mul_f32 v[104:105], v[164:165], v[104:105]
	v_pk_mul_f32 v[106:107], v[166:167], v[106:107]
	v_pk_add_f32 v[242:243], v[42:43], 1.0 op_sel_hi:[1,0]
	v_pk_add_f32 v[244:245], v[44:45], 1.0 op_sel_hi:[1,0]
	v_pk_fma_f32 v[104:105], v[242:243], v[104:105], v[232:233]
	v_pk_fma_f32 v[106:107], v[244:245], v[106:107], v[234:235]
	v_cvt_pk_bf16_f32 v104, v104, v105
	v_cvt_pk_bf16_f32 v105, v106, v107
	global_store_dwordx2 v146, v[104:105], s[66:67] offset:1024
	v_pk_mul_f32 v[108:109], v[108:109], v[204:205] op_sel_hi:[1,0]
	v_pk_mul_f32 v[110:111], v[110:111], v[204:205] op_sel_hi:[1,0]
	v_pk_mul_f32 v[108:109], v[168:169], v[108:109]
	v_pk_mul_f32 v[110:111], v[170:171], v[110:111]
	v_pk_add_f32 v[242:243], v[46:47], 1.0 op_sel_hi:[1,0]
	v_pk_add_f32 v[244:245], v[48:49], 1.0 op_sel_hi:[1,0]
	v_pk_fma_f32 v[108:109], v[242:243], v[108:109], v[236:237]
	v_pk_fma_f32 v[110:111], v[244:245], v[110:111], v[238:239]
	v_cvt_pk_bf16_f32 v108, v108, v109
	v_cvt_pk_bf16_f32 v109, v110, v111
	global_store_dwordx2 v146, v[108:109], s[66:67] offset:1536
	v_add_u32_e32 v146, 0x400000, v146
	global_load_dwordx4 v[34:37], v148, s[98:99]
	global_load_dwordx4 v[38:41], v148, s[98:99] offset:1024
	global_load_dwordx4 v[42:45], v148, s[98:99] offset:2048
	global_load_dwordx4 v[46:49], v148, s[98:99] offset:3072
	global_load_dwordx4 v[224:227], v148, s[50:51]
	global_load_dwordx4 v[228:231], v148, s[50:51] offset:1024
	global_load_dwordx4 v[232:235], v148, s[50:51] offset:2048
	global_load_dwordx4 v[236:239], v148, s[50:51] offset:3072
	v_add_u32_e32 v148, 0x6000, v148
	global_load_dwordx4 v[96:99], v144, s[46:47]
	global_load_dwordx4 v[100:103], v144, s[46:47] offset:1024
	global_load_dwordx4 v[104:107], v144, s[46:47] offset:2048
	global_load_dwordx4 v[108:111], v144, s[46:47] offset:3072
	v_add_u32_e32 v144, 0x800000, v144
	v_pk_mul_f32 v[242:243], v[112:113], v[112:113]
	v_pk_mul_f32 v[244:245], v[116:117], v[116:117]
	v_pk_mul_f32 v[246:247], v[114:115], v[114:115]
	v_pk_mul_f32 v[248:249], v[118:119], v[118:119]
	v_add_f32_e32 v204, v245, v244
	v_add_f32_e32 v205, v243, v242
	v_add_f32_e32 v204, v248, v204
	v_add_f32_e32 v205, v246, v205
	v_add_f32_e32 v204, v249, v204
	v_add_f32_e32 v205, v247, v205
	v_pk_mul_f32 v[242:243], v[120:121], v[120:121]
	v_pk_mul_f32 v[244:245], v[124:125], v[124:125]
	v_pk_mul_f32 v[246:247], v[122:123], v[122:123]
	v_pk_mul_f32 v[248:249], v[126:127], v[126:127]
	v_add_f32_e32 v206, v243, v242
	v_add_f32_e32 v207, v245, v244
	v_add_f32_e32 v206, v246, v206
	v_add_f32_e32 v207, v248, v207
	v_add_f32_e32 v206, v247, v206
	v_add_f32_e32 v207, v249, v207
	v_add_f32_e32 v204, v205, v204
	v_add_f32_e32 v204, v204, v206
	v_add_f32_e32 v204, v204, v207
	ds_swizzle_b32 v205, v204 offset:swizzle(SWAP,1)
	s_waitcnt lgkmcnt(0)
	v_add_f32_e32 v204, v204, v205
	ds_swizzle_b32 v205, v204 offset:swizzle(SWAP,2)
	s_waitcnt lgkmcnt(0)
	v_add_f32_e32 v204, v204, v205
	ds_swizzle_b32 v205, v204 offset:swizzle(SWAP,4)
	s_waitcnt lgkmcnt(0)
	v_add_f32_e32 v204, v204, v205
	ds_swizzle_b32 v205, v204 offset:swizzle(SWAP,8)
	s_waitcnt lgkmcnt(0)
	v_add_f32_e32 v204, v204, v205
	ds_swizzle_b32 v205, v204 offset:swizzle(SWAP,16)
	s_waitcnt lgkmcnt(0)
	v_add_f32_e32 v204, v204, v205
	v_mov_b32_e32 v205, v204
	s_nop 1
	v_permlane32_swap_b32_e32 v204, v205
	v_add_f32_e32 v204, v204, v205
	v_mov_b32_e32 v205, 0x358637bd
	v_fmamk_f32 v204, v204, 0x3a800000, v205
	v_rsq_f32_e32 v204, v204
	s_nop 0
	s_waitcnt vmcnt(20)
; __device__ __forceinline__ unsigned pk2(float lo, float hi) { const g_f32x2 f = {lo, hi}; return __builtin_bit_cast(unsigned, __builtin_convertvector(f, g_bf16x2)); }
; __device__ __forceinline__ void p_norm(const float* hlat, const float* hctx, const float* g, const float* modl, int sh_off, int sc_off, bf16_t* A, int M,
;                                        const float* part, const float* cgate, float* hcout) {
;     ...
;         float ss = 0.f;
; #pragma unroll
;         for (int i = 0; i < 4; ++i) {
;             if (part != nullptr && row >= NLAT) {
;                 const size_t po = (size_t)(row - NLAT) * 1024 + i * 256 + lane * 4;
;                 const float4 p0 = *(const float4*)(part + po), p1 = *(const float4*)(part + (size_t)4096 * 1024 + po), cg = *(const float4*)(cgate + i * 256 + lane * 4);
;                 v[i].x += cg.x * (p0.x + p1.x); v[i].y += cg.y * (p0.y + p1.y); v[i].z += cg.z * (p0.z + p1.z); v[i].w += cg.w * (p0.w + p1.w);
;                 *(float4*)(hcout + po) = v[i];
;             }
;             ss += v[i].x * v[i].x + v[i].y * v[i].y + v[i].z * v[i].z + v[i].w * v[i].w; }
;         ss = wave_sum(ss);
;         const float rstd = rsqrtf(ss * (1.0f / 1024.0f) + EPS);
;         const float* mr = modl + (size_t)r * 6144;
; #pragma unroll
;         for (int i = 0; i < 4; ++i) {
;             const int k = i * 256 + lane * 4;
;             const float4 gg = *(const float4*)(g + k), scv = *(const float4*)(mr + sc_off + k), shv = *(const float4*)(mr + sh_off + k);
;             const float o0 = v[i].x * rstd * gg.x * (1.0f + scv.x) + shv.x, o1 = v[i].y * rstd * gg.y * (1.0f + scv.y) + shv.y;
;             const float o2 = v[i].z * rstd * gg.z * (1.0f + scv.z) + shv.z, o3 = v[i].w * rstd * gg.w * (1.0f + scv.w) + shv.w;
;             uint2 w; w.x = pk2(o0, o1); w.y = pk2(o2, o3);
;             *(uint2*)(A + (size_t)row * 1024 + k) = w;
	v_pk_mul_f32 v[112:113], v[112:113], v[204:205] op_sel_hi:[1,0]
	v_pk_mul_f32 v[114:115], v[114:115], v[204:205] op_sel_hi:[1,0]
	v_pk_mul_f32 v[112:113], v[156:157], v[112:113]
	v_pk_mul_f32 v[114:115], v[158:159], v[114:115]
	v_pk_add_f32 v[242:243], v[172:173], 1.0 op_sel_hi:[1,0]
	v_pk_add_f32 v[244:245], v[174:175], 1.0 op_sel_hi:[1,0]
	v_pk_fma_f32 v[112:113], v[242:243], v[112:113], v[188:189]
	v_pk_fma_f32 v[114:115], v[244:245], v[114:115], v[190:191]
	v_cvt_pk_bf16_f32 v112, v112, v113
	v_cvt_pk_bf16_f32 v113, v114, v115
	global_store_dwordx2 v146, v[112:113], s[66:67]
	v_pk_mul_f32 v[116:117], v[116:117], v[204:205] op_sel_hi:[1,0]
	v_pk_mul_f32 v[118:119], v[118:119], v[204:205] op_sel_hi:[1,0]
	v_pk_mul_f32 v[116:117], v[160:161], v[116:117]
	v_pk_mul_f32 v[118:119], v[162:163], v[118:119]
	v_pk_add_f32 v[242:243], v[176:177], 1.0 op_sel_hi:[1,0]
	v_pk_add_f32 v[244:245], v[178:179], 1.0 op_sel_hi:[1,0]
	v_pk_fma_f32 v[116:117], v[242:243], v[116:117], v[192:193]
	v_pk_fma_f32 v[118:119], v[244:245], v[118:119], v[194:195]
	v_cvt_pk_bf16_f32 v116, v116, v117
	v_cvt_pk_bf16_f32 v117, v118, v119
	global_store_dwordx2 v146, v[116:117], s[66:67] offset:512
	v_pk_mul_f32 v[120:121], v[120:121], v[204:205] op_sel_hi:[1,0]
	v_pk_mul_f32 v[122:123], v[122:123], v[204:205] op_sel_hi:[1,0]
	v_pk_mul_f32 v[120:121], v[164:165], v[120:121]
	v_pk_mul_f32 v[122:123], v[166:167], v[122:123]
	v_pk_add_f32 v[242:243], v[180:181], 1.0 op_sel_hi:[1,0]
	v_pk_add_f32 v[244:245], v[182:183], 1.0 op_sel_hi:[1,0]
	v_pk_fma_f32 v[120:121], v[242:243], v[120:121], v[196:197]
	v_pk_fma_f32 v[122:123], v[244:245], v[122:123], v[198:199]
	v_cvt_pk_bf16_f32 v120, v120, v121
	v_cvt_pk_bf16_f32 v121, v122, v123
	global_store_dwordx2 v146, v[120:121], s[66:67] offset:1024
	v_pk_mul_f32 v[124:125], v[124:125], v[204:205] op_sel_hi:[1,0]
	v_pk_mul_f32 v[126:127], v[126:127], v[204:205] op_sel_hi:[1,0]
	v_pk_mul_f32 v[124:125], v[168:169], v[124:125]
	v_pk_mul_f32 v[126:127], v[170:171], v[126:127]
	v_pk_add_f32 v[242:243], v[184:185], 1.0 op_sel_hi:[1,0]
	v_pk_add_f32 v[244:245], v[186:187], 1.0 op_sel_hi:[1,0]
	v_pk_fma_f32 v[124:125], v[242:243], v[124:125], v[200:201]
	v_pk_fma_f32 v[126:127], v[244:245], v[126:127], v[202:203]
	v_cvt_pk_bf16_f32 v124, v124, v125
	v_cvt_pk_bf16_f32 v125, v126, v127
	global_store_dwordx2 v146, v[124:125], s[66:67] offset:1536
	v_add_u32_e32 v146, 0x400000, v146
	global_load_dwordx4 v[172:175], v148, s[98:99]
	global_load_dwordx4 v[176:179], v148, s[98:99] offset:1024
	global_load_dwordx4 v[180:183], v148, s[98:99] offset:2048
	global_load_dwordx4 v[184:187], v148, s[98:99] offset:3072
	global_load_dwordx4 v[188:191], v148, s[50:51]
	global_load_dwordx4 v[192:195], v148, s[50:51] offset:1024
	global_load_dwordx4 v[196:199], v148, s[50:51] offset:2048
	global_load_dwordx4 v[200:203], v148, s[50:51] offset:3072
	v_add_u32_e32 v148, 0x6000, v148
	global_load_dwordx4 v[112:115], v144, s[46:47]
	global_load_dwordx4 v[116:119], v144, s[46:47] offset:1024
	global_load_dwordx4 v[120:123], v144, s[46:47] offset:2048
	global_load_dwordx4 v[124:127], v144, s[46:47] offset:3072
	v_add_u32_e32 v144, 0x800000, v144
	v_pk_mul_f32 v[242:243], v[128:129], v[128:129]
	v_pk_mul_f32 v[244:245], v[132:133], v[132:133]
	v_pk_mul_f32 v[246:247], v[130:131], v[130:131]
	v_pk_mul_f32 v[248:249], v[134:135], v[134:135]
	v_add_f32_e32 v204, v245, v244
	v_add_f32_e32 v205, v243, v242
	v_add_f32_e32 v204, v248, v204
	v_add_f32_e32 v205, v246, v205
	v_add_f32_e32 v204, v249, v204
	v_add_f32_e32 v205, v247, v205
	v_pk_mul_f32 v[242:243], v[136:137], v[136:137]
	v_pk_mul_f32 v[244:245], v[140:141], v[140:141]
	v_pk_mul_f32 v[246:247], v[138:139], v[138:139]
	v_pk_mul_f32 v[248:249], v[142:143], v[142:143]
	v_add_f32_e32 v206, v243, v242
	v_add_f32_e32 v207, v245, v244
	v_add_f32_e32 v206, v246, v206
	v_add_f32_e32 v207, v248, v207
	v_add_f32_e32 v206, v247, v206
	v_add_f32_e32 v207, v249, v207
	v_add_f32_e32 v204, v205, v204
	v_add_f32_e32 v204, v204, v206
	v_add_f32_e32 v204, v204, v207
	ds_swizzle_b32 v205, v204 offset:swizzle(SWAP,1)
	s_waitcnt lgkmcnt(0)
	v_add_f32_e32 v204, v204, v205
	ds_swizzle_b32 v205, v204 offset:swizzle(SWAP,2)
	s_waitcnt lgkmcnt(0)
	v_add_f32_e32 v204, v204, v205
	ds_swizzle_b32 v205, v204 offset:swizzle(SWAP,4)
	s_waitcnt lgkmcnt(0)
	v_add_f32_e32 v204, v204, v205
	ds_swizzle_b32 v205, v204 offset:swizzle(SWAP,8)
	s_waitcnt lgkmcnt(0)
	v_add_f32_e32 v204, v204, v205
	ds_swizzle_b32 v205, v204 offset:swizzle(SWAP,16)
	s_waitcnt lgkmcnt(0)
	v_add_f32_e32 v204, v204, v205
	v_mov_b32_e32 v205, v204
	s_nop 1
	v_permlane32_swap_b32_e32 v204, v205
	v_add_f32_e32 v204, v204, v205
	v_mov_b32_e32 v205, 0x358637bd
	v_fmamk_f32 v204, v204, 0x3a800000, v205
	v_rsq_f32_e32 v204, v204
	s_nop 0
	s_waitcnt vmcnt(20)
; __device__ __forceinline__ unsigned pk2(float lo, float hi) { const g_f32x2 f = {lo, hi}; return __builtin_bit_cast(unsigned, __builtin_convertvector(f, g_bf16x2)); }
; __device__ __forceinline__ void p_norm(const float* hlat, const float* hctx, const float* g, const float* modl, int sh_off, int sc_off, bf16_t* A, int M,
;                                        const float* part, const float* cgate, float* hcout) {
;     ...
;         float ss = 0.f;
; #pragma unroll
;         for (int i = 0; i < 4; ++i) {
;             if (part != nullptr && row >= NLAT) {
;                 const size_t po = (size_t)(row - NLAT) * 1024 + i * 256 + lane * 4;
;                 const float4 p0 = *(const float4*)(part + po), p1 = *(const float4*)(part + (size_t)4096 * 1024 + po), cg = *(const float4*)(cgate + i * 256 + lane * 4);
;                 v[i].x += cg.x * (p0.x + p1.x); v[i].y += cg.y * (p0.y + p1.y); v[i].z += cg.z * (p0.z + p1.z); v[i].w += cg.w * (p0.w + p1.w);
;                 *(float4*)(hcout + po) = v[i];
;             }
;             ss += v[i].x * v[i].x + v[i].y * v[i].y + v[i].z * v[i].z + v[i].w * v[i].w; }
;         ss = wave_sum(ss);
;         const float rstd = rsqrtf(ss * (1.0f / 1024.0f) + EPS);
;         const float* mr = modl + (size_t)r * 6144;
; #pragma unroll
;         for (int i = 0; i < 4; ++i) {
;             const int k = i * 256 + lane * 4;
;             const float4 gg = *(const float4*)(g + k), scv = *(const float4*)(mr + sc_off + k), shv = *(const float4*)(mr + sh_off + k);
;             const float o0 = v[i].x * rstd * gg.x * (1.0f + scv.x) + shv.x, o1 = v[i].y * rstd * gg.y * (1.0f + scv.y) + shv.y;
;             const float o2 = v[i].z * rstd * gg.z * (1.0f + scv.z) + shv.z, o3 = v[i].w * rstd * gg.w * (1.0f + scv.w) + shv.w;
;             uint2 w; w.x = pk2(o0, o1); w.y = pk2(o2, o3);
;             *(uint2*)(A + (size_t)row * 1024 + k) = w;
	v_pk_mul_f32 v[128:129], v[128:129], v[204:205] op_sel_hi:[1,0]
	v_pk_mul_f32 v[130:131], v[130:131], v[204:205] op_sel_hi:[1,0]
	v_pk_mul_f32 v[128:129], v[156:157], v[128:129]
	v_pk_mul_f32 v[130:131], v[158:159], v[130:131]
	v_pk_add_f32 v[242:243], v[34:35], 1.0 op_sel_hi:[1,0]
	v_pk_add_f32 v[244:245], v[36:37], 1.0 op_sel_hi:[1,0]
	v_pk_fma_f32 v[128:129], v[242:243], v[128:129], v[224:225]
	v_pk_fma_f32 v[130:131], v[244:245], v[130:131], v[226:227]
	v_cvt_pk_bf16_f32 v128, v128, v129
	v_cvt_pk_bf16_f32 v129, v130, v131
	global_store_dwordx2 v146, v[128:129], s[66:67]
	v_pk_mul_f32 v[132:133], v[132:133], v[204:205] op_sel_hi:[1,0]
	v_pk_mul_f32 v[134:135], v[134:135], v[204:205] op_sel_hi:[1,0]
	v_pk_mul_f32 v[132:133], v[160:161], v[132:133]
	v_pk_mul_f32 v[134:135], v[162:163], v[134:135]
	v_pk_add_f32 v[242:243], v[38:39], 1.0 op_sel_hi:[1,0]
	v_pk_add_f32 v[244:245], v[40:41], 1.0 op_sel_hi:[1,0]
	v_pk_fma_f32 v[132:133], v[242:243], v[132:133], v[228:229]
	v_pk_fma_f32 v[134:135], v[244:245], v[134:135], v[230:231]
	v_cvt_pk_bf16_f32 v132, v132, v133
	v_cvt_pk_bf16_f32 v133, v134, v135
	global_store_dwordx2 v146, v[132:133], s[66:67] offset:512
	v_pk_mul_f32 v[136:137], v[136:137], v[204:205] op_sel_hi:[1,0]
	v_pk_mul_f32 v[138:139], v[138:139], v[204:205] op_sel_hi:[1,0]
	v_pk_mul_f32 v[136:137], v[164:165], v[136:137]
	v_pk_mul_f32 v[138:139], v[166:167], v[138:139]
	v_pk_add_f32 v[242:243], v[42:43], 1.0 op_sel_hi:[1,0]
	v_pk_add_f32 v[244:245], v[44:45], 1.0 op_sel_hi:[1,0]
	v_pk_fma_f32 v[136:137], v[242:243], v[136:137], v[232:233]
	v_pk_fma_f32 v[138:139], v[244:245], v[138:139], v[234:235]
	v_cvt_pk_bf16_f32 v136, v136, v137
	v_cvt_pk_bf16_f32 v137, v138, v139
	global_store_dwordx2 v146, v[136:137], s[66:67] offset:1024
	v_pk_mul_f32 v[140:141], v[140:141], v[204:205] op_sel_hi:[1,0]
	v_pk_mul_f32 v[142:143], v[142:143], v[204:205] op_sel_hi:[1,0]
	v_pk_mul_f32 v[140:141], v[168:169], v[140:141]
	v_pk_mul_f32 v[142:143], v[170:171], v[142:143]
	v_pk_add_f32 v[242:243], v[46:47], 1.0 op_sel_hi:[1,0]
	v_pk_add_f32 v[244:245], v[48:49], 1.0 op_sel_hi:[1,0]
	v_pk_fma_f32 v[140:141], v[242:243], v[140:141], v[236:237]
	v_pk_fma_f32 v[142:143], v[244:245], v[142:143], v[238:239]
	v_cvt_pk_bf16_f32 v140, v140, v141
	v_cvt_pk_bf16_f32 v141, v142, v143
	global_store_dwordx2 v146, v[140:141], s[66:67] offset:1536
	v_add_u32_e32 v146, 0x400000, v146
	global_load_dwordx4 v[34:37], v148, s[98:99]
	global_load_dwordx4 v[38:41], v148, s[98:99] offset:1024
	global_load_dwordx4 v[42:45], v148, s[98:99] offset:2048
	global_load_dwordx4 v[46:49], v148, s[98:99] offset:3072
	global_load_dwordx4 v[224:227], v148, s[50:51]
	global_load_dwordx4 v[228:231], v148, s[50:51] offset:1024
	global_load_dwordx4 v[232:235], v148, s[50:51] offset:2048
	global_load_dwordx4 v[236:239], v148, s[50:51] offset:3072
	v_add_u32_e32 v148, 0x6000, v148
	global_load_dwordx4 v[128:131], v144, s[46:47]
	global_load_dwordx4 v[132:135], v144, s[46:47] offset:1024
	global_load_dwordx4 v[136:139], v144, s[46:47] offset:2048
	global_load_dwordx4 v[140:143], v144, s[46:47] offset:3072
	v_add_u32_e32 v144, 0x800000, v144
	v_pk_mul_f32 v[242:243], v[80:81], v[80:81]
	v_pk_mul_f32 v[244:245], v[84:85], v[84:85]
	v_pk_mul_f32 v[246:247], v[82:83], v[82:83]
	v_pk_mul_f32 v[248:249], v[86:87], v[86:87]
	v_add_f32_e32 v204, v245, v244
	v_add_f32_e32 v205, v243, v242
	v_add_f32_e32 v204, v248, v204
	v_add_f32_e32 v205, v246, v205
	v_add_f32_e32 v204, v249, v204
	v_add_f32_e32 v205, v247, v205
	v_pk_mul_f32 v[242:243], v[88:89], v[88:89]
	v_pk_mul_f32 v[244:245], v[92:93], v[92:93]
	v_pk_mul_f32 v[246:247], v[90:91], v[90:91]
	v_pk_mul_f32 v[248:249], v[94:95], v[94:95]
	v_add_f32_e32 v206, v243, v242
	v_add_f32_e32 v207, v245, v244
	v_add_f32_e32 v206, v246, v206
	v_add_f32_e32 v207, v248, v207
	v_add_f32_e32 v206, v247, v206
	v_add_f32_e32 v207, v249, v207
	v_add_f32_e32 v204, v205, v204
	v_add_f32_e32 v204, v204, v206
	v_add_f32_e32 v204, v204, v207
	ds_swizzle_b32 v205, v204 offset:swizzle(SWAP,1)
	s_waitcnt lgkmcnt(0)
	v_add_f32_e32 v204, v204, v205
	ds_swizzle_b32 v205, v204 offset:swizzle(SWAP,2)
	s_waitcnt lgkmcnt(0)
	v_add_f32_e32 v204, v204, v205
	ds_swizzle_b32 v205, v204 offset:swizzle(SWAP,4)
	s_waitcnt lgkmcnt(0)
	v_add_f32_e32 v204, v204, v205
	ds_swizzle_b32 v205, v204 offset:swizzle(SWAP,8)
	s_waitcnt lgkmcnt(0)
	v_add_f32_e32 v204, v204, v205
	ds_swizzle_b32 v205, v204 offset:swizzle(SWAP,16)
	s_waitcnt lgkmcnt(0)
	v_add_f32_e32 v204, v204, v205
	v_mov_b32_e32 v205, v204
	s_nop 1
	v_permlane32_swap_b32_e32 v204, v205
	v_add_f32_e32 v204, v204, v205
	v_mov_b32_e32 v205, 0x358637bd
	v_fmamk_f32 v204, v204, 0x3a800000, v205
	v_rsq_f32_e32 v204, v204
	s_nop 0
	s_waitcnt vmcnt(20)
; __device__ __forceinline__ unsigned pk2(float lo, float hi) { const g_f32x2 f = {lo, hi}; return __builtin_bit_cast(unsigned, __builtin_convertvector(f, g_bf16x2)); }
; __device__ __forceinline__ void p_norm(const float* hlat, const float* hctx, const float* g, const float* modl, int sh_off, int sc_off, bf16_t* A, int M,
;                                        const float* part, const float* cgate, float* hcout) {
;     ...
;     while (row < M) {
;         const int nrow = row + stride;
;         if (nrow < M) PN_LOAD(nv, nrow);
;         const int r = row < NLAT ? (row >> 11) : 16;
;         float ss = 0.f;
; #pragma unroll
;         for (int i = 0; i < 4; ++i) {
;             if (part != nullptr && row >= NLAT) {
;                 const size_t po = (size_t)(row - NLAT) * 1024 + i * 256 + lane * 4;
;                 const float4 p0 = *(const float4*)(part + po), p1 = *(const float4*)(part + (size_t)4096 * 1024 + po), cg = *(const float4*)(cgate + i * 256 + lane * 4);
;                 v[i].x += cg.x * (p0.x + p1.x); v[i].y += cg.y * (p0.y + p1.y); v[i].z += cg.z * (p0.z + p1.z); v[i].w += cg.w * (p0.w + p1.w);
;                 *(float4*)(hcout + po) = v[i];
;             }
;             ss += v[i].x * v[i].x + v[i].y * v[i].y + v[i].z * v[i].z + v[i].w * v[i].w; }
;         ss = wave_sum(ss);
;         const float rstd = rsqrtf(ss * (1.0f / 1024.0f) + EPS);
;         const float* mr = modl + (size_t)r * 6144;
; #pragma unroll
;         for (int i = 0; i < 4; ++i) {
;             const int k = i * 256 + lane * 4;
;             const float4 gg = *(const float4*)(g + k), scv = *(const float4*)(mr + sc_off + k), shv = *(const float4*)(mr + sh_off + k);
;             const float o0 = v[i].x * rstd * gg.x * (1.0f + scv.x) + shv.x, o1 = v[i].y * rstd * gg.y * (1.0f + scv.y) + shv.y;
;             const float o2 = v[i].z * rstd * gg.z * (1.0f + scv.z) + shv.z, o3 = v[i].w * rstd * gg.w * (1.0f + scv.w) + shv.w;
;             uint2 w; w.x = pk2(o0, o1); w.y = pk2(o2, o3);
;             *(uint2*)(A + (size_t)row * 1024 + k) = w;
;         }
; #pragma unroll
;         for (int i = 0; i < 4; ++i) v[i] = nv[i];
;         row = nrow;
	v_pk_mul_f32 v[80:81], v[80:81], v[204:205] op_sel_hi:[1,0]
	v_pk_mul_f32 v[82:83], v[82:83], v[204:205] op_sel_hi:[1,0]
	v_pk_mul_f32 v[80:81], v[156:157], v[80:81]
	v_pk_mul_f32 v[82:83], v[158:159], v[82:83]
	v_pk_add_f32 v[242:243], v[172:173], 1.0 op_sel_hi:[1,0]
	v_pk_add_f32 v[244:245], v[174:175], 1.0 op_sel_hi:[1,0]
	v_pk_fma_f32 v[80:81], v[242:243], v[80:81], v[188:189]
	v_pk_fma_f32 v[82:83], v[244:245], v[82:83], v[190:191]
	v_cvt_pk_bf16_f32 v80, v80, v81
	v_cvt_pk_bf16_f32 v81, v82, v83
	global_store_dwordx2 v146, v[80:81], s[66:67]
	v_pk_mul_f32 v[84:85], v[84:85], v[204:205] op_sel_hi:[1,0]
	v_pk_mul_f32 v[86:87], v[86:87], v[204:205] op_sel_hi:[1,0]
	v_pk_mul_f32 v[84:85], v[160:161], v[84:85]
	v_pk_mul_f32 v[86:87], v[162:163], v[86:87]
	v_pk_add_f32 v[242:243], v[176:177], 1.0 op_sel_hi:[1,0]
	v_pk_add_f32 v[244:245], v[178:179], 1.0 op_sel_hi:[1,0]
	v_pk_fma_f32 v[84:85], v[242:243], v[84:85], v[192:193]
	v_pk_fma_f32 v[86:87], v[244:245], v[86:87], v[194:195]
	v_cvt_pk_bf16_f32 v84, v84, v85
	v_cvt_pk_bf16_f32 v85, v86, v87
	global_store_dwordx2 v146, v[84:85], s[66:67] offset:512
	v_pk_mul_f32 v[88:89], v[88:89], v[204:205] op_sel_hi:[1,0]
	v_pk_mul_f32 v[90:91], v[90:91], v[204:205] op_sel_hi:[1,0]
	v_pk_mul_f32 v[88:89], v[164:165], v[88:89]
	v_pk_mul_f32 v[90:91], v[166:167], v[90:91]
	v_pk_add_f32 v[242:243], v[180:181], 1.0 op_sel_hi:[1,0]
	v_pk_add_f32 v[244:245], v[182:183], 1.0 op_sel_hi:[1,0]
	v_pk_fma_f32 v[88:89], v[242:243], v[88:89], v[196:197]
	v_pk_fma_f32 v[90:91], v[244:245], v[90:91], v[198:199]
	v_cvt_pk_bf16_f32 v88, v88, v89
	v_cvt_pk_bf16_f32 v89, v90, v91
	global_store_dwordx2 v146, v[88:89], s[66:67] offset:1024
	v_pk_mul_f32 v[92:93], v[92:93], v[204:205] op_sel_hi:[1,0]
	v_pk_mul_f32 v[94:95], v[94:95], v[204:205] op_sel_hi:[1,0]
	v_pk_mul_f32 v[92:93], v[168:169], v[92:93]
	v_pk_mul_f32 v[94:95], v[170:171], v[94:95]
	v_pk_add_f32 v[242:243], v[184:185], 1.0 op_sel_hi:[1,0]
	v_pk_add_f32 v[244:245], v[186:187], 1.0 op_sel_hi:[1,0]
	v_pk_fma_f32 v[92:93], v[242:243], v[92:93], v[200:201]
	v_pk_fma_f32 v[94:95], v[244:245], v[94:95], v[202:203]
	v_cvt_pk_bf16_f32 v92, v92, v93
	v_cvt_pk_bf16_f32 v93, v94, v95
	global_store_dwordx2 v146, v[92:93], s[66:67] offset:1536
	v_add_u32_e32 v146, 0x400000, v146
	global_load_dwordx4 v[172:175], v148, s[98:99]
	global_load_dwordx4 v[176:179], v148, s[98:99] offset:1024
	global_load_dwordx4 v[180:183], v148, s[98:99] offset:2048
	global_load_dwordx4 v[184:187], v148, s[98:99] offset:3072
	global_load_dwordx4 v[188:191], v148, s[50:51]
	global_load_dwordx4 v[192:195], v148, s[50:51] offset:1024
	global_load_dwordx4 v[196:199], v148, s[50:51] offset:2048
	global_load_dwordx4 v[200:203], v148, s[50:51] offset:3072
	v_add_u32_e32 v148, 0x6000, v148
	global_load_dwordx4 v[80:83], v144, s[46:47]
	global_load_dwordx4 v[84:87], v144, s[46:47] offset:1024
	global_load_dwordx4 v[88:91], v144, s[46:47] offset:2048
	global_load_dwordx4 v[92:95], v144, s[46:47] offset:3072
	v_add_u32_e32 v144, 0x800000, v144
	v_pk_mul_f32 v[242:243], v[96:97], v[96:97]
	v_pk_mul_f32 v[244:245], v[100:101], v[100:101]
	v_pk_mul_f32 v[246:247], v[98:99], v[98:99]
	v_pk_mul_f32 v[248:249], v[102:103], v[102:103]
	v_add_f32_e32 v204, v245, v244
	v_add_f32_e32 v205, v243, v242
	v_add_f32_e32 v204, v248, v204
	v_add_f32_e32 v205, v246, v205
	v_add_f32_e32 v204, v249, v204
	v_add_f32_e32 v205, v247, v205
	v_pk_mul_f32 v[242:243], v[104:105], v[104:105]
	v_pk_mul_f32 v[244:245], v[108:109], v[108:109]
	v_pk_mul_f32 v[246:247], v[106:107], v[106:107]
	v_pk_mul_f32 v[248:249], v[110:111], v[110:111]
	v_add_f32_e32 v206, v243, v242
	v_add_f32_e32 v207, v245, v244
	v_add_f32_e32 v206, v246, v206
	v_add_f32_e32 v207, v248, v207
	v_add_f32_e32 v206, v247, v206
	v_add_f32_e32 v207, v249, v207
	v_add_f32_e32 v204, v205, v204
	v_add_f32_e32 v204, v204, v206
	v_add_f32_e32 v204, v204, v207
	ds_swizzle_b32 v205, v204 offset:swizzle(SWAP,1)
	s_waitcnt lgkmcnt(0)
	v_add_f32_e32 v204, v204, v205
	ds_swizzle_b32 v205, v204 offset:swizzle(SWAP,2)
	s_waitcnt lgkmcnt(0)
	v_add_f32_e32 v204, v204, v205
	ds_swizzle_b32 v205, v204 offset:swizzle(SWAP,4)
	s_waitcnt lgkmcnt(0)
	v_add_f32_e32 v204, v204, v205
	ds_swizzle_b32 v205, v204 offset:swizzle(SWAP,8)
	s_waitcnt lgkmcnt(0)
	v_add_f32_e32 v204, v204, v205
	ds_swizzle_b32 v205, v204 offset:swizzle(SWAP,16)
	s_waitcnt lgkmcnt(0)
	v_add_f32_e32 v204, v204, v205
	v_mov_b32_e32 v205, v204
	s_nop 1
	v_permlane32_swap_b32_e32 v204, v205
	v_add_f32_e32 v204, v204, v205
	v_mov_b32_e32 v205, 0x358637bd
	v_fmamk_f32 v204, v204, 0x3a800000, v205
	v_rsq_f32_e32 v204, v204
	s_nop 0
	s_waitcnt vmcnt(20)
; __device__ __forceinline__ unsigned pk2(float lo, float hi) { const g_f32x2 f = {lo, hi}; return __builtin_bit_cast(unsigned, __builtin_convertvector(f, g_bf16x2)); }
; __device__ __forceinline__ void p_norm(const float* hlat, const float* hctx, const float* g, const float* modl, int sh_off, int sc_off, bf16_t* A, int M,
;                                        const float* part, const float* cgate, float* hcout) {
;     ...
;     while (row < M) {
;         const int nrow = row + stride;
;         if (nrow < M) PN_LOAD(nv, nrow);
;         const int r = row < NLAT ? (row >> 11) : 16;
;         float ss = 0.f;
; #pragma unroll
;         for (int i = 0; i < 4; ++i) {
;             if (part != nullptr && row >= NLAT) {
;                 const size_t po = (size_t)(row - NLAT) * 1024 + i * 256 + lane * 4;
;                 const float4 p0 = *(const float4*)(part + po), p1 = *(const float4*)(part + (size_t)4096 * 1024 + po), cg = *(const float4*)(cgate + i * 256 + lane * 4);
;                 v[i].x += cg.x * (p0.x + p1.x); v[i].y += cg.y * (p0.y + p1.y); v[i].z += cg.z * (p0.z + p1.z); v[i].w += cg.w * (p0.w + p1.w);
;                 *(float4*)(hcout + po) = v[i];
;             }
;             ss += v[i].x * v[i].x + v[i].y * v[i].y + v[i].z * v[i].z + v[i].w * v[i].w; }
;         ss = wave_sum(ss);
;         const float rstd = rsqrtf(ss * (1.0f / 1024.0f) + EPS);
;         const float* mr = modl + (size_t)r * 6144;
; #pragma unroll
;         for (int i = 0; i < 4; ++i) {
;             const int k = i * 256 + lane * 4;
;             const float4 gg = *(const float4*)(g + k), scv = *(const float4*)(mr + sc_off + k), shv = *(const float4*)(mr + sh_off + k);
;             const float o0 = v[i].x * rstd * gg.x * (1.0f + scv.x) + shv.x, o1 = v[i].y * rstd * gg.y * (1.0f + scv.y) + shv.y;
;             const float o2 = v[i].z * rstd * gg.z * (1.0f + scv.z) + shv.z, o3 = v[i].w * rstd * gg.w * (1.0f + scv.w) + shv.w;
;             uint2 w; w.x = pk2(o0, o1); w.y = pk2(o2, o3);
;             *(uint2*)(A + (size_t)row * 1024 + k) = w;
;         }
; #pragma unroll
;         for (int i = 0; i < 4; ++i) v[i] = nv[i];
;         row = nrow;
	v_pk_mul_f32 v[96:97], v[96:97], v[204:205] op_sel_hi:[1,0]
	v_pk_mul_f32 v[98:99], v[98:99], v[204:205] op_sel_hi:[1,0]
	v_pk_mul_f32 v[96:97], v[156:157], v[96:97]
	v_pk_mul_f32 v[98:99], v[158:159], v[98:99]
	v_pk_add_f32 v[242:243], v[34:35], 1.0 op_sel_hi:[1,0]
	v_pk_add_f32 v[244:245], v[36:37], 1.0 op_sel_hi:[1,0]
	v_pk_fma_f32 v[96:97], v[242:243], v[96:97], v[224:225]
	v_pk_fma_f32 v[98:99], v[244:245], v[98:99], v[226:227]
	v_cvt_pk_bf16_f32 v96, v96, v97
	v_cvt_pk_bf16_f32 v97, v98, v99
	global_store_dwordx2 v146, v[96:97], s[66:67]
	v_pk_mul_f32 v[100:101], v[100:101], v[204:205] op_sel_hi:[1,0]
	v_pk_mul_f32 v[102:103], v[102:103], v[204:205] op_sel_hi:[1,0]
	v_pk_mul_f32 v[100:101], v[160:161], v[100:101]
	v_pk_mul_f32 v[102:103], v[162:163], v[102:103]
	v_pk_add_f32 v[242:243], v[38:39], 1.0 op_sel_hi:[1,0]
	v_pk_add_f32 v[244:245], v[40:41], 1.0 op_sel_hi:[1,0]
	v_pk_fma_f32 v[100:101], v[242:243], v[100:101], v[228:229]
	v_pk_fma_f32 v[102:103], v[244:245], v[102:103], v[230:231]
	v_cvt_pk_bf16_f32 v100, v100, v101
	v_cvt_pk_bf16_f32 v101, v102, v103
	global_store_dwordx2 v146, v[100:101], s[66:67] offset:512
	v_pk_mul_f32 v[104:105], v[104:105], v[204:205] op_sel_hi:[1,0]
	v_pk_mul_f32 v[106:107], v[106:107], v[204:205] op_sel_hi:[1,0]
	v_pk_mul_f32 v[104:105], v[164:165], v[104:105]
	v_pk_mul_f32 v[106:107], v[166:167], v[106:107]
	v_pk_add_f32 v[242:243], v[42:43], 1.0 op_sel_hi:[1,0]
	v_pk_add_f32 v[244:245], v[44:45], 1.0 op_sel_hi:[1,0]
	v_pk_fma_f32 v[104:105], v[242:243], v[104:105], v[232:233]
	v_pk_fma_f32 v[106:107], v[244:245], v[106:107], v[234:235]
	v_cvt_pk_bf16_f32 v104, v104, v105
	v_cvt_pk_bf16_f32 v105, v106, v107
	global_store_dwordx2 v146, v[104:105], s[66:67] offset:1024
	v_pk_mul_f32 v[108:109], v[108:109], v[204:205] op_sel_hi:[1,0]
	v_pk_mul_f32 v[110:111], v[110:111], v[204:205] op_sel_hi:[1,0]
	v_pk_mul_f32 v[108:109], v[168:169], v[108:109]
	v_pk_mul_f32 v[110:111], v[170:171], v[110:111]
	v_pk_add_f32 v[242:243], v[46:47], 1.0 op_sel_hi:[1,0]
	v_pk_add_f32 v[244:245], v[48:49], 1.0 op_sel_hi:[1,0]
	v_pk_fma_f32 v[108:109], v[242:243], v[108:109], v[236:237]
	v_pk_fma_f32 v[110:111], v[244:245], v[110:111], v[238:239]
	v_cvt_pk_bf16_f32 v108, v108, v109
	v_cvt_pk_bf16_f32 v109, v110, v111
	global_store_dwordx2 v146, v[108:109], s[66:67] offset:1536
	v_add_u32_e32 v146, 0x400000, v146
	global_load_dwordx4 v[34:37], v148, s[98:99]
	global_load_dwordx4 v[38:41], v148, s[98:99] offset:1024
	global_load_dwordx4 v[42:45], v148, s[98:99] offset:2048
	global_load_dwordx4 v[46:49], v148, s[98:99] offset:3072
	global_load_dwordx4 v[224:227], v148, s[50:51]
	global_load_dwordx4 v[228:231], v148, s[50:51] offset:1024
	global_load_dwordx4 v[232:235], v148, s[50:51] offset:2048
	global_load_dwordx4 v[236:239], v148, s[50:51] offset:3072
	v_add_u32_e32 v148, 0x6000, v148
	global_load_dwordx4 v[96:99], v144, s[46:47]
	global_load_dwordx4 v[100:103], v144, s[46:47] offset:1024
	global_load_dwordx4 v[104:107], v144, s[46:47] offset:2048
	global_load_dwordx4 v[108:111], v144, s[46:47] offset:3072
	v_add_u32_e32 v144, 0x800000, v144
	v_pk_mul_f32 v[242:243], v[112:113], v[112:113]
	v_pk_mul_f32 v[244:245], v[116:117], v[116:117]
	v_pk_mul_f32 v[246:247], v[114:115], v[114:115]
	v_pk_mul_f32 v[248:249], v[118:119], v[118:119]
	v_add_f32_e32 v204, v245, v244
	v_add_f32_e32 v205, v243, v242
	v_add_f32_e32 v204, v248, v204
	v_add_f32_e32 v205, v246, v205
	v_add_f32_e32 v204, v249, v204
	v_add_f32_e32 v205, v247, v205
	v_pk_mul_f32 v[242:243], v[120:121], v[120:121]
	v_pk_mul_f32 v[244:245], v[124:125], v[124:125]
	v_pk_mul_f32 v[246:247], v[122:123], v[122:123]
	v_pk_mul_f32 v[248:249], v[126:127], v[126:127]
	v_add_f32_e32 v206, v243, v242
	v_add_f32_e32 v207, v245, v244
	v_add_f32_e32 v206, v246, v206
	v_add_f32_e32 v207, v248, v207
	v_add_f32_e32 v206, v247, v206
	v_add_f32_e32 v207, v249, v207
	v_add_f32_e32 v204, v205, v204
	v_add_f32_e32 v204, v204, v206
	v_add_f32_e32 v204, v204, v207
	ds_swizzle_b32 v205, v204 offset:swizzle(SWAP,1)
	s_waitcnt lgkmcnt(0)
	v_add_f32_e32 v204, v204, v205
	ds_swizzle_b32 v205, v204 offset:swizzle(SWAP,2)
	s_waitcnt lgkmcnt(0)
	v_add_f32_e32 v204, v204, v205
	ds_swizzle_b32 v205, v204 offset:swizzle(SWAP,4)
	s_waitcnt lgkmcnt(0)
	v_add_f32_e32 v204, v204, v205
	ds_swizzle_b32 v205, v204 offset:swizzle(SWAP,8)
	s_waitcnt lgkmcnt(0)
	v_add_f32_e32 v204, v204, v205
	ds_swizzle_b32 v205, v204 offset:swizzle(SWAP,16)
	s_waitcnt lgkmcnt(0)
	v_add_f32_e32 v204, v204, v205
	v_mov_b32_e32 v205, v204
	s_nop 1
	v_permlane32_swap_b32_e32 v204, v205
	v_add_f32_e32 v204, v204, v205
	v_mov_b32_e32 v205, 0x358637bd
	v_fmamk_f32 v204, v204, 0x3a800000, v205
	v_rsq_f32_e32 v204, v204
	s_nop 0
	s_waitcnt vmcnt(20)
; __device__ __forceinline__ unsigned pk2(float lo, float hi) { const g_f32x2 f = {lo, hi}; return __builtin_bit_cast(unsigned, __builtin_convertvector(f, g_bf16x2)); }
; __device__ __forceinline__ void p_norm(const float* hlat, const float* hctx, const float* g, const float* modl, int sh_off, int sc_off, bf16_t* A, int M,
;                                        const float* part, const float* cgate, float* hcout) {
;     ...
;     while (row < M) {
;         const int nrow = row + stride;
;         if (nrow < M) PN_LOAD(nv, nrow);
;         const int r = row < NLAT ? (row >> 11) : 16;
;         float ss = 0.f;
; #pragma unroll
;         for (int i = 0; i < 4; ++i) {
;             if (part != nullptr && row >= NLAT) {
;                 const size_t po = (size_t)(row - NLAT) * 1024 + i * 256 + lane * 4;
;                 const float4 p0 = *(const float4*)(part + po), p1 = *(const float4*)(part + (size_t)4096 * 1024 + po), cg = *(const float4*)(cgate + i * 256 + lane * 4);
;                 v[i].x += cg.x * (p0.x + p1.x); v[i].y += cg.y * (p0.y + p1.y); v[i].z += cg.z * (p0.z + p1.z); v[i].w += cg.w * (p0.w + p1.w);
;                 *(float4*)(hcout + po) = v[i];
;             }
;             ss += v[i].x * v[i].x + v[i].y * v[i].y + v[i].z * v[i].z + v[i].w * v[i].w; }
;         ss = wave_sum(ss);
;         const float rstd = rsqrtf(ss * (1.0f / 1024.0f) + EPS);
;         const float* mr = modl + (size_t)r * 6144;
; #pragma unroll
;         for (int i = 0; i < 4; ++i) {
;             const int k = i * 256 + lane * 4;
;             const float4 gg = *(const float4*)(g + k), scv = *(const float4*)(mr + sc_off + k), shv = *(const float4*)(mr + sh_off + k);
;             const float o0 = v[i].x * rstd * gg.x * (1.0f + scv.x) + shv.x, o1 = v[i].y * rstd * gg.y * (1.0f + scv.y) + shv.y;
;             const float o2 = v[i].z * rstd * gg.z * (1.0f + scv.z) + shv.z, o3 = v[i].w * rstd * gg.w * (1.0f + scv.w) + shv.w;
;             uint2 w; w.x = pk2(o0, o1); w.y = pk2(o2, o3);
;             *(uint2*)(A + (size_t)row * 1024 + k) = w;
;         }
; #pragma unroll
;         for (int i = 0; i < 4; ++i) v[i] = nv[i];
;         row = nrow;
	v_pk_mul_f32 v[112:113], v[112:113], v[204:205] op_sel_hi:[1,0]
	v_pk_mul_f32 v[114:115], v[114:115], v[204:205] op_sel_hi:[1,0]
	v_pk_mul_f32 v[112:113], v[156:157], v[112:113]
	v_pk_mul_f32 v[114:115], v[158:159], v[114:115]
	v_pk_add_f32 v[242:243], v[172:173], 1.0 op_sel_hi:[1,0]
	v_pk_add_f32 v[244:245], v[174:175], 1.0 op_sel_hi:[1,0]
	v_pk_fma_f32 v[112:113], v[242:243], v[112:113], v[188:189]
	v_pk_fma_f32 v[114:115], v[244:245], v[114:115], v[190:191]
	v_cvt_pk_bf16_f32 v112, v112, v113
	v_cvt_pk_bf16_f32 v113, v114, v115
	global_store_dwordx2 v146, v[112:113], s[66:67]
	v_pk_mul_f32 v[116:117], v[116:117], v[204:205] op_sel_hi:[1,0]
	v_pk_mul_f32 v[118:119], v[118:119], v[204:205] op_sel_hi:[1,0]
	v_pk_mul_f32 v[116:117], v[160:161], v[116:117]
	v_pk_mul_f32 v[118:119], v[162:163], v[118:119]
	v_pk_add_f32 v[242:243], v[176:177], 1.0 op_sel_hi:[1,0]
	v_pk_add_f32 v[244:245], v[178:179], 1.0 op_sel_hi:[1,0]
	v_pk_fma_f32 v[116:117], v[242:243], v[116:117], v[192:193]
	v_pk_fma_f32 v[118:119], v[244:245], v[118:119], v[194:195]
	v_cvt_pk_bf16_f32 v116, v116, v117
	v_cvt_pk_bf16_f32 v117, v118, v119
	global_store_dwordx2 v146, v[116:117], s[66:67] offset:512
	v_pk_mul_f32 v[120:121], v[120:121], v[204:205] op_sel_hi:[1,0]
	v_pk_mul_f32 v[122:123], v[122:123], v[204:205] op_sel_hi:[1,0]
	v_pk_mul_f32 v[120:121], v[164:165], v[120:121]
	v_pk_mul_f32 v[122:123], v[166:167], v[122:123]
	v_pk_add_f32 v[242:243], v[180:181], 1.0 op_sel_hi:[1,0]
	v_pk_add_f32 v[244:245], v[182:183], 1.0 op_sel_hi:[1,0]
	v_pk_fma_f32 v[120:121], v[242:243], v[120:121], v[196:197]
	v_pk_fma_f32 v[122:123], v[244:245], v[122:123], v[198:199]
	v_cvt_pk_bf16_f32 v120, v120, v121
	v_cvt_pk_bf16_f32 v121, v122, v123
	global_store_dwordx2 v146, v[120:121], s[66:67] offset:1024
	v_pk_mul_f32 v[124:125], v[124:125], v[204:205] op_sel_hi:[1,0]
	v_pk_mul_f32 v[126:127], v[126:127], v[204:205] op_sel_hi:[1,0]
	v_pk_mul_f32 v[124:125], v[168:169], v[124:125]
	v_pk_mul_f32 v[126:127], v[170:171], v[126:127]
	v_pk_add_f32 v[242:243], v[184:185], 1.0 op_sel_hi:[1,0]
	v_pk_add_f32 v[244:245], v[186:187], 1.0 op_sel_hi:[1,0]
	v_pk_fma_f32 v[124:125], v[242:243], v[124:125], v[200:201]
	v_pk_fma_f32 v[126:127], v[244:245], v[126:127], v[202:203]
	v_cvt_pk_bf16_f32 v124, v124, v125
	v_cvt_pk_bf16_f32 v125, v126, v127
	global_store_dwordx2 v146, v[124:125], s[66:67] offset:1536
	v_add_u32_e32 v146, 0x400000, v146
	global_load_dwordx4 v[172:175], v148, s[98:99]
	global_load_dwordx4 v[176:179], v148, s[98:99] offset:1024
	global_load_dwordx4 v[180:183], v148, s[98:99] offset:2048
	global_load_dwordx4 v[184:187], v148, s[98:99] offset:3072
	global_load_dwordx4 v[188:191], v148, s[50:51]
	global_load_dwordx4 v[192:195], v148, s[50:51] offset:1024
	global_load_dwordx4 v[196:199], v148, s[50:51] offset:2048
	global_load_dwordx4 v[200:203], v148, s[50:51] offset:3072
	v_add_u32_e32 v148, 0x6000, v148
	global_load_dwordx4 v[112:115], v144, s[46:47]
	global_load_dwordx4 v[116:119], v144, s[46:47] offset:1024
	global_load_dwordx4 v[120:123], v144, s[46:47] offset:2048
	global_load_dwordx4 v[124:127], v144, s[46:47] offset:3072
	v_add_u32_e32 v144, 0x800000, v144
	v_pk_mul_f32 v[242:243], v[128:129], v[128:129]
	v_pk_mul_f32 v[244:245], v[132:133], v[132:133]
	v_pk_mul_f32 v[246:247], v[130:131], v[130:131]
	v_pk_mul_f32 v[248:249], v[134:135], v[134:135]
	v_add_f32_e32 v204, v245, v244
	v_add_f32_e32 v205, v243, v242
	v_add_f32_e32 v204, v248, v204
	v_add_f32_e32 v205, v246, v205
	v_add_f32_e32 v204, v249, v204
	v_add_f32_e32 v205, v247, v205
	v_pk_mul_f32 v[242:243], v[136:137], v[136:137]
	v_pk_mul_f32 v[244:245], v[140:141], v[140:141]
	v_pk_mul_f32 v[246:247], v[138:139], v[138:139]
	v_pk_mul_f32 v[248:249], v[142:143], v[142:143]
	v_add_f32_e32 v206, v243, v242
	v_add_f32_e32 v207, v245, v244
	v_add_f32_e32 v206, v246, v206
	v_add_f32_e32 v207, v248, v207
	v_add_f32_e32 v206, v247, v206
	v_add_f32_e32 v207, v249, v207
	v_add_f32_e32 v204, v205, v204
	v_add_f32_e32 v204, v204, v206
	v_add_f32_e32 v204, v204, v207
	ds_swizzle_b32 v205, v204 offset:swizzle(SWAP,1)
	s_waitcnt lgkmcnt(0)
	v_add_f32_e32 v204, v204, v205
	ds_swizzle_b32 v205, v204 offset:swizzle(SWAP,2)
	s_waitcnt lgkmcnt(0)
	v_add_f32_e32 v204, v204, v205
	ds_swizzle_b32 v205, v204 offset:swizzle(SWAP,4)
	s_waitcnt lgkmcnt(0)
	v_add_f32_e32 v204, v204, v205
	ds_swizzle_b32 v205, v204 offset:swizzle(SWAP,8)
	s_waitcnt lgkmcnt(0)
	v_add_f32_e32 v204, v204, v205
	ds_swizzle_b32 v205, v204 offset:swizzle(SWAP,16)
	s_waitcnt lgkmcnt(0)
	v_add_f32_e32 v204, v204, v205
	v_mov_b32_e32 v205, v204
	s_nop 1
	v_permlane32_swap_b32_e32 v204, v205
	v_add_f32_e32 v204, v204, v205
	v_mov_b32_e32 v205, 0x358637bd
	v_fmamk_f32 v204, v204, 0x3a800000, v205
	v_rsq_f32_e32 v204, v204
	s_nop 0
	s_waitcnt vmcnt(20)
; __device__ __forceinline__ unsigned pk2(float lo, float hi) { const g_f32x2 f = {lo, hi}; return __builtin_bit_cast(unsigned, __builtin_convertvector(f, g_bf16x2)); }
; __device__ __forceinline__ void p_norm(const float* hlat, const float* hctx, const float* g, const float* modl, int sh_off, int sc_off, bf16_t* A, int M,
;                                        const float* part, const float* cgate, float* hcout) {
;     ...
;     while (row < M) {
;         const int nrow = row + stride;
;         if (nrow < M) PN_LOAD(nv, nrow);
;         const int r = row < NLAT ? (row >> 11) : 16;
;         float ss = 0.f;
; #pragma unroll
;         for (int i = 0; i < 4; ++i) {
;             if (part != nullptr && row >= NLAT) {
;                 const size_t po = (size_t)(row - NLAT) * 1024 + i * 256 + lane * 4;
;                 const float4 p0 = *(const float4*)(part + po), p1 = *(const float4*)(part + (size_t)4096 * 1024 + po), cg = *(const float4*)(cgate + i * 256 + lane * 4);
;                 v[i].x += cg.x * (p0.x + p1.x); v[i].y += cg.y * (p0.y + p1.y); v[i].z += cg.z * (p0.z + p1.z); v[i].w += cg.w * (p0.w + p1.w);
;                 *(float4*)(hcout + po) = v[i];
;             }
;             ss += v[i].x * v[i].x + v[i].y * v[i].y + v[i].z * v[i].z + v[i].w * v[i].w; }
;         ss = wave_sum(ss);
;         const float rstd = rsqrtf(ss * (1.0f / 1024.0f) + EPS);
;         const float* mr = modl + (size_t)r * 6144;
; #pragma unroll
;         for (int i = 0; i < 4; ++i) {
;             const int k = i * 256 + lane * 4;
;             const float4 gg = *(const float4*)(g + k), scv = *(const float4*)(mr + sc_off + k), shv = *(const float4*)(mr + sh_off + k);
;             const float o0 = v[i].x * rstd * gg.x * (1.0f + scv.x) + shv.x, o1 = v[i].y * rstd * gg.y * (1.0f + scv.y) + shv.y;
;             const float o2 = v[i].z * rstd * gg.z * (1.0f + scv.z) + shv.z, o3 = v[i].w * rstd * gg.w * (1.0f + scv.w) + shv.w;
;             uint2 w; w.x = pk2(o0, o1); w.y = pk2(o2, o3);
;             *(uint2*)(A + (size_t)row * 1024 + k) = w;
;         }
; #pragma unroll
;         for (int i = 0; i < 4; ++i) v[i] = nv[i];
;         row = nrow;
	v_pk_mul_f32 v[128:129], v[128:129], v[204:205] op_sel_hi:[1,0]
	v_pk_mul_f32 v[130:131], v[130:131], v[204:205] op_sel_hi:[1,0]
	v_pk_mul_f32 v[128:129], v[156:157], v[128:129]
	v_pk_mul_f32 v[130:131], v[158:159], v[130:131]
	v_pk_add_f32 v[242:243], v[34:35], 1.0 op_sel_hi:[1,0]
	v_pk_add_f32 v[244:245], v[36:37], 1.0 op_sel_hi:[1,0]
	v_pk_fma_f32 v[128:129], v[242:243], v[128:129], v[224:225]
	v_pk_fma_f32 v[130:131], v[244:245], v[130:131], v[226:227]
	v_cvt_pk_bf16_f32 v128, v128, v129
	v_cvt_pk_bf16_f32 v129, v130, v131
	global_store_dwordx2 v146, v[128:129], s[66:67]
	v_pk_mul_f32 v[132:133], v[132:133], v[204:205] op_sel_hi:[1,0]
	v_pk_mul_f32 v[134:135], v[134:135], v[204:205] op_sel_hi:[1,0]
	v_pk_mul_f32 v[132:133], v[160:161], v[132:133]
	v_pk_mul_f32 v[134:135], v[162:163], v[134:135]
	v_pk_add_f32 v[242:243], v[38:39], 1.0 op_sel_hi:[1,0]
	v_pk_add_f32 v[244:245], v[40:41], 1.0 op_sel_hi:[1,0]
	v_pk_fma_f32 v[132:133], v[242:243], v[132:133], v[228:229]
	v_pk_fma_f32 v[134:135], v[244:245], v[134:135], v[230:231]
	v_cvt_pk_bf16_f32 v132, v132, v133
	v_cvt_pk_bf16_f32 v133, v134, v135
	global_store_dwordx2 v146, v[132:133], s[66:67] offset:512
	v_pk_mul_f32 v[136:137], v[136:137], v[204:205] op_sel_hi:[1,0]
	v_pk_mul_f32 v[138:139], v[138:139], v[204:205] op_sel_hi:[1,0]
	v_pk_mul_f32 v[136:137], v[164:165], v[136:137]
	v_pk_mul_f32 v[138:139], v[166:167], v[138:139]
	v_pk_add_f32 v[242:243], v[42:43], 1.0 op_sel_hi:[1,0]
	v_pk_add_f32 v[244:245], v[44:45], 1.0 op_sel_hi:[1,0]
	v_pk_fma_f32 v[136:137], v[242:243], v[136:137], v[232:233]
	v_pk_fma_f32 v[138:139], v[244:245], v[138:139], v[234:235]
	v_cvt_pk_bf16_f32 v136, v136, v137
	v_cvt_pk_bf16_f32 v137, v138, v139
	global_store_dwordx2 v146, v[136:137], s[66:67] offset:1024
	v_pk_mul_f32 v[140:141], v[140:141], v[204:205] op_sel_hi:[1,0]
	v_pk_mul_f32 v[142:143], v[142:143], v[204:205] op_sel_hi:[1,0]
	v_pk_mul_f32 v[140:141], v[168:169], v[140:141]
	v_pk_mul_f32 v[142:143], v[170:171], v[142:143]
	v_pk_add_f32 v[242:243], v[46:47], 1.0 op_sel_hi:[1,0]
	v_pk_add_f32 v[244:245], v[48:49], 1.0 op_sel_hi:[1,0]
	v_pk_fma_f32 v[140:141], v[242:243], v[140:141], v[236:237]
	v_pk_fma_f32 v[142:143], v[244:245], v[142:143], v[238:239]
	v_cvt_pk_bf16_f32 v140, v140, v141
	v_cvt_pk_bf16_f32 v141, v142, v143
	global_store_dwordx2 v146, v[140:141], s[66:67] offset:1536
	v_add_u32_e32 v146, 0x400000, v146
	global_load_dwordx4 v[34:37], v148, s[98:99]
	global_load_dwordx4 v[38:41], v148, s[98:99] offset:1024
	global_load_dwordx4 v[42:45], v148, s[98:99] offset:2048
	global_load_dwordx4 v[46:49], v148, s[98:99] offset:3072
	global_load_dwordx4 v[224:227], v148, s[50:51]
	global_load_dwordx4 v[228:231], v148, s[50:51] offset:1024
	global_load_dwordx4 v[232:235], v148, s[50:51] offset:2048
	global_load_dwordx4 v[236:239], v148, s[50:51] offset:3072
	v_add_u32_e32 v148, 0x6000, v148
	global_load_dwordx4 v[128:131], v144, s[46:47]
	global_load_dwordx4 v[132:135], v144, s[46:47] offset:1024
	global_load_dwordx4 v[136:139], v144, s[46:47] offset:2048
	global_load_dwordx4 v[140:143], v144, s[46:47] offset:3072
	v_add_u32_e32 v144, 0x800000, v144
	v_pk_mul_f32 v[242:243], v[80:81], v[80:81]
	v_pk_mul_f32 v[244:245], v[84:85], v[84:85]
	v_pk_mul_f32 v[246:247], v[82:83], v[82:83]
	v_pk_mul_f32 v[248:249], v[86:87], v[86:87]
	v_add_f32_e32 v204, v245, v244
	v_add_f32_e32 v205, v243, v242
	v_add_f32_e32 v204, v248, v204
	v_add_f32_e32 v205, v246, v205
	v_add_f32_e32 v204, v249, v204
	v_add_f32_e32 v205, v247, v205
	v_pk_mul_f32 v[242:243], v[88:89], v[88:89]
	v_pk_mul_f32 v[244:245], v[92:93], v[92:93]
	v_pk_mul_f32 v[246:247], v[90:91], v[90:91]
	v_pk_mul_f32 v[248:249], v[94:95], v[94:95]
	v_add_f32_e32 v206, v243, v242
	v_add_f32_e32 v207, v245, v244
	v_add_f32_e32 v206, v246, v206
	v_add_f32_e32 v207, v248, v207
	v_add_f32_e32 v206, v247, v206
	v_add_f32_e32 v207, v249, v207
	v_add_f32_e32 v204, v205, v204
	v_add_f32_e32 v204, v204, v206
	v_add_f32_e32 v204, v204, v207
	ds_swizzle_b32 v205, v204 offset:swizzle(SWAP,1)
	s_waitcnt lgkmcnt(0)
	v_add_f32_e32 v204, v204, v205
	ds_swizzle_b32 v205, v204 offset:swizzle(SWAP,2)
	s_waitcnt lgkmcnt(0)
	v_add_f32_e32 v204, v204, v205
	ds_swizzle_b32 v205, v204 offset:swizzle(SWAP,4)
	s_waitcnt lgkmcnt(0)
	v_add_f32_e32 v204, v204, v205
	ds_swizzle_b32 v205, v204 offset:swizzle(SWAP,8)
	s_waitcnt lgkmcnt(0)
	v_add_f32_e32 v204, v204, v205
	ds_swizzle_b32 v205, v204 offset:swizzle(SWAP,16)
	s_waitcnt lgkmcnt(0)
	v_add_f32_e32 v204, v204, v205
	v_mov_b32_e32 v205, v204
	s_nop 1
	v_permlane32_swap_b32_e32 v204, v205
	v_add_f32_e32 v204, v204, v205
	v_mov_b32_e32 v205, 0x358637bd
	v_fmamk_f32 v204, v204, 0x3a800000, v205
	v_rsq_f32_e32 v204, v204
	s_nop 0
	s_waitcnt vmcnt(20)
; __device__ __forceinline__ unsigned pk2(float lo, float hi) { const g_f32x2 f = {lo, hi}; return __builtin_bit_cast(unsigned, __builtin_convertvector(f, g_bf16x2)); }
; __device__ __forceinline__ void p_norm(const float* hlat, const float* hctx, const float* g, const float* modl, int sh_off, int sc_off, bf16_t* A, int M,
;                                        const float* part, const float* cgate, float* hcout) {
;     ...
;     while (row < M) {
;         const int nrow = row + stride;
;         if (nrow < M) PN_LOAD(nv, nrow);
;         const int r = row < NLAT ? (row >> 11) : 16;
;         float ss = 0.f;
; #pragma unroll
;         for (int i = 0; i < 4; ++i) {
;             if (part != nullptr && row >= NLAT) {
;                 const size_t po = (size_t)(row - NLAT) * 1024 + i * 256 + lane * 4;
;                 const float4 p0 = *(const float4*)(part + po), p1 = *(const float4*)(part + (size_t)4096 * 1024 + po), cg = *(const float4*)(cgate + i * 256 + lane * 4);
;                 v[i].x += cg.x * (p0.x + p1.x); v[i].y += cg.y * (p0.y + p1.y); v[i].z += cg.z * (p0.z + p1.z); v[i].w += cg.w * (p0.w + p1.w);
;                 *(float4*)(hcout + po) = v[i];
;             }
;             ss += v[i].x * v[i].x + v[i].y * v[i].y + v[i].z * v[i].z + v[i].w * v[i].w; }
;         ss = wave_sum(ss);
;         const float rstd = rsqrtf(ss * (1.0f / 1024.0f) + EPS);
;         const float* mr = modl + (size_t)r * 6144;
; #pragma unroll
;         for (int i = 0; i < 4; ++i) {
;             const int k = i * 256 + lane * 4;
;             const float4 gg = *(const float4*)(g + k), scv = *(const float4*)(mr + sc_off + k), shv = *(const float4*)(mr + sh_off + k);
;             const float o0 = v[i].x * rstd * gg.x * (1.0f + scv.x) + shv.x, o1 = v[i].y * rstd * gg.y * (1.0f + scv.y) + shv.y;
;             const float o2 = v[i].z * rstd * gg.z * (1.0f + scv.z) + shv.z, o3 = v[i].w * rstd * gg.w * (1.0f + scv.w) + shv.w;
;             uint2 w; w.x = pk2(o0, o1); w.y = pk2(o2, o3);
;             *(uint2*)(A + (size_t)row * 1024 + k) = w;
;         }
; #pragma unroll
;         for (int i = 0; i < 4; ++i) v[i] = nv[i];
;         row = nrow;
	v_pk_mul_f32 v[80:81], v[80:81], v[204:205] op_sel_hi:[1,0]
	v_pk_mul_f32 v[82:83], v[82:83], v[204:205] op_sel_hi:[1,0]
	v_pk_mul_f32 v[80:81], v[156:157], v[80:81]
	v_pk_mul_f32 v[82:83], v[158:159], v[82:83]
	v_pk_add_f32 v[242:243], v[172:173], 1.0 op_sel_hi:[1,0]
	v_pk_add_f32 v[244:245], v[174:175], 1.0 op_sel_hi:[1,0]
	v_pk_fma_f32 v[80:81], v[242:243], v[80:81], v[188:189]
	v_pk_fma_f32 v[82:83], v[244:245], v[82:83], v[190:191]
	v_cvt_pk_bf16_f32 v80, v80, v81
	v_cvt_pk_bf16_f32 v81, v82, v83
	global_store_dwordx2 v146, v[80:81], s[66:67]
	v_pk_mul_f32 v[84:85], v[84:85], v[204:205] op_sel_hi:[1,0]
	v_pk_mul_f32 v[86:87], v[86:87], v[204:205] op_sel_hi:[1,0]
	v_pk_mul_f32 v[84:85], v[160:161], v[84:85]
	v_pk_mul_f32 v[86:87], v[162:163], v[86:87]
	v_pk_add_f32 v[242:243], v[176:177], 1.0 op_sel_hi:[1,0]
	v_pk_add_f32 v[244:245], v[178:179], 1.0 op_sel_hi:[1,0]
	v_pk_fma_f32 v[84:85], v[242:243], v[84:85], v[192:193]
	v_pk_fma_f32 v[86:87], v[244:245], v[86:87], v[194:195]
	v_cvt_pk_bf16_f32 v84, v84, v85
	v_cvt_pk_bf16_f32 v85, v86, v87
	global_store_dwordx2 v146, v[84:85], s[66:67] offset:512
	v_pk_mul_f32 v[88:89], v[88:89], v[204:205] op_sel_hi:[1,0]
	v_pk_mul_f32 v[90:91], v[90:91], v[204:205] op_sel_hi:[1,0]
	v_pk_mul_f32 v[88:89], v[164:165], v[88:89]
	v_pk_mul_f32 v[90:91], v[166:167], v[90:91]
	v_pk_add_f32 v[242:243], v[180:181], 1.0 op_sel_hi:[1,0]
	v_pk_add_f32 v[244:245], v[182:183], 1.0 op_sel_hi:[1,0]
	v_pk_fma_f32 v[88:89], v[242:243], v[88:89], v[196:197]
	v_pk_fma_f32 v[90:91], v[244:245], v[90:91], v[198:199]
	v_cvt_pk_bf16_f32 v88, v88, v89
	v_cvt_pk_bf16_f32 v89, v90, v91
	global_store_dwordx2 v146, v[88:89], s[66:67] offset:1024
	v_pk_mul_f32 v[92:93], v[92:93], v[204:205] op_sel_hi:[1,0]
	v_pk_mul_f32 v[94:95], v[94:95], v[204:205] op_sel_hi:[1,0]
	v_pk_mul_f32 v[92:93], v[168:169], v[92:93]
	v_pk_mul_f32 v[94:95], v[170:171], v[94:95]
	v_pk_add_f32 v[242:243], v[184:185], 1.0 op_sel_hi:[1,0]
	v_pk_add_f32 v[244:245], v[186:187], 1.0 op_sel_hi:[1,0]
	v_pk_fma_f32 v[92:93], v[242:243], v[92:93], v[200:201]
	v_pk_fma_f32 v[94:95], v[244:245], v[94:95], v[202:203]
	v_cvt_pk_bf16_f32 v92, v92, v93
	v_cvt_pk_bf16_f32 v93, v94, v95
	global_store_dwordx2 v146, v[92:93], s[66:67] offset:1536
	v_add_u32_e32 v146, 0x400000, v146
	global_load_dwordx4 v[172:175], v148, s[98:99]
	global_load_dwordx4 v[176:179], v148, s[98:99] offset:1024
	global_load_dwordx4 v[180:183], v148, s[98:99] offset:2048
	global_load_dwordx4 v[184:187], v148, s[98:99] offset:3072
	global_load_dwordx4 v[188:191], v148, s[50:51]
	global_load_dwordx4 v[192:195], v148, s[50:51] offset:1024
	global_load_dwordx4 v[196:199], v148, s[50:51] offset:2048
	global_load_dwordx4 v[200:203], v148, s[50:51] offset:3072
	v_add_u32_e32 v148, 0x6000, v148
	v_pk_mul_f32 v[242:243], v[96:97], v[96:97]
	v_pk_mul_f32 v[244:245], v[100:101], v[100:101]
	v_pk_mul_f32 v[246:247], v[98:99], v[98:99]
	v_pk_mul_f32 v[248:249], v[102:103], v[102:103]
	v_add_f32_e32 v204, v245, v244
	v_add_f32_e32 v205, v243, v242
	v_add_f32_e32 v204, v248, v204
	v_add_f32_e32 v205, v246, v205
	v_add_f32_e32 v204, v249, v204
	v_add_f32_e32 v205, v247, v205
	v_pk_mul_f32 v[242:243], v[104:105], v[104:105]
	v_pk_mul_f32 v[244:245], v[108:109], v[108:109]
	v_pk_mul_f32 v[246:247], v[106:107], v[106:107]
	v_pk_mul_f32 v[248:249], v[110:111], v[110:111]
	v_add_f32_e32 v206, v243, v242
	v_add_f32_e32 v207, v245, v244
	v_add_f32_e32 v206, v246, v206
	v_add_f32_e32 v207, v248, v207
	v_add_f32_e32 v206, v247, v206
	v_add_f32_e32 v207, v249, v207
	v_add_f32_e32 v204, v205, v204
	v_add_f32_e32 v204, v204, v206
	v_add_f32_e32 v204, v204, v207
	ds_swizzle_b32 v205, v204 offset:swizzle(SWAP,1)
	s_waitcnt lgkmcnt(0)
	v_add_f32_e32 v204, v204, v205
	ds_swizzle_b32 v205, v204 offset:swizzle(SWAP,2)
	s_waitcnt lgkmcnt(0)
	v_add_f32_e32 v204, v204, v205
	ds_swizzle_b32 v205, v204 offset:swizzle(SWAP,4)
	s_waitcnt lgkmcnt(0)
	v_add_f32_e32 v204, v204, v205
	ds_swizzle_b32 v205, v204 offset:swizzle(SWAP,8)
	s_waitcnt lgkmcnt(0)
	v_add_f32_e32 v204, v204, v205
	ds_swizzle_b32 v205, v204 offset:swizzle(SWAP,16)
	s_waitcnt lgkmcnt(0)
	v_add_f32_e32 v204, v204, v205
	v_mov_b32_e32 v205, v204
	s_nop 1
	v_permlane32_swap_b32_e32 v204, v205
	v_add_f32_e32 v204, v204, v205
	v_mov_b32_e32 v205, 0x358637bd
	v_fmamk_f32 v204, v204, 0x3a800000, v205
	v_rsq_f32_e32 v204, v204
	s_nop 0
	s_waitcnt vmcnt(16)
; __device__ __forceinline__ unsigned pk2(float lo, float hi) { const g_f32x2 f = {lo, hi}; return __builtin_bit_cast(unsigned, __builtin_convertvector(f, g_bf16x2)); }
; __device__ __forceinline__ void p_norm(const float* hlat, const float* hctx, const float* g, const float* modl, int sh_off, int sc_off, bf16_t* A, int M,
;                                        const float* part, const float* cgate, float* hcout) {
;     ...
;     while (row < M) {
;         const int nrow = row + stride;
;         if (nrow < M) PN_LOAD(nv, nrow);
;         const int r = row < NLAT ? (row >> 11) : 16;
;         float ss = 0.f;
; #pragma unroll
;         for (int i = 0; i < 4; ++i) {
;             if (part != nullptr && row >= NLAT) {
;                 const size_t po = (size_t)(row - NLAT) * 1024 + i * 256 + lane * 4;
;                 const float4 p0 = *(const float4*)(part + po), p1 = *(const float4*)(part + (size_t)4096 * 1024 + po), cg = *(const float4*)(cgate + i * 256 + lane * 4);
;                 v[i].x += cg.x * (p0.x + p1.x); v[i].y += cg.y * (p0.y + p1.y); v[i].z += cg.z * (p0.z + p1.z); v[i].w += cg.w * (p0.w + p1.w);
;                 *(float4*)(hcout + po) = v[i];
;             }
;             ss += v[i].x * v[i].x + v[i].y * v[i].y + v[i].z * v[i].z + v[i].w * v[i].w; }
;         ss = wave_sum(ss);
;         const float rstd = rsqrtf(ss * (1.0f / 1024.0f) + EPS);
;         const float* mr = modl + (size_t)r * 6144;
; #pragma unroll
;         for (int i = 0; i < 4; ++i) {
;             const int k = i * 256 + lane * 4;
;             const float4 gg = *(const float4*)(g + k), scv = *(const float4*)(mr + sc_off + k), shv = *(const float4*)(mr + sh_off + k);
;             const float o0 = v[i].x * rstd * gg.x * (1.0f + scv.x) + shv.x, o1 = v[i].y * rstd * gg.y * (1.0f + scv.y) + shv.y;
;             const float o2 = v[i].z * rstd * gg.z * (1.0f + scv.z) + shv.z, o3 = v[i].w * rstd * gg.w * (1.0f + scv.w) + shv.w;
;             uint2 w; w.x = pk2(o0, o1); w.y = pk2(o2, o3);
;             *(uint2*)(A + (size_t)row * 1024 + k) = w;
;         }
; #pragma unroll
;         for (int i = 0; i < 4; ++i) v[i] = nv[i];
;         row = nrow;
	v_pk_mul_f32 v[96:97], v[96:97], v[204:205] op_sel_hi:[1,0]
	v_pk_mul_f32 v[98:99], v[98:99], v[204:205] op_sel_hi:[1,0]
	v_pk_mul_f32 v[96:97], v[156:157], v[96:97]
	v_pk_mul_f32 v[98:99], v[158:159], v[98:99]
	v_pk_add_f32 v[242:243], v[34:35], 1.0 op_sel_hi:[1,0]
	v_pk_add_f32 v[244:245], v[36:37], 1.0 op_sel_hi:[1,0]
	v_pk_fma_f32 v[96:97], v[242:243], v[96:97], v[224:225]
	v_pk_fma_f32 v[98:99], v[244:245], v[98:99], v[226:227]
	v_cvt_pk_bf16_f32 v96, v96, v97
	v_cvt_pk_bf16_f32 v97, v98, v99
	global_store_dwordx2 v146, v[96:97], s[66:67]
	v_pk_mul_f32 v[100:101], v[100:101], v[204:205] op_sel_hi:[1,0]
	v_pk_mul_f32 v[102:103], v[102:103], v[204:205] op_sel_hi:[1,0]
	v_pk_mul_f32 v[100:101], v[160:161], v[100:101]
	v_pk_mul_f32 v[102:103], v[162:163], v[102:103]
	v_pk_add_f32 v[242:243], v[38:39], 1.0 op_sel_hi:[1,0]
	v_pk_add_f32 v[244:245], v[40:41], 1.0 op_sel_hi:[1,0]
	v_pk_fma_f32 v[100:101], v[242:243], v[100:101], v[228:229]
	v_pk_fma_f32 v[102:103], v[244:245], v[102:103], v[230:231]
	v_cvt_pk_bf16_f32 v100, v100, v101
	v_cvt_pk_bf16_f32 v101, v102, v103
	global_store_dwordx2 v146, v[100:101], s[66:67] offset:512
	v_pk_mul_f32 v[104:105], v[104:105], v[204:205] op_sel_hi:[1,0]
	v_pk_mul_f32 v[106:107], v[106:107], v[204:205] op_sel_hi:[1,0]
	v_pk_mul_f32 v[104:105], v[164:165], v[104:105]
	v_pk_mul_f32 v[106:107], v[166:167], v[106:107]
	v_pk_add_f32 v[242:243], v[42:43], 1.0 op_sel_hi:[1,0]
	v_pk_add_f32 v[244:245], v[44:45], 1.0 op_sel_hi:[1,0]
	v_pk_fma_f32 v[104:105], v[242:243], v[104:105], v[232:233]
	v_pk_fma_f32 v[106:107], v[244:245], v[106:107], v[234:235]
	v_cvt_pk_bf16_f32 v104, v104, v105
	v_cvt_pk_bf16_f32 v105, v106, v107
	global_store_dwordx2 v146, v[104:105], s[66:67] offset:1024
	v_pk_mul_f32 v[108:109], v[108:109], v[204:205] op_sel_hi:[1,0]
	v_pk_mul_f32 v[110:111], v[110:111], v[204:205] op_sel_hi:[1,0]
	v_pk_mul_f32 v[108:109], v[168:169], v[108:109]
	v_pk_mul_f32 v[110:111], v[170:171], v[110:111]
	v_pk_add_f32 v[242:243], v[46:47], 1.0 op_sel_hi:[1,0]
	v_pk_add_f32 v[244:245], v[48:49], 1.0 op_sel_hi:[1,0]
	v_pk_fma_f32 v[108:109], v[242:243], v[108:109], v[236:237]
	v_pk_fma_f32 v[110:111], v[244:245], v[110:111], v[238:239]
	v_cvt_pk_bf16_f32 v108, v108, v109
	v_cvt_pk_bf16_f32 v109, v110, v111
	global_store_dwordx2 v146, v[108:109], s[66:67] offset:1536
	v_add_u32_e32 v146, 0x400000, v146
	global_load_dwordx4 v[34:37], v148, s[98:99]
	global_load_dwordx4 v[38:41], v148, s[98:99] offset:1024
	global_load_dwordx4 v[42:45], v148, s[98:99] offset:2048
	global_load_dwordx4 v[46:49], v148, s[98:99] offset:3072
	global_load_dwordx4 v[224:227], v148, s[50:51]
	global_load_dwordx4 v[228:231], v148, s[50:51] offset:1024
	global_load_dwordx4 v[232:235], v148, s[50:51] offset:2048
	global_load_dwordx4 v[236:239], v148, s[50:51] offset:3072
	v_add_u32_e32 v148, 0x6000, v148
	v_pk_mul_f32 v[242:243], v[112:113], v[112:113]
	v_pk_mul_f32 v[244:245], v[116:117], v[116:117]
	v_pk_mul_f32 v[246:247], v[114:115], v[114:115]
	v_pk_mul_f32 v[248:249], v[118:119], v[118:119]
	v_add_f32_e32 v204, v245, v244
	v_add_f32_e32 v205, v243, v242
	v_add_f32_e32 v204, v248, v204
	v_add_f32_e32 v205, v246, v205
	v_add_f32_e32 v204, v249, v204
	v_add_f32_e32 v205, v247, v205
	v_pk_mul_f32 v[242:243], v[120:121], v[120:121]
	v_pk_mul_f32 v[244:245], v[124:125], v[124:125]
	v_pk_mul_f32 v[246:247], v[122:123], v[122:123]
	v_pk_mul_f32 v[248:249], v[126:127], v[126:127]
	v_add_f32_e32 v206, v243, v242
	v_add_f32_e32 v207, v245, v244
	v_add_f32_e32 v206, v246, v206
	v_add_f32_e32 v207, v248, v207
	v_add_f32_e32 v206, v247, v206
	v_add_f32_e32 v207, v249, v207
	v_add_f32_e32 v204, v205, v204
	v_add_f32_e32 v204, v204, v206
	v_add_f32_e32 v204, v204, v207
	ds_swizzle_b32 v205, v204 offset:swizzle(SWAP,1)
	s_waitcnt lgkmcnt(0)
	v_add_f32_e32 v204, v204, v205
	ds_swizzle_b32 v205, v204 offset:swizzle(SWAP,2)
	s_waitcnt lgkmcnt(0)
	v_add_f32_e32 v204, v204, v205
	ds_swizzle_b32 v205, v204 offset:swizzle(SWAP,4)
	s_waitcnt lgkmcnt(0)
	v_add_f32_e32 v204, v204, v205
	ds_swizzle_b32 v205, v204 offset:swizzle(SWAP,8)
	s_waitcnt lgkmcnt(0)
	v_add_f32_e32 v204, v204, v205
	ds_swizzle_b32 v205, v204 offset:swizzle(SWAP,16)
	s_waitcnt lgkmcnt(0)
	v_add_f32_e32 v204, v204, v205
	v_mov_b32_e32 v205, v204
	s_nop 1
	v_permlane32_swap_b32_e32 v204, v205
	v_add_f32_e32 v204, v204, v205
	v_mov_b32_e32 v205, 0x358637bd
	v_fmamk_f32 v204, v204, 0x3a800000, v205
	v_rsq_f32_e32 v204, v204
	s_nop 0
	s_waitcnt vmcnt(12)
; __device__ __forceinline__ unsigned pk2(float lo, float hi) { const g_f32x2 f = {lo, hi}; return __builtin_bit_cast(unsigned, __builtin_convertvector(f, g_bf16x2)); }
; __device__ __forceinline__ void p_norm(const float* hlat, const float* hctx, const float* g, const float* modl, int sh_off, int sc_off, bf16_t* A, int M,
;                                        const float* part, const float* cgate, float* hcout) {
;     ...
;     while (row < M) {
;         const int nrow = row + stride;
;         if (nrow < M) PN_LOAD(nv, nrow);
;         const int r = row < NLAT ? (row >> 11) : 16;
;         float ss = 0.f;
; #pragma unroll
;         for (int i = 0; i < 4; ++i) {
;             if (part != nullptr && row >= NLAT) {
;                 const size_t po = (size_t)(row - NLAT) * 1024 + i * 256 + lane * 4;
;                 const float4 p0 = *(const float4*)(part + po), p1 = *(const float4*)(part + (size_t)4096 * 1024 + po), cg = *(const float4*)(cgate + i * 256 + lane * 4);
;                 v[i].x += cg.x * (p0.x + p1.x); v[i].y += cg.y * (p0.y + p1.y); v[i].z += cg.z * (p0.z + p1.z); v[i].w += cg.w * (p0.w + p1.w);
;                 *(float4*)(hcout + po) = v[i];
;             }
;             ss += v[i].x * v[i].x + v[i].y * v[i].y + v[i].z * v[i].z + v[i].w * v[i].w; }
;         ss = wave_sum(ss);
;         const float rstd = rsqrtf(ss * (1.0f / 1024.0f) + EPS);
;         const float* mr = modl + (size_t)r * 6144;
; #pragma unroll
;         for (int i = 0; i < 4; ++i) {
;             const int k = i * 256 + lane * 4;
;             const float4 gg = *(const float4*)(g + k), scv = *(const float4*)(mr + sc_off + k), shv = *(const float4*)(mr + sh_off + k);
;             const float o0 = v[i].x * rstd * gg.x * (1.0f + scv.x) + shv.x, o1 = v[i].y * rstd * gg.y * (1.0f + scv.y) + shv.y;
;             const float o2 = v[i].z * rstd * gg.z * (1.0f + scv.z) + shv.z, o3 = v[i].w * rstd * gg.w * (1.0f + scv.w) + shv.w;
;             uint2 w; w.x = pk2(o0, o1); w.y = pk2(o2, o3);
;             *(uint2*)(A + (size_t)row * 1024 + k) = w;
;         }
; #pragma unroll
;         for (int i = 0; i < 4; ++i) v[i] = nv[i];
;         row = nrow;
	v_pk_mul_f32 v[112:113], v[112:113], v[204:205] op_sel_hi:[1,0]
	v_pk_mul_f32 v[114:115], v[114:115], v[204:205] op_sel_hi:[1,0]
	v_pk_mul_f32 v[112:113], v[156:157], v[112:113]
	v_pk_mul_f32 v[114:115], v[158:159], v[114:115]
	v_pk_add_f32 v[242:243], v[172:173], 1.0 op_sel_hi:[1,0]
	v_pk_add_f32 v[244:245], v[174:175], 1.0 op_sel_hi:[1,0]
	v_pk_fma_f32 v[112:113], v[242:243], v[112:113], v[188:189]
	v_pk_fma_f32 v[114:115], v[244:245], v[114:115], v[190:191]
	v_cvt_pk_bf16_f32 v112, v112, v113
	v_cvt_pk_bf16_f32 v113, v114, v115
	global_store_dwordx2 v146, v[112:113], s[66:67]
	v_pk_mul_f32 v[116:117], v[116:117], v[204:205] op_sel_hi:[1,0]
	v_pk_mul_f32 v[118:119], v[118:119], v[204:205] op_sel_hi:[1,0]
	v_pk_mul_f32 v[116:117], v[160:161], v[116:117]
	v_pk_mul_f32 v[118:119], v[162:163], v[118:119]
	v_pk_add_f32 v[242:243], v[176:177], 1.0 op_sel_hi:[1,0]
	v_pk_add_f32 v[244:245], v[178:179], 1.0 op_sel_hi:[1,0]
	v_pk_fma_f32 v[116:117], v[242:243], v[116:117], v[192:193]
	v_pk_fma_f32 v[118:119], v[244:245], v[118:119], v[194:195]
	v_cvt_pk_bf16_f32 v116, v116, v117
	v_cvt_pk_bf16_f32 v117, v118, v119
	global_store_dwordx2 v146, v[116:117], s[66:67] offset:512
	v_pk_mul_f32 v[120:121], v[120:121], v[204:205] op_sel_hi:[1,0]
	v_pk_mul_f32 v[122:123], v[122:123], v[204:205] op_sel_hi:[1,0]
	v_pk_mul_f32 v[120:121], v[164:165], v[120:121]
	v_pk_mul_f32 v[122:123], v[166:167], v[122:123]
	v_pk_add_f32 v[242:243], v[180:181], 1.0 op_sel_hi:[1,0]
	v_pk_add_f32 v[244:245], v[182:183], 1.0 op_sel_hi:[1,0]
	v_pk_fma_f32 v[120:121], v[242:243], v[120:121], v[196:197]
	v_pk_fma_f32 v[122:123], v[244:245], v[122:123], v[198:199]
	v_cvt_pk_bf16_f32 v120, v120, v121
	v_cvt_pk_bf16_f32 v121, v122, v123
	global_store_dwordx2 v146, v[120:121], s[66:67] offset:1024
	v_pk_mul_f32 v[124:125], v[124:125], v[204:205] op_sel_hi:[1,0]
	v_pk_mul_f32 v[126:127], v[126:127], v[204:205] op_sel_hi:[1,0]
	v_pk_mul_f32 v[124:125], v[168:169], v[124:125]
	v_pk_mul_f32 v[126:127], v[170:171], v[126:127]
	v_pk_add_f32 v[242:243], v[184:185], 1.0 op_sel_hi:[1,0]
	v_pk_add_f32 v[244:245], v[186:187], 1.0 op_sel_hi:[1,0]
	v_pk_fma_f32 v[124:125], v[242:243], v[124:125], v[200:201]
	v_pk_fma_f32 v[126:127], v[244:245], v[126:127], v[202:203]
	v_cvt_pk_bf16_f32 v124, v124, v125
	v_cvt_pk_bf16_f32 v125, v126, v127
	global_store_dwordx2 v146, v[124:125], s[66:67] offset:1536
	v_add_u32_e32 v146, 0x400000, v146
	v_pk_mul_f32 v[242:243], v[128:129], v[128:129]
	v_pk_mul_f32 v[244:245], v[132:133], v[132:133]
	v_pk_mul_f32 v[246:247], v[130:131], v[130:131]
	v_pk_mul_f32 v[248:249], v[134:135], v[134:135]
	v_add_f32_e32 v204, v245, v244
	v_add_f32_e32 v205, v243, v242
	v_add_f32_e32 v204, v248, v204
	v_add_f32_e32 v205, v246, v205
	v_add_f32_e32 v204, v249, v204
	v_add_f32_e32 v205, v247, v205
	v_pk_mul_f32 v[242:243], v[136:137], v[136:137]
	v_pk_mul_f32 v[244:245], v[140:141], v[140:141]
	v_pk_mul_f32 v[246:247], v[138:139], v[138:139]
	v_pk_mul_f32 v[248:249], v[142:143], v[142:143]
	v_add_f32_e32 v206, v243, v242
	v_add_f32_e32 v207, v245, v244
	v_add_f32_e32 v206, v246, v206
	v_add_f32_e32 v207, v248, v207
	v_add_f32_e32 v206, v247, v206
	v_add_f32_e32 v207, v249, v207
	v_add_f32_e32 v204, v205, v204
	v_add_f32_e32 v204, v204, v206
	v_add_f32_e32 v204, v204, v207
	ds_swizzle_b32 v205, v204 offset:swizzle(SWAP,1)
	s_waitcnt lgkmcnt(0)
	v_add_f32_e32 v204, v204, v205
	ds_swizzle_b32 v205, v204 offset:swizzle(SWAP,2)
	s_waitcnt lgkmcnt(0)
	v_add_f32_e32 v204, v204, v205
	ds_swizzle_b32 v205, v204 offset:swizzle(SWAP,4)
	s_waitcnt lgkmcnt(0)
	v_add_f32_e32 v204, v204, v205
	ds_swizzle_b32 v205, v204 offset:swizzle(SWAP,8)
	s_waitcnt lgkmcnt(0)
	v_add_f32_e32 v204, v204, v205
	ds_swizzle_b32 v205, v204 offset:swizzle(SWAP,16)
	s_waitcnt lgkmcnt(0)
	v_add_f32_e32 v204, v204, v205
	v_mov_b32_e32 v205, v204
	s_nop 1
	v_permlane32_swap_b32_e32 v204, v205
	v_add_f32_e32 v204, v204, v205
	v_mov_b32_e32 v205, 0x358637bd
	v_fmamk_f32 v204, v204, 0x3a800000, v205
	v_rsq_f32_e32 v204, v204
	s_nop 0
	s_waitcnt vmcnt(4)
	v_pk_mul_f32 v[128:129], v[128:129], v[204:205] op_sel_hi:[1,0]
	v_pk_mul_f32 v[130:131], v[130:131], v[204:205] op_sel_hi:[1,0]
	v_pk_mul_f32 v[128:129], v[156:157], v[128:129]
	v_pk_mul_f32 v[130:131], v[158:159], v[130:131]
	v_pk_add_f32 v[242:243], v[34:35], 1.0 op_sel_hi:[1,0]
	v_pk_add_f32 v[244:245], v[36:37], 1.0 op_sel_hi:[1,0]
	v_pk_fma_f32 v[128:129], v[242:243], v[128:129], v[224:225]
	v_pk_fma_f32 v[130:131], v[244:245], v[130:131], v[226:227]
	v_cvt_pk_bf16_f32 v128, v128, v129
	v_cvt_pk_bf16_f32 v129, v130, v131
	global_store_dwordx2 v146, v[128:129], s[66:67]
	v_pk_mul_f32 v[132:133], v[132:133], v[204:205] op_sel_hi:[1,0]
	v_pk_mul_f32 v[134:135], v[134:135], v[204:205] op_sel_hi:[1,0]
	v_pk_mul_f32 v[132:133], v[160:161], v[132:133]
	v_pk_mul_f32 v[134:135], v[162:163], v[134:135]
	v_pk_add_f32 v[242:243], v[38:39], 1.0 op_sel_hi:[1,0]
	v_pk_add_f32 v[244:245], v[40:41], 1.0 op_sel_hi:[1,0]
	v_pk_fma_f32 v[132:133], v[242:243], v[132:133], v[228:229]
	v_pk_fma_f32 v[134:135], v[244:245], v[134:135], v[230:231]
	v_cvt_pk_bf16_f32 v132, v132, v133
	v_cvt_pk_bf16_f32 v133, v134, v135
	global_store_dwordx2 v146, v[132:133], s[66:67] offset:512
	v_pk_mul_f32 v[136:137], v[136:137], v[204:205] op_sel_hi:[1,0]
	v_pk_mul_f32 v[138:139], v[138:139], v[204:205] op_sel_hi:[1,0]
	v_pk_mul_f32 v[136:137], v[164:165], v[136:137]
	v_pk_mul_f32 v[138:139], v[166:167], v[138:139]
	v_pk_add_f32 v[242:243], v[42:43], 1.0 op_sel_hi:[1,0]
	v_pk_add_f32 v[244:245], v[44:45], 1.0 op_sel_hi:[1,0]
	v_pk_fma_f32 v[136:137], v[242:243], v[136:137], v[232:233]
	v_pk_fma_f32 v[138:139], v[244:245], v[138:139], v[234:235]
	v_cvt_pk_bf16_f32 v136, v136, v137
	v_cvt_pk_bf16_f32 v137, v138, v139
	global_store_dwordx2 v146, v[136:137], s[66:67] offset:1024
	v_pk_mul_f32 v[140:141], v[140:141], v[204:205] op_sel_hi:[1,0]
	v_pk_mul_f32 v[142:143], v[142:143], v[204:205] op_sel_hi:[1,0]
	v_pk_mul_f32 v[140:141], v[168:169], v[140:141]
	v_pk_mul_f32 v[142:143], v[170:171], v[142:143]
	v_pk_add_f32 v[242:243], v[46:47], 1.0 op_sel_hi:[1,0]
	v_pk_add_f32 v[244:245], v[48:49], 1.0 op_sel_hi:[1,0]
	v_pk_fma_f32 v[140:141], v[242:243], v[140:141], v[236:237]
	v_pk_fma_f32 v[142:143], v[244:245], v[142:143], v[238:239]
	v_cvt_pk_bf16_f32 v140, v140, v141
	v_cvt_pk_bf16_f32 v141, v142, v143
	global_store_dwordx2 v146, v[140:141], s[66:67] offset:1536
	v_add_u32_e32 v146, 0x400000, v146
	v_add_u32_e32 v50, 0x8000, v50
	v_cmp_gt_i32_e32 vcc, s7, v50
	s_and_saveexec_b64 s[2:3], vcc
	s_cbranch_execz .LBB0_1050
; #define PN_LOAD(dst, rw) do { const float* s_ = (rw) < NLAT ? hlat + (size_t)(rw) * 1024 : hctx + (size_t)((rw) - NLAT) * 1024; \
;         _Pragma("unroll") for (int i = 0; i < 4; ++i) dst[i] = *(const float4*)(s_ + i * 256 + lane * 4); } while (0)
; __device__ __forceinline__ void p_norm(const float* hlat, const float* hctx, const float* g, const float* modl, int sh_off, int sc_off, bf16_t* A, int M,
;                                        const float* part, const float* cgate, float* hcout) {
;     ...
;     if (row < M) PN_LOAD(v, row);
;     while (row < M) {
;         const int nrow = row + stride;
;         if (nrow < M) PN_LOAD(nv, nrow);
;         const int r = row < NLAT ? (row >> 11) : 16;
;         float ss = 0.f;
; #pragma unroll
;         for (int i = 0; i < 4; ++i) {
;             if (part != nullptr && row >= NLAT) {
;                 const size_t po = (size_t)(row - NLAT) * 1024 + i * 256 + lane * 4;
;                 const float4 p0 = *(const float4*)(part + po), p1 = *(const float4*)(part + (size_t)4096 * 1024 + po), cg = *(const float4*)(cgate + i * 256 + lane * 4);
	v_readlane_b32 s8, v255, 39
	s_mov_b32 s6, 0x8000
	v_readlane_b32 s9, v255, 40
	v_add_u32_e32 v2, 0xffff8000, v50
	v_ashrrev_i32_e32 v51, 31, v50
	v_cmp_gt_i32_e32 vcc, s6, v50
	v_mov_b32_e32 v4, s9
	v_mov_b32_e32 v5, s43
	v_cndmask_b32_e32 v3, 0, v51, vcc
	v_cndmask_b32_e32 v2, v2, v50, vcc
	v_cndmask_b32_e32 v5, v4, v5, vcc
	v_mov_b32_e32 v4, s8
	v_mov_b32_e32 v7, s42
	v_cndmask_b32_e32 v4, v4, v7, vcc
	v_lshlrev_b64 v[2:3], 12, v[2:3]
	v_lshl_add_u64 v[2:3], v[4:5], 0, v[2:3]
	v_lshlrev_b32_e32 v4, 2, v6
	v_and_b32_e32 v34, 0xfc, v4
	v_lshlrev_b32_e32 v8, 2, v34
	v_mov_b32_e32 v9, v0
	v_lshl_add_u64 v[2:3], v[2:3], 0, v[8:9]
	global_load_dwordx4 v[30:33], v[2:3], off
	global_load_dwordx4 v[26:29], v[2:3], off offset:1024
	global_load_dwordx4 v[22:25], v[2:3], off offset:2048
	s_nop 0
	global_load_dwordx4 v[2:5], v[2:3], off offset:3072
	s_load_dwordx2 s[8:9], s[0:1], 0x38
	s_and_b64 s[10:11], s[18:19], exec
	v_readlane_b32 s10, v255, 47
	v_readlane_b32 s11, v255, 48
	s_cselect_b32 s17, 0, s71
	s_cselect_b32 s16, 0, s70
	s_lshl_b64 s[10:11], s[10:11], 2
	s_waitcnt lgkmcnt(0)
	s_add_u32 s8, s8, s10
	s_addc_u32 s9, s9, s11
	s_cmp_lg_u64 s[16:17], 0
	v_readlane_b32 s10, v255, 43
	s_cselect_b64 s[24:25], -1, 0
	s_add_u32 s26, s16, 0x1000000
	v_readlane_b32 s11, v255, 44
	s_addc_u32 s27, s17, 0
	v_lshlrev_b64 v[14:15], 11, v[50:51]
	v_lshl_add_u64 v[10:11], s[10:11], 0, v[8:9]
	s_mov_b64 s[10:11], 0x62000
	v_and_b32_e32 v6, 63, v6
	s_add_i32 s5, s5, s72
	v_lshl_add_u64 v[36:37], v[10:11], 0, s[10:11]
	v_lshl_add_u64 v[38:39], s[8:9], 0, v[8:9]
	v_or_b32_e32 v8, 0x100, v34
	v_or_b32_e32 v10, 0x200, v34
	v_or_b32_e32 v12, 0x300, v34
	v_lshl_or_b32 v14, v6, 3, v14
	v_add_u32_e32 v42, s5, v1
	s_mov_b64 s[20:21], 0
	v_lshl_add_u64 v[40:41], s[66:67], 0, v[14:15]
	v_ashrrev_i32_e32 v43, 31, v42
	v_lshlrev_b32_e32 v44, 2, v8
	v_lshlrev_b32_e32 v46, 2, v10
	v_lshlrev_b32_e32 v48, 2, v12
	s_branch .LBB0_1040

; #define PG8_LAS __attribute__((address_space(3)))
; __global__ void __launch_bounds__(512, 2) hybrid_fwd(Params P) {
;     extern __shared__ __attribute__((aligned(16))) unsigned char smem[];
;     cg::grid_group grid = cg::this_grid();
;     float* lf = (float*)smem;
;     PG8_LAS unsigned char* lds = (PG8_LAS unsigned char*)smem;
;     const int G = gridDim.x, bid = blockIdx.x;
;     float* mod = (float*)(PWS + WS_MOD);
;     float* hc = (float*)(PWS + WS_HC);
;     bf16_t* AO = (bf16_t*)(PWS + WS_AO);
;     bf16_t* U = (bf16_t*)(PWS + WS_U);
;     bf16_t* HID = (bf16_t*)(PWS + WS_HID);
;     unsigned* barw = (unsigned*)(PWS + WS_BAR);
	.amdhsa_kernel _Z10hybrid_fwd6Params
		.amdhsa_group_segment_fixed_size 0
		.amdhsa_private_segment_fixed_size 0
		.amdhsa_kernarg_size 504
		.amdhsa_user_sgpr_count 2
		.amdhsa_user_sgpr_dispatch_ptr 0
		.amdhsa_user_sgpr_queue_ptr 0
		.amdhsa_user_sgpr_kernarg_segment_ptr 1
		.amdhsa_user_sgpr_dispatch_id 0
		.amdhsa_user_sgpr_kernarg_preload_length 0
		.amdhsa_user_sgpr_kernarg_preload_offset 0
		.amdhsa_user_sgpr_private_segment_size 0
		.amdhsa_uses_dynamic_stack 0
		.amdhsa_enable_private_segment 0
		.amdhsa_system_sgpr_workgroup_id_x 1
		.amdhsa_system_sgpr_workgroup_id_y 0
		.amdhsa_system_sgpr_workgroup_id_z 0
		.amdhsa_system_sgpr_workgroup_info 0
		.amdhsa_system_vgpr_workitem_id 2
		.amdhsa_next_free_vgpr 256
		.amdhsa_next_free_sgpr 102
		.amdhsa_accum_offset 256
		.amdhsa_reserve_vcc 1
		.amdhsa_float_round_mode_32 0
		.amdhsa_float_round_mode_16_64 0
		.amdhsa_float_denorm_mode_32 3
		.amdhsa_float_denorm_mode_16_64 3
		.amdhsa_dx10_clamp 1
		.amdhsa_ieee_mode 1
		.amdhsa_fp16_overflow 0
		.amdhsa_tg_split 0
		.amdhsa_exception_fp_ieee_invalid_op 0
		.amdhsa_exception_fp_denorm_src 0
		.amdhsa_exception_fp_ieee_div_zero 0
		.amdhsa_exception_fp_ieee_overflow 0
		.amdhsa_exception_fp_ieee_underflow 0
		.amdhsa_exception_fp_ieee_inexact 0
		.amdhsa_exception_int_div_zero 0
	.end_amdhsa_kernel

; #define PG8_LAS __attribute__((address_space(3)))
; __global__ void __launch_bounds__(512, 2) hybrid_fwd(Params P) {
;     extern __shared__ __attribute__((aligned(16))) unsigned char smem[];
;     cg::grid_group grid = cg::this_grid();
;     float* lf = (float*)smem;
;     PG8_LAS unsigned char* lds = (PG8_LAS unsigned char*)smem;
;     const int G = gridDim.x, bid = blockIdx.x;
;     float* mod = (float*)(PWS + WS_MOD);
;     float* hc = (float*)(PWS + WS_HC);
;     bf16_t* AO = (bf16_t*)(PWS + WS_AO);
;     bf16_t* U = (bf16_t*)(PWS + WS_U);
;     bf16_t* HID = (bf16_t*)(PWS + WS_HID);
;     unsigned* barw = (unsigned*)(PWS + WS_BAR);
amdhsa.kernels:
  - .agpr_count:     0
    .args:
      - .offset:         0
        .size:           248
        .value_kind:     by_value
      - .offset:         248
        .size:           4
        .value_kind:     hidden_block_count_x
      - .offset:         252
        .size:           4
        .value_kind:     hidden_block_count_y
      - .offset:         256
        .size:           4
        .value_kind:     hidden_block_count_z
      - .offset:         260
        .size:           2
        .value_kind:     hidden_group_size_x
      - .offset:         262
        .size:           2
        .value_kind:     hidden_group_size_y
      - .offset:         264
        .size:           2
        .value_kind:     hidden_group_size_z
      - .offset:         266
        .size:           2
        .value_kind:     hidden_remainder_x
      - .offset:         268
        .size:           2
        .value_kind:     hidden_remainder_y
      - .offset:         270
        .size:           2
        .value_kind:     hidden_remainder_z
      - .offset:         288
        .size:           8
        .value_kind:     hidden_global_offset_x
      - .offset:         296
        .size:           8
        .value_kind:     hidden_global_offset_y
      - .offset:         304
        .size:           8
        .value_kind:     hidden_global_offset_z
      - .offset:         312
        .size:           2
        .value_kind:     hidden_grid_dims
      - .offset:         336
        .size:           8
        .value_kind:     hidden_multigrid_sync_arg
      - .offset:         368
        .size:           4
        .value_kind:     hidden_dynamic_lds_size
    .group_segment_fixed_size: 0
    .kernarg_segment_align: 8
    .kernarg_segment_size: 504
    .language:       OpenCL C
    .language_version:
      - 2
      - 0
    .max_flat_workgroup_size: 512
    .name:           _Z10hybrid_fwd6Params
    .private_segment_fixed_size: 0
    .sgpr_count:     108
    .sgpr_spill_count: 127
    .symbol:         _Z10hybrid_fwd6Params.kd
    .uniform_work_group_size: 1
    .uses_dynamic_stack: false
    .vgpr_count:     256
    .vgpr_spill_count: 0
    .wavefront_size: 64
